# baseline (speedup 1.0000x reference)
; #define PG8_STAGE(bufoff, gbase, voff) do { _Pragma("unroll") for (int _i = 0; _i < 2; ++_i) \
;         __builtin_amdgcn_global_load_lds((const unsigned*)((const char*)(gbase) + (voff)[_i]), (LAS unsigned*)(lds + (bufoff) + ldsw + _i * 8192), 16, 0, 0); } while (0)
; #define PG8_LDA(dst, b, h) do { _Pragma("unroll") for (int m = 0; m < 4; ++m) _Pragma("unroll") for (int k = 0; k < 2; ++k) dst[m][k] = *(const LAS bf16x8*)(lds + PG8_SA(b, h) + aoff + m * 2048 + k * 1024); } while (0)
; #define PG8_LDB(dst, b, h) do { _Pragma("unroll") for (int n = 0; n < 2; ++n) _Pragma("unroll") for (int k = 0; k < 2; ++k) dst[n][k] = *(const LAS bf16x8*)(lds + PG8_SB(b, h) + boff + n * 2048 + k * 1024); } while (0)
; #define PG8_MMA(ai, bj, At, Bt) do { __builtin_amdgcn_s_setprio(1); _Pragma("unroll") for (int m = 0; m < 4; ++m) _Pragma("unroll") for (int n = 0; n < 2; ++n) _Pragma("unroll") for (int k = 0; k < 2; ++k) \
;         acc[ai][bj][m][n] = __builtin_amdgcn_mfma_f32_16x16x32_bf16(Bt[n][k], At[m][k], acc[ai][bj][m][n], 0, 0, 0); __builtin_amdgcn_s_setprio(0); } while (0)
; #define PG8_WAIT_L(n) asm volatile("s_waitcnt lgkmcnt(" #n ")" ::: "memory")
; #define PG8_BAR __builtin_amdgcn_s_barrier()
; #define PG8_SCHED __builtin_amdgcn_sched_barrier(0)
; template <class Epi>
; DEV void gemm_phase(LAS unsigned char* lds, const Gemm g, const StaticOrder& S, const Epi& E) {
;     ...
;             PG8_LDB(B0, 0, 0); PG8_SCHED; PG8_LDA(At, 0, 0); PG8_STAGE(PG8_SA(1, 1), a1 + hstep, voffA);
;             PG8_WAIT_L(8); PG8_BAR; PG8_WAIT_L(0); PG8_MMA(0, 0, At, B0); PG8_BAR; PG8_SCHED;
;             PG8_LDB(B1, 0, 1); PG8_STAGE(PG8_SB(0, 0), b2, voffB);
;             PG8_BAR; PG8_WAIT_L(0); PG8_MMA(0, 1, At, B1); PG8_BAR;
;             PG8_LDA(At, 0, 1); PG8_STAGE(PG8_SA(0, 0), a2, voffA);
;             PG8_BAR; PG8_WAIT_L(0); PG8_MMA(1, 0, At, B0); PG8_BAR; PG8_SCHED;
.LBB0_61:
	s_add_u32 s28, s26, 0xfff80080
	s_addc_u32 s29, s27, -1
	s_add_i32 s49, 0, 0x10000
	v_add_u32_e32 v140, s49, v178
	ds_read_b128 v[128:131], v140
	ds_read_b128 v[132:135], v140 offset:1024
	ds_read_b128 v[136:139], v140 offset:2048
	ds_read_b128 v[140:143], v140 offset:3072
	s_cmp_eq_u32 s48, 28
	s_cselect_b32 s31, s15, s29
	s_cselect_b32 s30, s19, s28
	s_cselect_b32 s29, s17, s47
	s_cselect_b32 s28, s25, s46
	v_lshl_add_u64 v[158:159], s[26:27], 0, v[150:151]
	s_add_i32 m0, s37, 0xc000
	ds_read_b128 v[154:157], v181
	ds_read_b128 v[174:177], v181 offset:1024
	ds_read_b128 v[182:185], v181 offset:2048
	ds_read_b128 v[186:189], v181 offset:3072
	ds_read_b128 v[190:193], v181 offset:4096
	ds_read_b128 v[194:197], v181 offset:5120
	ds_read_b128 v[214:217], v181 offset:6144
	ds_read_b128 v[218:221], v181 offset:7168
	global_load_lds_dwordx4 v[158:159], off
	v_lshl_add_u64 v[158:159], s[26:27], 0, v[152:153]
	s_add_i32 m0, s37, 0xe000
	s_nop 0
	global_load_lds_dwordx4 v[158:159], off
	s_waitcnt lgkmcnt(8)
	s_barrier
	s_waitcnt lgkmcnt(0)
	s_setprio 1
	v_mfma_f32_16x16x32_bf16 v[124:127], v[128:131], v[154:157], v[124:127]
	v_mfma_f32_16x16x32_bf16 v[120:123], v[136:139], v[154:157], v[120:123]
	v_mfma_f32_16x16x32_bf16 v[108:111], v[128:131], v[182:185], v[108:111]
	v_mfma_f32_16x16x32_bf16 v[104:107], v[136:139], v[182:185], v[104:107]
	v_mfma_f32_16x16x32_bf16 v[92:95], v[128:131], v[190:193], v[92:95]
	v_mfma_f32_16x16x32_bf16 v[88:91], v[136:139], v[190:193], v[88:91]
	v_mfma_f32_16x16x32_bf16 v[76:79], v[128:131], v[214:217], v[76:79]
	v_mfma_f32_16x16x32_bf16 v[72:75], v[136:139], v[214:217], v[72:75]
	v_mfma_f32_16x16x32_bf16 v[124:127], v[132:135], v[174:177], v[124:127]
	v_mfma_f32_16x16x32_bf16 v[120:123], v[140:143], v[174:177], v[120:123]
	v_mfma_f32_16x16x32_bf16 v[108:111], v[132:135], v[186:189], v[108:111]
	v_mfma_f32_16x16x32_bf16 v[104:107], v[140:143], v[186:189], v[104:107]
	v_mfma_f32_16x16x32_bf16 v[92:95], v[132:135], v[194:197], v[92:95]
	v_mfma_f32_16x16x32_bf16 v[88:91], v[140:143], v[194:197], v[88:91]
	v_mfma_f32_16x16x32_bf16 v[76:79], v[132:135], v[218:221], v[76:79]
	v_mfma_f32_16x16x32_bf16 v[72:75], v[140:143], v[218:221], v[72:75]
	s_setprio 0
	s_barrier
	s_add_i32 s52, 0, 0x14000
	v_add_u32_e32 v158, s52, v178
	s_add_i32 s49, s49, s36
	ds_read_b128 v[222:225], v158
	ds_read_b128 v[226:229], v158 offset:1024
	ds_read_b128 v[230:233], v158 offset:2048
	ds_read_b128 v[234:237], v158 offset:3072
	v_lshl_add_u64 v[158:159], s[28:29], 0, v[160:161]
	s_mov_b32 m0, s49
	v_lshl_add_u64 v[238:239], s[28:29], 0, v[148:149]
	global_load_lds_dwordx4 v[158:159], off
	s_add_i32 m0, s49, 0x2000
	s_nop 0
	global_load_lds_dwordx4 v[238:239], off
	s_barrier
	s_waitcnt lgkmcnt(0)
	s_setprio 1
	v_mfma_f32_16x16x32_bf16 v[116:119], v[222:225], v[154:157], v[116:119]
	v_mfma_f32_16x16x32_bf16 v[112:115], v[230:233], v[154:157], v[112:115]
	v_mfma_f32_16x16x32_bf16 v[100:103], v[222:225], v[182:185], v[100:103]
	v_mfma_f32_16x16x32_bf16 v[96:99], v[230:233], v[182:185], v[96:99]
	v_mfma_f32_16x16x32_bf16 v[84:87], v[222:225], v[190:193], v[84:87]
	v_mfma_f32_16x16x32_bf16 v[80:83], v[230:233], v[190:193], v[80:83]
	v_mfma_f32_16x16x32_bf16 v[68:71], v[222:225], v[214:217], v[68:71]
	v_mfma_f32_16x16x32_bf16 v[64:67], v[230:233], v[214:217], v[64:67]
	v_mfma_f32_16x16x32_bf16 v[116:119], v[226:229], v[174:177], v[116:119]
	v_mfma_f32_16x16x32_bf16 v[112:115], v[234:237], v[174:177], v[112:115]
	v_mfma_f32_16x16x32_bf16 v[100:103], v[226:229], v[186:189], v[100:103]
	v_mfma_f32_16x16x32_bf16 v[96:99], v[234:237], v[186:189], v[96:99]
	v_mfma_f32_16x16x32_bf16 v[84:87], v[226:229], v[194:197], v[84:87]
	v_mfma_f32_16x16x32_bf16 v[80:83], v[234:237], v[194:197], v[80:83]
	v_mfma_f32_16x16x32_bf16 v[68:71], v[226:229], v[218:221], v[68:71]
	v_mfma_f32_16x16x32_bf16 v[64:67], v[234:237], v[218:221], v[64:67]
	s_setprio 0
	s_mov_b32 m0, s37
	v_lshl_add_u64 v[240:241], s[30:31], 0, v[144:145]
	s_barrier
	ds_read_b128 v[154:157], v181 offset:16384
	ds_read_b128 v[174:177], v181 offset:17408
	ds_read_b128 v[182:185], v181 offset:18432
	ds_read_b128 v[186:189], v181 offset:19456
	ds_read_b128 v[190:193], v181 offset:20480
	ds_read_b128 v[194:197], v181 offset:21504
	ds_read_b128 v[214:217], v181 offset:22528
	ds_read_b128 v[218:221], v181 offset:23552
	global_load_lds_dwordx4 v[240:241], off
	v_lshl_add_u64 v[242:243], s[30:31], 0, v[146:147]
	s_mov_b32 m0, s38
	s_nop 0
	global_load_lds_dwordx4 v[242:243], off
	s_barrier
	s_waitcnt lgkmcnt(0)
	s_setprio 1
	v_mfma_f32_16x16x32_bf16 v[60:63], v[128:131], v[154:157], v[60:63]
	v_mfma_f32_16x16x32_bf16 v[56:59], v[136:139], v[154:157], v[56:59]
	v_mfma_f32_16x16x32_bf16 v[44:47], v[128:131], v[182:185], v[44:47]
	v_mfma_f32_16x16x32_bf16 v[40:43], v[136:139], v[182:185], v[40:43]
	v_mfma_f32_16x16x32_bf16 v[28:31], v[128:131], v[190:193], v[28:31]
	v_mfma_f32_16x16x32_bf16 v[24:27], v[136:139], v[190:193], v[24:27]
	v_mfma_f32_16x16x32_bf16 v[12:15], v[128:131], v[214:217], v[12:15]
	v_mfma_f32_16x16x32_bf16 v[8:11], v[136:139], v[214:217], v[8:11]
	v_mfma_f32_16x16x32_bf16 v[60:63], v[132:135], v[174:177], v[60:63]
	v_mfma_f32_16x16x32_bf16 v[56:59], v[140:143], v[174:177], v[56:59]
	v_mfma_f32_16x16x32_bf16 v[44:47], v[132:135], v[186:189], v[44:47]
	v_mfma_f32_16x16x32_bf16 v[40:43], v[140:143], v[186:189], v[40:43]
	v_mfma_f32_16x16x32_bf16 v[28:31], v[132:135], v[194:197], v[28:31]
	v_mfma_f32_16x16x32_bf16 v[24:27], v[140:143], v[194:197], v[24:27]
	v_mfma_f32_16x16x32_bf16 v[12:15], v[132:135], v[218:221], v[12:15]
	v_mfma_f32_16x16x32_bf16 v[8:11], v[140:143], v[218:221], v[8:11]
	s_setprio 0
	s_barrier
; #define PG8_STAGE(bufoff, gbase, voff) do { _Pragma("unroll") for (int _i = 0; _i < 2; ++_i) \
;         __builtin_amdgcn_global_load_lds((const unsigned*)((const char*)(gbase) + (voff)[_i]), (LAS unsigned*)(lds + (bufoff) + ldsw + _i * 8192), 16, 0, 0); } while (0)
; #define PG8_LDA(dst, b, h) do { _Pragma("unroll") for (int m = 0; m < 4; ++m) _Pragma("unroll") for (int k = 0; k < 2; ++k) dst[m][k] = *(const LAS bf16x8*)(lds + PG8_SA(b, h) + aoff + m * 2048 + k * 1024); } while (0)
; #define PG8_LDB(dst, b, h) do { _Pragma("unroll") for (int n = 0; n < 2; ++n) _Pragma("unroll") for (int k = 0; k < 2; ++k) dst[n][k] = *(const LAS bf16x8*)(lds + PG8_SB(b, h) + boff + n * 2048 + k * 1024); } while (0)
; #define PG8_MMA(ai, bj, At, Bt) do { __builtin_amdgcn_s_setprio(1); _Pragma("unroll") for (int m = 0; m < 4; ++m) _Pragma("unroll") for (int n = 0; n < 2; ++n) _Pragma("unroll") for (int k = 0; k < 2; ++k) \
;         acc[ai][bj][m][n] = __builtin_amdgcn_mfma_f32_16x16x32_bf16(Bt[n][k], At[m][k], acc[ai][bj][m][n], 0, 0, 0); __builtin_amdgcn_s_setprio(0); } while (0)
; #define PG8_WAIT_V(n) asm volatile("s_waitcnt vmcnt(" #n ")" ::: "memory")
; #define PG8_WAIT_L(n) asm volatile("s_waitcnt lgkmcnt(" #n ")" ::: "memory")
; #define PG8_BAR __builtin_amdgcn_s_barrier()
; #define PG8_SCHED __builtin_amdgcn_sched_barrier(0)
; template <class Epi>
; DEV void gemm_phase(LAS unsigned char* lds, const Gemm g, const StaticOrder& S, const Epi& E) {
;     ...
;             PG8_STAGE(PG8_SB(0, 1), b2 + hstep, voffB);
;             PG8_WAIT_V(6); PG8_BAR; PG8_MMA(1, 1, At, B1); PG8_BAR;
;             PG8_LDB(B0, 1, 0); PG8_SCHED; PG8_LDA(At, 1, 0); PG8_STAGE(PG8_SA(0, 1), a2 + hstep, voffA);
;             PG8_WAIT_L(8); PG8_BAR; PG8_WAIT_L(0); PG8_MMA(0, 0, At, B0); PG8_BAR; PG8_SCHED;
;             PG8_LDB(B1, 1, 1); PG8_STAGE(PG8_SB(1, 0), b3, voffB);
;             PG8_BAR; PG8_WAIT_L(0); PG8_MMA(0, 1, At, B1); PG8_BAR;
;             PG8_LDA(At, 1, 1); PG8_STAGE(PG8_SA(1, 0), a3, voffA);
	s_add_u32 s50, s28, 0x80000
	s_addc_u32 s51, s29, 0
	s_add_i32 s49, s52, s36
	v_lshl_add_u64 v[128:129], s[50:51], 0, v[160:161]
	s_mov_b32 m0, s49
	s_nop 0
	global_load_lds_dwordx4 v[128:129], off
	v_lshl_add_u64 v[128:129], s[50:51], 0, v[148:149]
	s_add_i32 m0, s49, 0x2000
	s_nop 0
	global_load_lds_dwordx4 v[128:129], off
	s_waitcnt vmcnt(6)
	s_barrier
	s_setprio 1
	v_mfma_f32_16x16x32_bf16 v[52:55], v[222:225], v[154:157], v[52:55]
	v_mfma_f32_16x16x32_bf16 v[48:51], v[230:233], v[154:157], v[48:51]
	v_mfma_f32_16x16x32_bf16 v[36:39], v[222:225], v[182:185], v[36:39]
	v_mfma_f32_16x16x32_bf16 v[32:35], v[230:233], v[182:185], v[32:35]
	v_mfma_f32_16x16x32_bf16 v[20:23], v[222:225], v[190:193], v[20:23]
	v_mfma_f32_16x16x32_bf16 v[16:19], v[230:233], v[190:193], v[16:19]
	v_mfma_f32_16x16x32_bf16 v[4:7], v[222:225], v[214:217], v[4:7]
	v_mfma_f32_16x16x32_bf16 v[0:3], v[230:233], v[214:217], v[0:3]
	v_mfma_f32_16x16x32_bf16 v[52:55], v[226:229], v[174:177], v[52:55]
	v_mfma_f32_16x16x32_bf16 v[48:51], v[234:237], v[174:177], v[48:51]
	v_mfma_f32_16x16x32_bf16 v[36:39], v[226:229], v[186:189], v[36:39]
	v_mfma_f32_16x16x32_bf16 v[32:35], v[234:237], v[186:189], v[32:35]
	v_mfma_f32_16x16x32_bf16 v[20:23], v[226:229], v[194:197], v[20:23]
	v_mfma_f32_16x16x32_bf16 v[16:19], v[234:237], v[194:197], v[16:19]
	v_mfma_f32_16x16x32_bf16 v[4:7], v[226:229], v[218:221], v[4:7]
	v_mfma_f32_16x16x32_bf16 v[0:3], v[234:237], v[218:221], v[0:3]
	s_setprio 0
	s_add_i32 s49, 0, 0x18000
	v_add_u32_e32 v140, s49, v178
	s_barrier
	ds_read_b128 v[128:131], v140
	ds_read_b128 v[132:135], v140 offset:1024
	ds_read_b128 v[136:139], v140 offset:2048
	ds_read_b128 v[140:143], v140 offset:3072
	s_add_u32 s30, s30, 0x80000
	s_addc_u32 s31, s31, 0
	s_mov_b32 m0, s39
	v_lshl_add_u64 v[222:223], s[30:31], 0, v[144:145]
	ds_read_b128 v[154:157], v181 offset:32768
	ds_read_b128 v[174:177], v181 offset:33792
	ds_read_b128 v[182:185], v181 offset:34816
	ds_read_b128 v[186:189], v181 offset:35840
	ds_read_b128 v[190:193], v181 offset:36864
	ds_read_b128 v[194:197], v181 offset:37888
	ds_read_b128 v[214:217], v181 offset:38912
	ds_read_b128 v[218:221], v181 offset:39936
	global_load_lds_dwordx4 v[222:223], off
	v_lshl_add_u64 v[222:223], s[30:31], 0, v[146:147]
	s_mov_b32 m0, s40
	s_nop 0
	global_load_lds_dwordx4 v[222:223], off
	s_waitcnt lgkmcnt(8)
	s_barrier
	s_waitcnt lgkmcnt(0)
	s_setprio 1
	v_mfma_f32_16x16x32_bf16 v[124:127], v[128:131], v[154:157], v[124:127]
	v_mfma_f32_16x16x32_bf16 v[120:123], v[136:139], v[154:157], v[120:123]
	v_mfma_f32_16x16x32_bf16 v[108:111], v[128:131], v[182:185], v[108:111]
	v_mfma_f32_16x16x32_bf16 v[104:107], v[136:139], v[182:185], v[104:107]
	v_mfma_f32_16x16x32_bf16 v[92:95], v[128:131], v[190:193], v[92:95]
	v_mfma_f32_16x16x32_bf16 v[88:91], v[136:139], v[190:193], v[88:91]
	v_mfma_f32_16x16x32_bf16 v[76:79], v[128:131], v[214:217], v[76:79]
	v_mfma_f32_16x16x32_bf16 v[72:75], v[136:139], v[214:217], v[72:75]
	v_mfma_f32_16x16x32_bf16 v[124:127], v[132:135], v[174:177], v[124:127]
	v_mfma_f32_16x16x32_bf16 v[120:123], v[140:143], v[174:177], v[120:123]
	v_mfma_f32_16x16x32_bf16 v[108:111], v[132:135], v[186:189], v[108:111]
	v_mfma_f32_16x16x32_bf16 v[104:107], v[140:143], v[186:189], v[104:107]
	v_mfma_f32_16x16x32_bf16 v[92:95], v[132:135], v[194:197], v[92:95]
	v_mfma_f32_16x16x32_bf16 v[88:91], v[140:143], v[194:197], v[88:91]
	v_mfma_f32_16x16x32_bf16 v[76:79], v[132:135], v[218:221], v[76:79]
	v_mfma_f32_16x16x32_bf16 v[72:75], v[140:143], v[218:221], v[72:75]
	s_setprio 0
	s_barrier
	s_add_i32 s30, 0, 0x1c000
	s_add_i32 s31, s49, s36
	v_add_u32_e32 v234, s30, v178
	v_lshl_add_u64 v[158:159], v[158:159], 0, s[2:3]
	s_mov_b32 m0, s31
	ds_read_b128 v[222:225], v234
	ds_read_b128 v[226:229], v234 offset:1024
	ds_read_b128 v[230:233], v234 offset:2048
	ds_read_b128 v[234:237], v234 offset:3072
	global_load_lds_dwordx4 v[158:159], off
	v_lshl_add_u64 v[158:159], v[238:239], 0, s[2:3]
	s_add_i32 m0, s31, 0x2000
	s_nop 0
	global_load_lds_dwordx4 v[158:159], off
	s_barrier
	s_waitcnt lgkmcnt(0)
	s_setprio 1
	v_mfma_f32_16x16x32_bf16 v[116:119], v[222:225], v[154:157], v[116:119]
	v_mfma_f32_16x16x32_bf16 v[112:115], v[230:233], v[154:157], v[112:115]
	v_mfma_f32_16x16x32_bf16 v[100:103], v[222:225], v[182:185], v[100:103]
	v_mfma_f32_16x16x32_bf16 v[96:99], v[230:233], v[182:185], v[96:99]
	v_mfma_f32_16x16x32_bf16 v[84:87], v[222:225], v[190:193], v[84:87]
	v_mfma_f32_16x16x32_bf16 v[80:83], v[230:233], v[190:193], v[80:83]
	v_mfma_f32_16x16x32_bf16 v[68:71], v[222:225], v[214:217], v[68:71]
	v_mfma_f32_16x16x32_bf16 v[64:67], v[230:233], v[214:217], v[64:67]
	v_mfma_f32_16x16x32_bf16 v[116:119], v[226:229], v[174:177], v[116:119]
	v_mfma_f32_16x16x32_bf16 v[112:115], v[234:237], v[174:177], v[112:115]
	v_mfma_f32_16x16x32_bf16 v[100:103], v[226:229], v[186:189], v[100:103]
	v_mfma_f32_16x16x32_bf16 v[96:99], v[234:237], v[186:189], v[96:99]
	v_mfma_f32_16x16x32_bf16 v[84:87], v[226:229], v[194:197], v[84:87]
	v_mfma_f32_16x16x32_bf16 v[80:83], v[234:237], v[194:197], v[80:83]
	v_mfma_f32_16x16x32_bf16 v[68:71], v[226:229], v[218:221], v[68:71]
	v_mfma_f32_16x16x32_bf16 v[64:67], v[234:237], v[218:221], v[64:67]
	s_setprio 0
	s_mov_b32 m0, s41
	v_lshl_add_u64 v[158:159], v[240:241], 0, s[2:3]
	s_barrier
	ds_read_b128 v[154:157], v181 offset:49152
	ds_read_b128 v[174:177], v181 offset:50176
	ds_read_b128 v[182:185], v181 offset:51200
	ds_read_b128 v[186:189], v181 offset:52224
	ds_read_b128 v[190:193], v181 offset:53248
	ds_read_b128 v[194:197], v181 offset:54272
	ds_read_b128 v[214:217], v181 offset:55296
	ds_read_b128 v[218:221], v181 offset:56320
	global_load_lds_dwordx4 v[158:159], off
	v_lshl_add_u64 v[158:159], v[242:243], 0, s[2:3]
	s_mov_b32 m0, s42
	s_nop 0
	global_load_lds_dwordx4 v[158:159], off
	s_barrier
; #define PG8_STAGE(bufoff, gbase, voff) do { _Pragma("unroll") for (int _i = 0; _i < 2; ++_i) \
;         __builtin_amdgcn_global_load_lds((const unsigned*)((const char*)(gbase) + (voff)[_i]), (LAS unsigned*)(lds + (bufoff) + ldsw + _i * 8192), 16, 0, 0); } while (0)
; #define PG8_MMA(ai, bj, At, Bt) do { __builtin_amdgcn_s_setprio(1); _Pragma("unroll") for (int m = 0; m < 4; ++m) _Pragma("unroll") for (int n = 0; n < 2; ++n) _Pragma("unroll") for (int k = 0; k < 2; ++k) \
;         acc[ai][bj][m][n] = __builtin_amdgcn_mfma_f32_16x16x32_bf16(Bt[n][k], At[m][k], acc[ai][bj][m][n], 0, 0, 0); __builtin_amdgcn_s_setprio(0); } while (0)
; #define PG8_WAIT_V(n) asm volatile("s_waitcnt vmcnt(" #n ")" ::: "memory")
; #define PG8_WAIT_L(n) asm volatile("s_waitcnt lgkmcnt(" #n ")" ::: "memory")
; #define PG8_BAR __builtin_amdgcn_s_barrier()
; #define PG8_SCHED __builtin_amdgcn_sched_barrier(0)
; template <class Epi>
; DEV void gemm_phase(LAS unsigned char* lds, const Gemm g, const StaticOrder& S, const Epi& E) {
;     ...
;             PG8_BAR; PG8_WAIT_L(0); PG8_MMA(1, 0, At, B0); PG8_BAR; PG8_SCHED;
;             PG8_STAGE(PG8_SB(1, 1), b3 + hstep, voffB);
;             PG8_WAIT_V(6); PG8_BAR; PG8_MMA(1, 1, At, B1); PG8_BAR;
	s_waitcnt lgkmcnt(0)
	s_setprio 1
	v_mfma_f32_16x16x32_bf16 v[60:63], v[128:131], v[154:157], v[60:63]
	v_mfma_f32_16x16x32_bf16 v[56:59], v[136:139], v[154:157], v[56:59]
	v_mfma_f32_16x16x32_bf16 v[44:47], v[128:131], v[182:185], v[44:47]
	v_mfma_f32_16x16x32_bf16 v[40:43], v[136:139], v[182:185], v[40:43]
	v_mfma_f32_16x16x32_bf16 v[28:31], v[128:131], v[190:193], v[28:31]
	v_mfma_f32_16x16x32_bf16 v[24:27], v[136:139], v[190:193], v[24:27]
	v_mfma_f32_16x16x32_bf16 v[12:15], v[128:131], v[214:217], v[12:15]
	v_mfma_f32_16x16x32_bf16 v[8:11], v[136:139], v[214:217], v[8:11]
	v_mfma_f32_16x16x32_bf16 v[60:63], v[132:135], v[174:177], v[60:63]
	v_mfma_f32_16x16x32_bf16 v[56:59], v[140:143], v[174:177], v[56:59]
	v_mfma_f32_16x16x32_bf16 v[44:47], v[132:135], v[186:189], v[44:47]
	v_mfma_f32_16x16x32_bf16 v[40:43], v[140:143], v[186:189], v[40:43]
	v_mfma_f32_16x16x32_bf16 v[28:31], v[132:135], v[194:197], v[28:31]
	v_mfma_f32_16x16x32_bf16 v[24:27], v[140:143], v[194:197], v[24:27]
	v_mfma_f32_16x16x32_bf16 v[12:15], v[132:135], v[218:221], v[12:15]
	v_mfma_f32_16x16x32_bf16 v[8:11], v[140:143], v[218:221], v[8:11]
	s_setprio 0
	s_barrier
	s_add_u32 s28, s28, 0x80080
	s_addc_u32 s29, s29, 0
	s_add_i32 s30, s30, s36
	v_lshl_add_u64 v[128:129], s[28:29], 0, v[160:161]
	s_mov_b32 m0, s30
	s_nop 0
	global_load_lds_dwordx4 v[128:129], off
	v_lshl_add_u64 v[128:129], s[28:29], 0, v[148:149]
	s_add_i32 m0, s30, 0x2000
	s_nop 0
	global_load_lds_dwordx4 v[128:129], off
	s_waitcnt vmcnt(6)
	s_barrier
	s_setprio 1
	v_mfma_f32_16x16x32_bf16 v[52:55], v[222:225], v[154:157], v[52:55]
	v_mfma_f32_16x16x32_bf16 v[48:51], v[230:233], v[154:157], v[48:51]
	v_mfma_f32_16x16x32_bf16 v[36:39], v[222:225], v[182:185], v[36:39]
	v_mfma_f32_16x16x32_bf16 v[32:35], v[230:233], v[182:185], v[32:35]
	v_mfma_f32_16x16x32_bf16 v[20:23], v[222:225], v[190:193], v[20:23]
	v_mfma_f32_16x16x32_bf16 v[16:19], v[230:233], v[190:193], v[16:19]
	v_mfma_f32_16x16x32_bf16 v[4:7], v[222:225], v[214:217], v[4:7]
	v_mfma_f32_16x16x32_bf16 v[0:3], v[230:233], v[214:217], v[0:3]
	v_mfma_f32_16x16x32_bf16 v[52:55], v[226:229], v[174:177], v[52:55]
	v_mfma_f32_16x16x32_bf16 v[48:51], v[234:237], v[174:177], v[48:51]
	v_mfma_f32_16x16x32_bf16 v[36:39], v[226:229], v[186:189], v[36:39]
	v_mfma_f32_16x16x32_bf16 v[32:35], v[234:237], v[186:189], v[32:35]
	v_mfma_f32_16x16x32_bf16 v[20:23], v[226:229], v[194:197], v[20:23]
	v_mfma_f32_16x16x32_bf16 v[16:19], v[234:237], v[194:197], v[16:19]
	v_mfma_f32_16x16x32_bf16 v[4:7], v[226:229], v[218:221], v[4:7]
	v_mfma_f32_16x16x32_bf16 v[0:3], v[234:237], v[218:221], v[0:3]
	s_setprio 0
	s_add_i32 s48, s48, 2
	s_add_u32 s26, s26, 0x100
	s_addc_u32 s27, s27, 0
	s_add_u32 s46, s46, 0x100
	s_addc_u32 s47, s47, 0
	s_cmp_gt_u32 s48, 29
	s_barrier
	s_cbranch_scc0 .LBB0_61
; DEV bf16x8 pack8(f32x4 a, f32x4 b) { u32x4 w; w.x = cvt_pk_bf16(a[0], a[1]); w.y = cvt_pk_bf16(a[2], a[3]); w.z = cvt_pk_bf16(b[0], b[1]); w.w = cvt_pk_bf16(b[2], b[3]); return __builtin_bit_cast(bf16x8, w); }
;     DEV void operator()(AccRef acc, const pg8::Unit& u, int wr, int wc, int fr, int fq) const {
;         const int row0 = u.pm * 256 + wr * 64 + fr, col0 = u.pn * 256 + wc * 32 + 8 * fq;
; #pragma unroll
;         for (int am = 0; am < 4; ++am) { const int ai = am >> 1, m0 = (am & 1) * 2;
;             f32x4 bv[4][2][2];
; #pragma unroll
;             for (int m = m0; m < m0 + 2; ++m)
; #pragma unroll
;                 for (int bj = 0; bj < 2; ++bj)
; #pragma unroll
;                     for (int n = 0; n < 2; ++n) bv[m][bj][n] = *(const f32x4*)(base + (size_t)(row0 + ai * 128 + m * 16) * 2048 + col0 + bj * 128 + n * 4);
; #pragma unroll
;             for (int m = m0; m < m0 + 2; ++m) { const size_t off = (size_t)(row0 + ai * 128 + m * 16) * 2048 + col0; float sq = 0.f;
; #pragma unroll
;                 for (int bj = 0; bj < 2; ++bj) { const f32x4 o0 = bv[m][bj][0] + scale * acc[ai][bj][m][0], o1 = bv[m][bj][1] + scale * acc[ai][bj][m][1];
;                     *(f32x4*)(out + off + bj * 128) = o0; *(f32x4*)(out + off + bj * 128 + 4) = o1;
;                     if (xb) { *(u32x4*)(xb + off + bj * 128) = __builtin_bit_cast(u32x4, pack8(o0, o1));
;                         sq += (o0[0] * o0[0] + o0[1] * o0[1] + o0[2] * o0[2] + o0[3] * o0[3]) + (o1[0] * o1[0] + o1[1] * o1[1] + o1[2] * o1[2] + o1[3] * o1[3]); } }
;                 if (ssout) { sq += __shfl_xor(sq, 16); sq += __shfl_xor(sq, 32);
;                     if (fq == 0) { if (red) red[(ai * 128 + wr * 64 + m * 16 + fr) * 4 + wc] = sq; else atomicAdd(ssout + (size_t)(row0 + ai * 128 + m * 16) * 8 + u.pn, sq); } } }
	v_lshl_add_u32 v156, s24, 8, v167
	v_lshl_or_b32 v154, s14, 8, v179
	v_readlane_b32 s24, v254, 16
	v_ashrrev_i32_e32 v155, 31, v154
	v_readlane_b32 s25, v254, 17
	v_ashrrev_i32_e32 v157, 31, v156
	v_lshlrev_b64 v[128:129], 13, v[156:157]
	v_lshl_add_u64 v[158:159], v[154:155], 2, s[24:25]
	v_lshl_add_u64 v[214:215], v[158:159], 0, v[128:129]
	global_load_dwordx4 v[182:185], v[214:215], off offset:16
	global_load_dwordx4 v[186:189], v[214:215], off
	global_load_dwordx4 v[190:193], v[214:215], off offset:528
	global_load_dwordx4 v[194:197], v[214:215], off offset:512
	v_or_b32_e32 v174, 16, v156
	v_ashrrev_i32_e32 v175, 31, v174
	v_lshlrev_b64 v[128:129], 13, v[174:175]
	v_lshl_add_u64 v[176:177], v[158:159], 0, v[128:129]
	global_load_dwordx4 v[136:139], v[176:177], off offset:16
	global_load_dwordx4 v[140:143], v[176:177], off
	global_load_dwordx4 v[128:131], v[176:177], off offset:528
	global_load_dwordx4 v[132:135], v[176:177], off offset:512
	v_add_u32_e32 v255, 32, v156
	v_lshlrev_b32_e32 v255, 13, v255
	v_lshl_add_u32 v255, v154, 2, v255
	global_load_dwordx4 v[218:221], v255, s[24:25]
	global_load_dwordx4 v[222:225], v255, s[24:25] offset:16
	global_load_dwordx4 v[226:229], v255, s[24:25] offset:512
	global_load_dwordx4 v[230:233], v255, s[24:25] offset:528
	v_add_u32_e32 v255, 48, v156
	v_lshlrev_b32_e32 v255, 13, v255
	v_lshl_add_u32 v255, v154, 2, v255
	global_load_dwordx4 v[234:237], v255, s[24:25] offset:16
	global_load_dwordx4 v[238:241], v255, s[24:25]
	global_load_dwordx4 v[242:245], v255, s[24:25] offset:528
	global_load_dwordx4 v[246:249], v255, s[24:25] offset:512
	v_lshlrev_b64 v[216:217], 11, v[156:157]
	v_readlane_b32 s24, v250, 9
	v_lshl_add_u64 v[216:217], v[216:217], 0, v[154:155]
	v_readlane_b32 s25, v250, 10
	v_cmp_lt_i32_e32 vcc, v208, v206
	s_ashr_i32 s15, s14, 31
	s_waitcnt vmcnt(0)
	v_pk_add_f32 v[120:121], v[120:121], v[182:183]
	v_pk_add_f32 v[126:127], v[126:127], v[188:189]
	v_pk_add_f32 v[124:125], v[124:125], v[186:187]
	v_pk_add_f32 v[122:123], v[122:123], v[184:185]
	global_store_dwordx4 v[214:215], v[124:127], off
	global_store_dwordx4 v[214:215], v[120:123], off offset:16
	v_cvt_pk_bf16_f32 v184, v120, v121
	v_cvt_pk_bf16_f32 v182, v124, v125
	v_mul_f32_e32 v121, v121, v121
	v_cvt_pk_bf16_f32 v183, v126, v127
	v_cvt_pk_bf16_f32 v185, v122, v123
	v_lshl_add_u64 v[186:187], v[216:217], 1, s[24:25]
	v_fmac_f32_e32 v121, v120, v120
	v_pk_add_f32 v[118:119], v[118:119], v[196:197]
	v_pk_add_f32 v[116:117], v[116:117], v[194:195]
	v_pk_add_f32 v[112:113], v[112:113], v[190:191]
	global_store_dwordx4 v[186:187], v[182:185], off
	v_mul_f32_e32 v125, v125, v125
	v_fmac_f32_e32 v121, v122, v122
	v_pk_add_f32 v[114:115], v[114:115], v[192:193]
	global_store_dwordx4 v[214:215], v[116:119], off offset:512
	global_store_dwordx4 v[214:215], v[112:115], off offset:528
	v_cvt_pk_bf16_f32 v120, v116, v117
	v_cvt_pk_bf16_f32 v122, v112, v113
	v_mul_f32_e32 v117, v117, v117
	v_mul_f32_e32 v113, v113, v113
	v_fmac_f32_e32 v125, v124, v124
	v_fmac_f32_e32 v117, v116, v116
	v_fmac_f32_e32 v113, v112, v112
	v_fmac_f32_e32 v125, v126, v126
	v_fmac_f32_e32 v117, v118, v118
	v_fmac_f32_e32 v113, v114, v114
	v_fmac_f32_e32 v125, v127, v127
	v_fmac_f32_e32 v121, v123, v123
	v_fmac_f32_e32 v117, v119, v119
	v_fmac_f32_e32 v113, v115, v115
	v_add_f32_e32 v124, v125, v121
	v_add_f32_e32 v112, v117, v113
	v_cndmask_b32_e32 v113, v204, v208, vcc
	v_cvt_pk_bf16_f32 v121, v118, v119
	v_add_f32_e32 v112, v124, v112
	v_lshlrev_b32_e32 v118, 2, v113
	ds_bpermute_b32 v113, v118, v112
	v_cmp_lt_i32_e32 vcc, v207, v206
	v_cvt_pk_bf16_f32 v123, v114, v115
	global_store_dwordx4 v[186:187], v[120:123], off offset:256
	s_waitcnt lgkmcnt(0)
	v_add_f32_e32 v112, v112, v113
	v_cndmask_b32_e32 v113, v204, v207, vcc
	v_lshlrev_b32_e32 v119, 2, v113
	ds_bpermute_b32 v113, v119, v112
	s_and_saveexec_b64 s[24:25], s[6:7]
	s_cbranch_execz .LBB0_67
	s_waitcnt lgkmcnt(0)
	v_add_f32_e32 v112, v112, v113
	s_mov_b64 s[26:27], -1
	s_and_b64 vcc, exec, s[12:13]
	s_cbranch_vccz .LBB0_65
	v_readlane_b32 s26, v250, 37
	v_lshlrev_b64 v[114:115], 5, v[156:157]
	v_readlane_b32 s27, v250, 38
	s_nop 1
	v_lshl_add_u64 v[114:115], s[26:27], 0, v[114:115]
	v_lshl_add_u64 v[114:115], s[14:15], 2, v[114:115]
	global_atomic_add_f32 v[114:115], v112, off
	s_mov_b64 s[26:27], 0

; DEV bf16x8 pack8(f32x4 a, f32x4 b) { u32x4 w; w.x = cvt_pk_bf16(a[0], a[1]); w.y = cvt_pk_bf16(a[2], a[3]); w.z = cvt_pk_bf16(b[0], b[1]); w.w = cvt_pk_bf16(b[2], b[3]); return __builtin_bit_cast(bf16x8, w); }
;     DEV void operator()(AccRef acc, const pg8::Unit& u, int wr, int wc, int fr, int fq) const {
;     ...
;         for (int am = 0; am < 4; ++am) { const int ai = am >> 1, m0 = (am & 1) * 2;
;             f32x4 bv[4][2][2];
; #pragma unroll
;             for (int m = m0; m < m0 + 2; ++m)
; #pragma unroll
;                 for (int bj = 0; bj < 2; ++bj)
; #pragma unroll
;                     for (int n = 0; n < 2; ++n) bv[m][bj][n] = *(const f32x4*)(base + (size_t)(row0 + ai * 128 + m * 16) * 2048 + col0 + bj * 128 + n * 4);
; #pragma unroll
;             for (int m = m0; m < m0 + 2; ++m) { const size_t off = (size_t)(row0 + ai * 128 + m * 16) * 2048 + col0; float sq = 0.f;
; #pragma unroll
;                 for (int bj = 0; bj < 2; ++bj) { const f32x4 o0 = bv[m][bj][0] + scale * acc[ai][bj][m][0], o1 = bv[m][bj][1] + scale * acc[ai][bj][m][1];
;                     *(f32x4*)(out + off + bj * 128) = o0; *(f32x4*)(out + off + bj * 128 + 4) = o1;
;                     if (xb) { *(u32x4*)(xb + off + bj * 128) = __builtin_bit_cast(u32x4, pack8(o0, o1));
;                         sq += (o0[0] * o0[0] + o0[1] * o0[1] + o0[2] * o0[2] + o0[3] * o0[3]) + (o1[0] * o1[0] + o1[1] * o1[1] + o1[2] * o1[2] + o1[3] * o1[3]); } }
;                 if (ssout) { sq += __shfl_xor(sq, 16); sq += __shfl_xor(sq, 32);
;                     if (fq == 0) { if (red) red[(ai * 128 + wr * 64 + m * 16 + fr) * 4 + wc] = sq; else atomicAdd(ssout + (size_t)(row0 + ai * 128 + m * 16) * 8 + u.pn, sq); } } }
.LBB0_72:
	s_or_b64 exec, exec, s[24:25]
	v_or_b32_e32 v116, 32, v156
	v_ashrrev_i32_e32 v117, 31, v116
	s_waitcnt lgkmcnt(0)
	v_lshlrev_b64 v[96:97], 13, v[116:117]
	v_lshl_add_u64 v[136:137], v[158:159], 0, v[96:97]
	v_mov_b32_e32 v120, v218
	v_mov_b32_e32 v121, v219
	v_mov_b32_e32 v122, v220
	v_mov_b32_e32 v123, v221
	v_mov_b32_e32 v124, v222
	v_mov_b32_e32 v125, v223
	v_mov_b32_e32 v126, v224
	v_mov_b32_e32 v127, v225
	v_mov_b32_e32 v128, v226
	v_mov_b32_e32 v129, v227
	v_mov_b32_e32 v130, v228
	v_mov_b32_e32 v131, v229
	v_mov_b32_e32 v132, v230
	v_mov_b32_e32 v133, v231
	v_mov_b32_e32 v134, v232
	v_mov_b32_e32 v135, v233
	v_or_b32_e32 v112, 48, v156
	v_ashrrev_i32_e32 v113, 31, v112
	v_lshlrev_b64 v[96:97], 13, v[112:113]
	v_lshl_add_u64 v[114:115], v[158:159], 0, v[96:97]
	v_mov_b32_e32 v104, v234
	v_mov_b32_e32 v105, v235
	v_mov_b32_e32 v106, v236
	v_mov_b32_e32 v107, v237
	v_mov_b32_e32 v108, v238
	v_mov_b32_e32 v109, v239
	v_mov_b32_e32 v110, v240
	v_mov_b32_e32 v111, v241
	v_mov_b32_e32 v96, v242
	v_mov_b32_e32 v97, v243
	v_mov_b32_e32 v98, v244
	v_mov_b32_e32 v99, v245
	v_mov_b32_e32 v100, v246
	v_mov_b32_e32 v101, v247
	v_mov_b32_e32 v102, v248
	v_mov_b32_e32 v103, v249
	v_readlane_b32 s24, v254, 16
	v_readlane_b32 s25, v254, 17
	v_add_u32_e32 v255, 128, v156
	v_lshlrev_b32_e32 v255, 13, v255
	v_lshl_add_u32 v255, v154, 2, v255
	s_nop 1
	global_load_dwordx4 v[218:221], v255, s[24:25]
	global_load_dwordx4 v[222:225], v255, s[24:25] offset:16
	global_load_dwordx4 v[226:229], v255, s[24:25] offset:512
	global_load_dwordx4 v[230:233], v255, s[24:25] offset:528
	v_add_u32_e32 v255, 144, v156
	v_lshlrev_b32_e32 v255, 13, v255
	v_lshl_add_u32 v255, v154, 2, v255
	global_load_dwordx4 v[234:237], v255, s[24:25] offset:16
	global_load_dwordx4 v[238:241], v255, s[24:25]
	global_load_dwordx4 v[242:245], v255, s[24:25] offset:528
	global_load_dwordx4 v[246:249], v255, s[24:25] offset:512
	v_lshlrev_b64 v[138:139], 11, v[116:117]
	v_readlane_b32 s24, v250, 9
	v_lshl_add_u64 v[138:139], v[138:139], 0, v[154:155]
	v_readlane_b32 s25, v250, 10
	v_pk_add_f32 v[94:95], v[94:95], v[122:123]
	v_pk_add_f32 v[92:93], v[92:93], v[120:121]
	v_pk_add_f32 v[88:89], v[88:89], v[124:125]
	v_pk_add_f32 v[84:85], v[84:85], v[128:129]
	v_pk_add_f32 v[120:121], v[80:81], v[132:133]
	v_pk_add_f32 v[90:91], v[90:91], v[126:127]
	v_pk_add_f32 v[122:123], v[82:83], v[134:135]
	global_store_dwordx4 v[136:137], v[92:95], off
	global_store_dwordx4 v[136:137], v[88:91], off offset:16
	v_cvt_pk_bf16_f32 v80, v92, v93
	v_cvt_pk_bf16_f32 v82, v88, v89
	v_mul_f32_e32 v93, v93, v93
	v_mul_f32_e32 v89, v89, v89
	v_mul_f32_e32 v124, v85, v85
	v_mul_f32_e32 v125, v121, v121
	v_pk_add_f32 v[86:87], v[86:87], v[130:131]
	v_fmac_f32_e32 v93, v92, v92
	v_fmac_f32_e32 v89, v88, v88
	v_fmac_f32_e32 v124, v84, v84
	v_fmac_f32_e32 v125, v120, v120
	v_fmac_f32_e32 v93, v94, v94
	v_fmac_f32_e32 v89, v90, v90
	v_fmac_f32_e32 v124, v86, v86
	v_fmac_f32_e32 v125, v122, v122
	v_fmac_f32_e32 v93, v95, v95
	v_fmac_f32_e32 v89, v91, v91
	v_fmac_f32_e32 v124, v87, v87
	v_fmac_f32_e32 v125, v123, v123
	v_add_f32_e32 v88, v93, v89
	v_add_f32_e32 v89, v124, v125
	v_add_f32_e32 v88, v88, v89
	ds_bpermute_b32 v89, v118, v88
	v_lshl_add_u64 v[138:139], v[138:139], 1, s[24:25]
	v_cvt_pk_bf16_f32 v81, v94, v95
	v_cvt_pk_bf16_f32 v83, v90, v91
	global_store_dwordx4 v[138:139], v[80:83], off
	global_store_dwordx4 v[136:137], v[84:87], off offset:512
	global_store_dwordx4 v[136:137], v[120:123], off offset:528
	s_waitcnt lgkmcnt(0)
	v_add_f32_e32 v80, v88, v89
	ds_bpermute_b32 v81, v119, v80
	v_cvt_pk_bf16_f32 v82, v84, v85
	v_cvt_pk_bf16_f32 v83, v86, v87
	v_cvt_pk_bf16_f32 v84, v120, v121
	v_cvt_pk_bf16_f32 v85, v122, v123
	global_store_dwordx4 v[138:139], v[82:85], off offset:256
	s_and_saveexec_b64 s[24:25], s[6:7]
	s_cbranch_execz .LBB0_77
	s_waitcnt lgkmcnt(0)
	v_add_f32_e32 v80, v80, v81
	s_mov_b64 s[26:27], -1
	s_and_b64 vcc, exec, s[12:13]
	s_cbranch_vccz .LBB0_75
	v_readlane_b32 s26, v250, 37
	v_lshlrev_b64 v[82:83], 5, v[116:117]
	v_readlane_b32 s27, v250, 38
	s_nop 1
	v_lshl_add_u64 v[82:83], s[26:27], 0, v[82:83]
	v_lshl_add_u64 v[82:83], s[14:15], 2, v[82:83]
	global_atomic_add_f32 v[82:83], v80, off
	s_mov_b64 s[26:27], 0

; DEV bf16x8 pack8(f32x4 a, f32x4 b) { u32x4 w; w.x = cvt_pk_bf16(a[0], a[1]); w.y = cvt_pk_bf16(a[2], a[3]); w.z = cvt_pk_bf16(b[0], b[1]); w.w = cvt_pk_bf16(b[2], b[3]); return __builtin_bit_cast(bf16x8, w); }
;     DEV void operator()(AccRef acc, const pg8::Unit& u, int wr, int wc, int fr, int fq) const {
;     ...
;             for (int m = m0; m < m0 + 2; ++m) { const size_t off = (size_t)(row0 + ai * 128 + m * 16) * 2048 + col0; float sq = 0.f;
; #pragma unroll
;                 for (int bj = 0; bj < 2; ++bj) { const f32x4 o0 = bv[m][bj][0] + scale * acc[ai][bj][m][0], o1 = bv[m][bj][1] + scale * acc[ai][bj][m][1];
;                     *(f32x4*)(out + off + bj * 128) = o0; *(f32x4*)(out + off + bj * 128 + 4) = o1;
;                     if (xb) { *(u32x4*)(xb + off + bj * 128) = __builtin_bit_cast(u32x4, pack8(o0, o1));
;                         sq += (o0[0] * o0[0] + o0[1] * o0[1] + o0[2] * o0[2] + o0[3] * o0[3]) + (o1[0] * o1[0] + o1[1] * o1[1] + o1[2] * o1[2] + o1[3] * o1[3]); } }
;                 if (ssout) { sq += __shfl_xor(sq, 16); sq += __shfl_xor(sq, 32);
;                     if (fq == 0) { if (red) red[(ai * 128 + wr * 64 + m * 16 + fr) * 4 + wc] = sq; else atomicAdd(ssout + (size_t)(row0 + ai * 128 + m * 16) * 8 + u.pn, sq); } } }
.LBB0_77:
	s_or_b64 exec, exec, s[24:25]
	s_waitcnt lgkmcnt(0)
	v_lshlrev_b64 v[80:81], 11, v[112:113]
	v_pk_add_f32 v[78:79], v[78:79], v[110:111]
	v_pk_add_f32 v[76:77], v[76:77], v[108:109]
	v_pk_add_f32 v[72:73], v[72:73], v[104:105]
	v_lshl_add_u64 v[84:85], v[80:81], 0, v[154:155]
	v_pk_add_f32 v[74:75], v[74:75], v[106:107]
	global_store_dwordx4 v[114:115], v[76:79], off
	global_store_dwordx4 v[114:115], v[72:75], off offset:16
	v_cvt_pk_bf16_f32 v80, v76, v77
	v_cvt_pk_bf16_f32 v82, v72, v73
	v_mul_f32_e32 v77, v77, v77
	v_mul_f32_e32 v73, v73, v73
	v_fmac_f32_e32 v77, v76, v76
	v_fmac_f32_e32 v73, v72, v72
	v_fmac_f32_e32 v77, v78, v78
	v_fmac_f32_e32 v73, v74, v74
	v_fmac_f32_e32 v77, v79, v79
	v_fmac_f32_e32 v73, v75, v75
	v_add_f32_e32 v76, v77, v73
	v_pk_add_f32 v[68:69], v[68:69], v[100:101]
	v_pk_add_f32 v[72:73], v[64:65], v[96:97]
	v_mul_f32_e32 v64, v69, v69
	v_mul_f32_e32 v65, v73, v73
	v_cvt_pk_bf16_f32 v83, v74, v75
	v_pk_add_f32 v[70:71], v[70:71], v[102:103]
	v_pk_add_f32 v[74:75], v[66:67], v[98:99]
	v_fmac_f32_e32 v64, v68, v68
	v_fmac_f32_e32 v65, v72, v72
	v_fmac_f32_e32 v64, v70, v70
	v_fmac_f32_e32 v65, v74, v74
	v_fmac_f32_e32 v64, v71, v71
	v_fmac_f32_e32 v65, v75, v75
	v_add_f32_e32 v64, v64, v65
	v_add_f32_e32 v64, v76, v64
	ds_bpermute_b32 v65, v118, v64
	v_readlane_b32 s24, v250, 9
	v_readlane_b32 s25, v250, 10
	v_cvt_pk_bf16_f32 v81, v78, v79
	v_cvt_pk_bf16_f32 v66, v68, v69
	s_waitcnt lgkmcnt(0)
	v_add_f32_e32 v64, v64, v65
	ds_bpermute_b32 v65, v119, v64
	v_lshl_add_u64 v[84:85], v[84:85], 1, s[24:25]
	global_store_dwordx4 v[84:85], v[80:83], off
	global_store_dwordx4 v[114:115], v[68:71], off offset:512
	global_store_dwordx4 v[114:115], v[72:75], off offset:528
	v_cvt_pk_bf16_f32 v67, v70, v71
	v_cvt_pk_bf16_f32 v68, v72, v73
	v_cvt_pk_bf16_f32 v69, v74, v75
	global_store_dwordx4 v[84:85], v[66:69], off offset:256
	s_and_saveexec_b64 s[24:25], s[6:7]
	s_cbranch_execz .LBB0_82
	s_waitcnt lgkmcnt(0)
	v_add_f32_e32 v64, v64, v65
	s_mov_b64 s[26:27], -1
	s_and_b64 vcc, exec, s[12:13]
	s_cbranch_vccz .LBB0_80
	v_readlane_b32 s26, v250, 37
	v_lshlrev_b64 v[66:67], 5, v[112:113]
	v_readlane_b32 s27, v250, 38
	s_nop 1
	v_lshl_add_u64 v[66:67], s[26:27], 0, v[66:67]
	v_lshl_add_u64 v[66:67], s[14:15], 2, v[66:67]
	global_atomic_add_f32 v[66:67], v64, off
	s_mov_b64 s[26:27], 0

; DEV bf16x8 pack8(f32x4 a, f32x4 b) { u32x4 w; w.x = cvt_pk_bf16(a[0], a[1]); w.y = cvt_pk_bf16(a[2], a[3]); w.z = cvt_pk_bf16(b[0], b[1]); w.w = cvt_pk_bf16(b[2], b[3]); return __builtin_bit_cast(bf16x8, w); }
;     DEV void operator()(AccRef acc, const pg8::Unit& u, int wr, int wc, int fr, int fq) const {
;     ...
;         for (int am = 0; am < 4; ++am) { const int ai = am >> 1, m0 = (am & 1) * 2;
;             f32x4 bv[4][2][2];
; #pragma unroll
;             for (int m = m0; m < m0 + 2; ++m)
; #pragma unroll
;                 for (int bj = 0; bj < 2; ++bj)
; #pragma unroll
;                     for (int n = 0; n < 2; ++n) bv[m][bj][n] = *(const f32x4*)(base + (size_t)(row0 + ai * 128 + m * 16) * 2048 + col0 + bj * 128 + n * 4);
; #pragma unroll
;             for (int m = m0; m < m0 + 2; ++m) { const size_t off = (size_t)(row0 + ai * 128 + m * 16) * 2048 + col0; float sq = 0.f;
; #pragma unroll
;                 for (int bj = 0; bj < 2; ++bj) { const f32x4 o0 = bv[m][bj][0] + scale * acc[ai][bj][m][0], o1 = bv[m][bj][1] + scale * acc[ai][bj][m][1];
;                     *(f32x4*)(out + off + bj * 128) = o0; *(f32x4*)(out + off + bj * 128 + 4) = o1;
;                     if (xb) { *(u32x4*)(xb + off + bj * 128) = __builtin_bit_cast(u32x4, pack8(o0, o1));
;                         sq += (o0[0] * o0[0] + o0[1] * o0[1] + o0[2] * o0[2] + o0[3] * o0[3]) + (o1[0] * o1[0] + o1[1] * o1[1] + o1[2] * o1[2] + o1[3] * o1[3]); } }
;                 if (ssout) { sq += __shfl_xor(sq, 16); sq += __shfl_xor(sq, 32);
;                     if (fq == 0) { if (red) red[(ai * 128 + wr * 64 + m * 16 + fr) * 4 + wc] = sq; else atomicAdd(ssout + (size_t)(row0 + ai * 128 + m * 16) * 8 + u.pn, sq); } } }
.LBB0_82:
	s_or_b64 exec, exec, s[24:25]
	v_add_u32_e32 v84, 0x80, v156
	v_ashrrev_i32_e32 v85, 31, v84
	s_waitcnt lgkmcnt(0)
	v_lshlrev_b64 v[64:65], 13, v[84:85]
	v_lshl_add_u64 v[102:103], v[158:159], 0, v[64:65]
	s_waitcnt vmcnt(4)
	v_mov_b32_e32 v86, v218
	v_mov_b32_e32 v87, v219
	v_mov_b32_e32 v88, v220
	v_mov_b32_e32 v89, v221
	v_mov_b32_e32 v90, v222
	v_mov_b32_e32 v91, v223
	v_mov_b32_e32 v92, v224
	v_mov_b32_e32 v93, v225
	v_mov_b32_e32 v94, v226
	v_mov_b32_e32 v95, v227
	v_mov_b32_e32 v96, v228
	v_mov_b32_e32 v97, v229
	v_mov_b32_e32 v98, v230
	v_mov_b32_e32 v99, v231
	v_mov_b32_e32 v100, v232
	v_mov_b32_e32 v101, v233
	v_add_u32_e32 v80, 0x90, v156
	v_ashrrev_i32_e32 v81, 31, v80
	v_lshlrev_b64 v[64:65], 13, v[80:81]
	v_lshl_add_u64 v[82:83], v[158:159], 0, v[64:65]
	v_mov_b32_e32 v72, v234
	v_mov_b32_e32 v73, v235
	v_mov_b32_e32 v74, v236
	v_mov_b32_e32 v75, v237
	v_mov_b32_e32 v76, v238
	v_mov_b32_e32 v77, v239
	v_mov_b32_e32 v78, v240
	v_mov_b32_e32 v79, v241
	v_mov_b32_e32 v64, v242
	v_mov_b32_e32 v65, v243
	v_mov_b32_e32 v66, v244
	v_mov_b32_e32 v67, v245
	v_mov_b32_e32 v68, v246
	v_mov_b32_e32 v69, v247
	v_mov_b32_e32 v70, v248
	v_mov_b32_e32 v71, v249
	v_readlane_b32 s24, v254, 16
	v_readlane_b32 s25, v254, 17
	v_add_u32_e32 v255, 160, v156
	v_lshlrev_b32_e32 v255, 13, v255
	v_lshl_add_u32 v255, v154, 2, v255
	s_nop 1
	global_load_dwordx4 v[218:221], v255, s[24:25]
	global_load_dwordx4 v[222:225], v255, s[24:25] offset:16
	global_load_dwordx4 v[226:229], v255, s[24:25] offset:512
	global_load_dwordx4 v[230:233], v255, s[24:25] offset:528
	v_add_u32_e32 v255, 176, v156
	v_lshlrev_b32_e32 v255, 13, v255
	v_lshl_add_u32 v255, v154, 2, v255
	global_load_dwordx4 v[234:237], v255, s[24:25] offset:16
	global_load_dwordx4 v[238:241], v255, s[24:25]
	global_load_dwordx4 v[242:245], v255, s[24:25] offset:528
	global_load_dwordx4 v[246:249], v255, s[24:25] offset:512
	v_lshlrev_b64 v[104:105], 11, v[84:85]
	v_readlane_b32 s24, v250, 9
	v_lshl_add_u64 v[104:105], v[104:105], 0, v[154:155]
	v_readlane_b32 s25, v250, 10
	v_pk_add_f32 v[62:63], v[62:63], v[88:89]
	v_pk_add_f32 v[60:61], v[60:61], v[86:87]
	v_pk_add_f32 v[56:57], v[56:57], v[90:91]
	v_pk_add_f32 v[52:53], v[52:53], v[94:95]
	v_pk_add_f32 v[86:87], v[48:49], v[98:99]
	v_pk_add_f32 v[58:59], v[58:59], v[92:93]
	v_pk_add_f32 v[88:89], v[50:51], v[100:101]
	global_store_dwordx4 v[102:103], v[60:63], off
	global_store_dwordx4 v[102:103], v[56:59], off offset:16
	v_cvt_pk_bf16_f32 v48, v60, v61
	v_cvt_pk_bf16_f32 v50, v56, v57
	v_mul_f32_e32 v61, v61, v61
	v_mul_f32_e32 v57, v57, v57
	v_mul_f32_e32 v90, v53, v53
	v_mul_f32_e32 v91, v87, v87
	v_pk_add_f32 v[54:55], v[54:55], v[96:97]
	v_fmac_f32_e32 v61, v60, v60
	v_fmac_f32_e32 v57, v56, v56
	v_fmac_f32_e32 v90, v52, v52
	v_fmac_f32_e32 v91, v86, v86
	v_fmac_f32_e32 v61, v62, v62
	v_fmac_f32_e32 v57, v58, v58
	v_fmac_f32_e32 v90, v54, v54
	v_fmac_f32_e32 v91, v88, v88
	v_fmac_f32_e32 v61, v63, v63
	v_fmac_f32_e32 v57, v59, v59
	v_fmac_f32_e32 v90, v55, v55
	v_fmac_f32_e32 v91, v89, v89
	v_add_f32_e32 v56, v61, v57
	v_add_f32_e32 v57, v90, v91
	v_add_f32_e32 v56, v56, v57
	ds_bpermute_b32 v57, v118, v56
	v_lshl_add_u64 v[104:105], v[104:105], 1, s[24:25]
	v_cvt_pk_bf16_f32 v49, v62, v63
	v_cvt_pk_bf16_f32 v51, v58, v59
	global_store_dwordx4 v[104:105], v[48:51], off
	global_store_dwordx4 v[102:103], v[52:55], off offset:512
	global_store_dwordx4 v[102:103], v[86:89], off offset:528
	s_waitcnt lgkmcnt(0)
	v_add_f32_e32 v48, v56, v57
	ds_bpermute_b32 v49, v119, v48
	v_cvt_pk_bf16_f32 v50, v52, v53
	v_cvt_pk_bf16_f32 v51, v54, v55
	v_cvt_pk_bf16_f32 v52, v86, v87
	v_cvt_pk_bf16_f32 v53, v88, v89
	global_store_dwordx4 v[104:105], v[50:53], off offset:256
	s_and_saveexec_b64 s[24:25], s[6:7]
	s_cbranch_execz .LBB0_87
	s_waitcnt lgkmcnt(0)
	v_add_f32_e32 v48, v48, v49
	s_mov_b64 s[26:27], -1
	s_and_b64 vcc, exec, s[12:13]
	s_cbranch_vccz .LBB0_85
	v_readlane_b32 s26, v250, 37
	v_lshlrev_b64 v[50:51], 5, v[84:85]
	v_readlane_b32 s27, v250, 38
	s_nop 1
	v_lshl_add_u64 v[50:51], s[26:27], 0, v[50:51]
	v_lshl_add_u64 v[50:51], s[14:15], 2, v[50:51]
	global_atomic_add_f32 v[50:51], v48, off
	s_mov_b64 s[26:27], 0

; DEV bf16x8 pack8(f32x4 a, f32x4 b) { u32x4 w; w.x = cvt_pk_bf16(a[0], a[1]); w.y = cvt_pk_bf16(a[2], a[3]); w.z = cvt_pk_bf16(b[0], b[1]); w.w = cvt_pk_bf16(b[2], b[3]); return __builtin_bit_cast(bf16x8, w); }
;     DEV void operator()(AccRef acc, const pg8::Unit& u, int wr, int wc, int fr, int fq) const {
;     ...
;             for (int m = m0; m < m0 + 2; ++m) { const size_t off = (size_t)(row0 + ai * 128 + m * 16) * 2048 + col0; float sq = 0.f;
; #pragma unroll
;                 for (int bj = 0; bj < 2; ++bj) { const f32x4 o0 = bv[m][bj][0] + scale * acc[ai][bj][m][0], o1 = bv[m][bj][1] + scale * acc[ai][bj][m][1];
;                     *(f32x4*)(out + off + bj * 128) = o0; *(f32x4*)(out + off + bj * 128 + 4) = o1;
;                     if (xb) { *(u32x4*)(xb + off + bj * 128) = __builtin_bit_cast(u32x4, pack8(o0, o1));
;                         sq += (o0[0] * o0[0] + o0[1] * o0[1] + o0[2] * o0[2] + o0[3] * o0[3]) + (o1[0] * o1[0] + o1[1] * o1[1] + o1[2] * o1[2] + o1[3] * o1[3]); } }
;                 if (ssout) { sq += __shfl_xor(sq, 16); sq += __shfl_xor(sq, 32);
;                     if (fq == 0) { if (red) red[(ai * 128 + wr * 64 + m * 16 + fr) * 4 + wc] = sq; else atomicAdd(ssout + (size_t)(row0 + ai * 128 + m * 16) * 8 + u.pn, sq); } } }
.LBB0_87:
	s_or_b64 exec, exec, s[24:25]
	s_waitcnt lgkmcnt(0)
	v_lshlrev_b64 v[48:49], 11, v[80:81]
	v_pk_add_f32 v[46:47], v[46:47], v[78:79]
	v_pk_add_f32 v[44:45], v[44:45], v[76:77]
	v_pk_add_f32 v[40:41], v[40:41], v[72:73]
	v_lshl_add_u64 v[52:53], v[48:49], 0, v[154:155]
	v_pk_add_f32 v[42:43], v[42:43], v[74:75]
	global_store_dwordx4 v[82:83], v[44:47], off
	global_store_dwordx4 v[82:83], v[40:43], off offset:16
	v_cvt_pk_bf16_f32 v48, v44, v45
	v_cvt_pk_bf16_f32 v50, v40, v41
	v_mul_f32_e32 v45, v45, v45
	v_mul_f32_e32 v41, v41, v41
	v_fmac_f32_e32 v45, v44, v44
	v_fmac_f32_e32 v41, v40, v40
	v_fmac_f32_e32 v45, v46, v46
	v_fmac_f32_e32 v41, v42, v42
	v_fmac_f32_e32 v45, v47, v47
	v_fmac_f32_e32 v41, v43, v43
	v_add_f32_e32 v44, v45, v41
	v_pk_add_f32 v[36:37], v[36:37], v[68:69]
	v_pk_add_f32 v[40:41], v[32:33], v[64:65]
	v_mul_f32_e32 v32, v37, v37
	v_mul_f32_e32 v33, v41, v41
	v_cvt_pk_bf16_f32 v51, v42, v43
	v_pk_add_f32 v[38:39], v[38:39], v[70:71]
	v_pk_add_f32 v[42:43], v[34:35], v[66:67]
	v_fmac_f32_e32 v32, v36, v36
	v_fmac_f32_e32 v33, v40, v40
	v_fmac_f32_e32 v32, v38, v38
	v_fmac_f32_e32 v33, v42, v42
	v_fmac_f32_e32 v32, v39, v39
	v_fmac_f32_e32 v33, v43, v43
	v_add_f32_e32 v32, v32, v33
	v_add_f32_e32 v32, v44, v32
	ds_bpermute_b32 v33, v118, v32
	v_readlane_b32 s24, v250, 9
	v_readlane_b32 s25, v250, 10
	v_cvt_pk_bf16_f32 v49, v46, v47
	v_cvt_pk_bf16_f32 v34, v36, v37
	s_waitcnt lgkmcnt(0)
	v_add_f32_e32 v32, v32, v33
	ds_bpermute_b32 v33, v119, v32
	v_lshl_add_u64 v[52:53], v[52:53], 1, s[24:25]
	global_store_dwordx4 v[52:53], v[48:51], off
	global_store_dwordx4 v[82:83], v[36:39], off offset:512
	global_store_dwordx4 v[82:83], v[40:43], off offset:528
	v_cvt_pk_bf16_f32 v35, v38, v39
	v_cvt_pk_bf16_f32 v36, v40, v41
	v_cvt_pk_bf16_f32 v37, v42, v43
	global_store_dwordx4 v[52:53], v[34:37], off offset:256
	s_and_saveexec_b64 s[24:25], s[6:7]
	s_cbranch_execz .LBB0_92
	s_waitcnt lgkmcnt(0)
	v_add_f32_e32 v32, v32, v33
	s_mov_b64 s[26:27], -1
	s_and_b64 vcc, exec, s[12:13]
	s_cbranch_vccz .LBB0_90
	v_readlane_b32 s26, v250, 37
	v_lshlrev_b64 v[34:35], 5, v[80:81]
	v_readlane_b32 s27, v250, 38
	s_nop 1
	v_lshl_add_u64 v[34:35], s[26:27], 0, v[34:35]
	v_lshl_add_u64 v[34:35], s[14:15], 2, v[34:35]
	global_atomic_add_f32 v[34:35], v32, off
	s_mov_b64 s[26:27], 0

; DEV bf16x8 pack8(f32x4 a, f32x4 b) { u32x4 w; w.x = cvt_pk_bf16(a[0], a[1]); w.y = cvt_pk_bf16(a[2], a[3]); w.z = cvt_pk_bf16(b[0], b[1]); w.w = cvt_pk_bf16(b[2], b[3]); return __builtin_bit_cast(bf16x8, w); }
;     DEV void operator()(AccRef acc, const pg8::Unit& u, int wr, int wc, int fr, int fq) const {
;     ...
;         for (int am = 0; am < 4; ++am) { const int ai = am >> 1, m0 = (am & 1) * 2;
;             f32x4 bv[4][2][2];
; #pragma unroll
;             for (int m = m0; m < m0 + 2; ++m)
; #pragma unroll
;                 for (int bj = 0; bj < 2; ++bj)
; #pragma unroll
;                     for (int n = 0; n < 2; ++n) bv[m][bj][n] = *(const f32x4*)(base + (size_t)(row0 + ai * 128 + m * 16) * 2048 + col0 + bj * 128 + n * 4);
; #pragma unroll
;             for (int m = m0; m < m0 + 2; ++m) { const size_t off = (size_t)(row0 + ai * 128 + m * 16) * 2048 + col0; float sq = 0.f;
; #pragma unroll
;                 for (int bj = 0; bj < 2; ++bj) { const f32x4 o0 = bv[m][bj][0] + scale * acc[ai][bj][m][0], o1 = bv[m][bj][1] + scale * acc[ai][bj][m][1];
;                     *(f32x4*)(out + off + bj * 128) = o0; *(f32x4*)(out + off + bj * 128 + 4) = o1;
;                     if (xb) { *(u32x4*)(xb + off + bj * 128) = __builtin_bit_cast(u32x4, pack8(o0, o1));
;                         sq += (o0[0] * o0[0] + o0[1] * o0[1] + o0[2] * o0[2] + o0[3] * o0[3]) + (o1[0] * o1[0] + o1[1] * o1[1] + o1[2] * o1[2] + o1[3] * o1[3]); } }
;                 if (ssout) { sq += __shfl_xor(sq, 16); sq += __shfl_xor(sq, 32);
;                     if (fq == 0) { if (red) red[(ai * 128 + wr * 64 + m * 16 + fr) * 4 + wc] = sq; else atomicAdd(ssout + (size_t)(row0 + ai * 128 + m * 16) * 8 + u.pn, sq); } } }
.LBB0_92:
	s_or_b64 exec, exec, s[24:25]
	v_add_u32_e32 v52, 0xa0, v156
	v_ashrrev_i32_e32 v53, 31, v52
	s_waitcnt lgkmcnt(0)
	v_lshlrev_b64 v[32:33], 13, v[52:53]
	v_lshl_add_u64 v[70:71], v[158:159], 0, v[32:33]
	s_waitcnt vmcnt(4)
	v_mov_b32_e32 v54, v218
	v_mov_b32_e32 v55, v219
	v_mov_b32_e32 v56, v220
	v_mov_b32_e32 v57, v221
	v_mov_b32_e32 v58, v222
	v_mov_b32_e32 v59, v223
	v_mov_b32_e32 v60, v224
	v_mov_b32_e32 v61, v225
	v_mov_b32_e32 v62, v226
	v_mov_b32_e32 v63, v227
	v_mov_b32_e32 v64, v228
	v_mov_b32_e32 v65, v229
	v_mov_b32_e32 v66, v230
	v_mov_b32_e32 v67, v231
	v_mov_b32_e32 v68, v232
	v_mov_b32_e32 v69, v233
	v_add_u32_e32 v48, 0xb0, v156
	v_ashrrev_i32_e32 v49, 31, v48
	v_lshlrev_b64 v[32:33], 13, v[48:49]
	v_lshl_add_u64 v[50:51], v[158:159], 0, v[32:33]
	v_mov_b32_e32 v40, v234
	v_mov_b32_e32 v41, v235
	v_mov_b32_e32 v42, v236
	v_mov_b32_e32 v43, v237
	v_mov_b32_e32 v44, v238
	v_mov_b32_e32 v45, v239
	v_mov_b32_e32 v46, v240
	v_mov_b32_e32 v47, v241
	v_mov_b32_e32 v32, v242
	v_mov_b32_e32 v33, v243
	v_mov_b32_e32 v34, v244
	v_mov_b32_e32 v35, v245
	v_mov_b32_e32 v36, v246
	v_mov_b32_e32 v37, v247
	v_mov_b32_e32 v38, v248
	v_mov_b32_e32 v39, v249
	v_lshlrev_b64 v[72:73], 11, v[52:53]
	v_readlane_b32 s24, v250, 9
	v_lshl_add_u64 v[72:73], v[72:73], 0, v[154:155]
	v_readlane_b32 s25, v250, 10
	v_pk_add_f32 v[30:31], v[30:31], v[56:57]
	v_pk_add_f32 v[28:29], v[28:29], v[54:55]
	v_pk_add_f32 v[24:25], v[24:25], v[58:59]
	v_pk_add_f32 v[20:21], v[20:21], v[62:63]
	v_pk_add_f32 v[54:55], v[16:17], v[66:67]
	v_pk_add_f32 v[26:27], v[26:27], v[60:61]
	v_pk_add_f32 v[56:57], v[18:19], v[68:69]
	global_store_dwordx4 v[70:71], v[28:31], off
	global_store_dwordx4 v[70:71], v[24:27], off offset:16
	v_cvt_pk_bf16_f32 v16, v28, v29
	v_cvt_pk_bf16_f32 v18, v24, v25
	v_mul_f32_e32 v29, v29, v29
	v_mul_f32_e32 v25, v25, v25
	v_mul_f32_e32 v58, v21, v21
	v_mul_f32_e32 v59, v55, v55
	v_pk_add_f32 v[22:23], v[22:23], v[64:65]
	v_fmac_f32_e32 v29, v28, v28
	v_fmac_f32_e32 v25, v24, v24
	v_fmac_f32_e32 v58, v20, v20
	v_fmac_f32_e32 v59, v54, v54
	v_fmac_f32_e32 v29, v30, v30
	v_fmac_f32_e32 v25, v26, v26
	v_fmac_f32_e32 v58, v22, v22
	v_fmac_f32_e32 v59, v56, v56
	v_fmac_f32_e32 v29, v31, v31
	v_fmac_f32_e32 v25, v27, v27
	v_fmac_f32_e32 v58, v23, v23
	v_fmac_f32_e32 v59, v57, v57
	v_add_f32_e32 v24, v29, v25
	v_add_f32_e32 v25, v58, v59
	v_add_f32_e32 v24, v24, v25
	ds_bpermute_b32 v25, v118, v24
	v_lshl_add_u64 v[72:73], v[72:73], 1, s[24:25]
	v_cvt_pk_bf16_f32 v17, v30, v31
	v_cvt_pk_bf16_f32 v19, v26, v27
	global_store_dwordx4 v[72:73], v[16:19], off
	global_store_dwordx4 v[70:71], v[20:23], off offset:512
	global_store_dwordx4 v[70:71], v[54:57], off offset:528
	s_waitcnt lgkmcnt(0)
	v_add_f32_e32 v16, v24, v25
	ds_bpermute_b32 v17, v119, v16
	v_cvt_pk_bf16_f32 v18, v20, v21
	v_cvt_pk_bf16_f32 v19, v22, v23
	v_cvt_pk_bf16_f32 v20, v54, v55
	v_cvt_pk_bf16_f32 v21, v56, v57
	global_store_dwordx4 v[72:73], v[18:21], off offset:256
	s_and_saveexec_b64 s[24:25], s[6:7]
	s_cbranch_execz .LBB0_97
	s_waitcnt lgkmcnt(0)
	v_add_f32_e32 v16, v16, v17
	s_mov_b64 s[26:27], -1
	s_and_b64 vcc, exec, s[12:13]
	s_cbranch_vccz .LBB0_95
	v_readlane_b32 s26, v250, 37
	v_lshlrev_b64 v[18:19], 5, v[52:53]
	v_readlane_b32 s27, v250, 38
	s_nop 1
	v_lshl_add_u64 v[18:19], s[26:27], 0, v[18:19]
	v_lshl_add_u64 v[18:19], s[14:15], 2, v[18:19]
	global_atomic_add_f32 v[18:19], v16, off
	s_mov_b64 s[26:27], 0

; DEV bf16x8 pack8(f32x4 a, f32x4 b) { u32x4 w; w.x = cvt_pk_bf16(a[0], a[1]); w.y = cvt_pk_bf16(a[2], a[3]); w.z = cvt_pk_bf16(b[0], b[1]); w.w = cvt_pk_bf16(b[2], b[3]); return __builtin_bit_cast(bf16x8, w); }
;     DEV void operator()(AccRef acc, const pg8::Unit& u, int wr, int wc, int fr, int fq) const {
;     ...
;             for (int m = m0; m < m0 + 2; ++m) { const size_t off = (size_t)(row0 + ai * 128 + m * 16) * 2048 + col0; float sq = 0.f;
; #pragma unroll
;                 for (int bj = 0; bj < 2; ++bj) { const f32x4 o0 = bv[m][bj][0] + scale * acc[ai][bj][m][0], o1 = bv[m][bj][1] + scale * acc[ai][bj][m][1];
;                     *(f32x4*)(out + off + bj * 128) = o0; *(f32x4*)(out + off + bj * 128 + 4) = o1;
;                     if (xb) { *(u32x4*)(xb + off + bj * 128) = __builtin_bit_cast(u32x4, pack8(o0, o1));
;                         sq += (o0[0] * o0[0] + o0[1] * o0[1] + o0[2] * o0[2] + o0[3] * o0[3]) + (o1[0] * o1[0] + o1[1] * o1[1] + o1[2] * o1[2] + o1[3] * o1[3]); } }
;                 if (ssout) { sq += __shfl_xor(sq, 16); sq += __shfl_xor(sq, 32);
;                     if (fq == 0) { if (red) red[(ai * 128 + wr * 64 + m * 16 + fr) * 4 + wc] = sq; else atomicAdd(ssout + (size_t)(row0 + ai * 128 + m * 16) * 8 + u.pn, sq); } } }
.LBB0_97:
	s_or_b64 exec, exec, s[24:25]
	s_waitcnt lgkmcnt(0)
	v_lshlrev_b64 v[16:17], 11, v[48:49]
	v_pk_add_f32 v[14:15], v[14:15], v[46:47]
	v_pk_add_f32 v[12:13], v[12:13], v[44:45]
	v_pk_add_f32 v[8:9], v[8:9], v[40:41]
	v_lshl_add_u64 v[20:21], v[16:17], 0, v[154:155]
	v_pk_add_f32 v[10:11], v[10:11], v[42:43]
	global_store_dwordx4 v[50:51], v[12:15], off
	global_store_dwordx4 v[50:51], v[8:11], off offset:16
	v_cvt_pk_bf16_f32 v16, v12, v13
	v_cvt_pk_bf16_f32 v18, v8, v9
	v_mul_f32_e32 v13, v13, v13
	v_mul_f32_e32 v9, v9, v9
	v_fmac_f32_e32 v13, v12, v12
	v_fmac_f32_e32 v9, v8, v8
	v_fmac_f32_e32 v13, v14, v14
	v_fmac_f32_e32 v9, v10, v10
	v_fmac_f32_e32 v13, v15, v15
	v_fmac_f32_e32 v9, v11, v11
	v_add_f32_e32 v12, v13, v9
	v_pk_add_f32 v[4:5], v[4:5], v[36:37]
	v_pk_add_f32 v[8:9], v[0:1], v[32:33]
	v_mul_f32_e32 v0, v5, v5
	v_mul_f32_e32 v1, v9, v9
	v_cvt_pk_bf16_f32 v19, v10, v11
	v_pk_add_f32 v[6:7], v[6:7], v[38:39]
	v_pk_add_f32 v[10:11], v[2:3], v[34:35]
	v_fmac_f32_e32 v0, v4, v4
	v_fmac_f32_e32 v1, v8, v8
	v_fmac_f32_e32 v0, v6, v6
	v_fmac_f32_e32 v1, v10, v10
	v_fmac_f32_e32 v0, v7, v7
	v_fmac_f32_e32 v1, v11, v11
	v_add_f32_e32 v0, v0, v1
	v_add_f32_e32 v0, v12, v0
	ds_bpermute_b32 v1, v118, v0
	v_readlane_b32 s24, v250, 9
	v_readlane_b32 s25, v250, 10
	v_cvt_pk_bf16_f32 v17, v14, v15
	v_cvt_pk_bf16_f32 v2, v4, v5
	s_waitcnt lgkmcnt(0)
	v_add_f32_e32 v0, v0, v1
	ds_bpermute_b32 v1, v119, v0
	v_lshl_add_u64 v[20:21], v[20:21], 1, s[24:25]
	global_store_dwordx4 v[20:21], v[16:19], off
	global_store_dwordx4 v[50:51], v[4:7], off offset:512
	global_store_dwordx4 v[50:51], v[8:11], off offset:528
	v_cvt_pk_bf16_f32 v3, v6, v7
	v_cvt_pk_bf16_f32 v4, v8, v9
	v_cvt_pk_bf16_f32 v5, v10, v11
	global_store_dwordx4 v[20:21], v[2:5], off offset:256
	s_and_saveexec_b64 s[24:25], s[6:7]
	s_cbranch_execz .LBB0_102
	s_waitcnt lgkmcnt(0)
	v_add_f32_e32 v0, v0, v1
	s_mov_b64 s[26:27], -1
	s_and_b64 vcc, exec, s[12:13]
	s_cbranch_vccz .LBB0_100
	v_readlane_b32 s26, v250, 37
	v_lshlrev_b64 v[2:3], 5, v[48:49]
	v_readlane_b32 s27, v250, 38
	s_nop 1
	v_lshl_add_u64 v[2:3], s[26:27], 0, v[2:3]
	v_lshl_add_u64 v[2:3], s[14:15], 2, v[2:3]
	global_atomic_add_f32 v[2:3], v0, off
	s_mov_b64 s[26:27], 0

; #define PG8_STAGE(bufoff, gbase, voff) do { _Pragma("unroll") for (int _i = 0; _i < 2; ++_i) \
;         __builtin_amdgcn_global_load_lds((const unsigned*)((const char*)(gbase) + (voff)[_i]), (LAS unsigned*)(lds + (bufoff) + ldsw + _i * 8192), 16, 0, 0); } while (0)
; #define PG8_LDA(dst, b, h) do { _Pragma("unroll") for (int m = 0; m < 4; ++m) _Pragma("unroll") for (int k = 0; k < 2; ++k) dst[m][k] = *(const LAS bf16x8*)(lds + PG8_SA(b, h) + aoff + m * 2048 + k * 1024); } while (0)
; #define PG8_LDB(dst, b, h) do { _Pragma("unroll") for (int n = 0; n < 2; ++n) _Pragma("unroll") for (int k = 0; k < 2; ++k) dst[n][k] = *(const LAS bf16x8*)(lds + PG8_SB(b, h) + boff + n * 2048 + k * 1024); } while (0)
; #define PG8_MMA(ai, bj, At, Bt) do { __builtin_amdgcn_s_setprio(1); _Pragma("unroll") for (int m = 0; m < 4; ++m) _Pragma("unroll") for (int n = 0; n < 2; ++n) _Pragma("unroll") for (int k = 0; k < 2; ++k) \
;         acc[ai][bj][m][n] = __builtin_amdgcn_mfma_f32_16x16x32_bf16(Bt[n][k], At[m][k], acc[ai][bj][m][n], 0, 0, 0); __builtin_amdgcn_s_setprio(0); } while (0)
; #define PG8_WAIT_L(n) asm volatile("s_waitcnt lgkmcnt(" #n ")" ::: "memory")
; #define PG8_BAR __builtin_amdgcn_s_barrier()
; #define PG8_SCHED __builtin_amdgcn_sched_barrier(0)
; template <class Epi>
; DEV void gemm_phase(LAS unsigned char* lds, const Gemm g, const StaticOrder& S, const Epi& E) {
;     ...
;             PG8_LDB(B0, 0, 0); PG8_SCHED; PG8_LDA(At, 0, 0); PG8_STAGE(PG8_SA(1, 1), a1 + hstep, voffA);
;             PG8_WAIT_L(8); PG8_BAR; PG8_WAIT_L(0); PG8_MMA(0, 0, At, B0); PG8_BAR; PG8_SCHED;
;             PG8_LDB(B1, 0, 1); PG8_STAGE(PG8_SB(0, 0), b2, voffB);
;             PG8_BAR; PG8_WAIT_L(0); PG8_MMA(0, 1, At, B1); PG8_BAR;
;             PG8_LDA(At, 0, 1); PG8_STAGE(PG8_SA(0, 0), a2, voffA);
;             PG8_BAR; PG8_WAIT_L(0); PG8_MMA(1, 0, At, B0); PG8_BAR; PG8_SCHED;
.LBB0_260:
	s_add_u32 s34, s30, 0xfffe0080
	s_addc_u32 s35, s31, -1
	s_add_i32 s55, 0, 0x10000
	v_add_u32_e32 v140, s55, v178
	ds_read_b128 v[128:131], v140
	ds_read_b128 v[132:135], v140 offset:1024
	ds_read_b128 v[136:139], v140 offset:2048
	ds_read_b128 v[140:143], v140 offset:3072
	s_cmp_eq_u32 s54, 4
	s_cselect_b32 s37, s19, s35
	s_cselect_b32 s36, s23, s34
	s_cselect_b32 s35, s21, s53
	s_cselect_b32 s34, s29, s52
	v_lshl_add_u64 v[158:159], s[30:31], 0, v[150:151]
	s_add_i32 m0, s43, 0xc000
	ds_read_b128 v[154:157], v181
	ds_read_b128 v[174:177], v181 offset:1024
	ds_read_b128 v[182:185], v181 offset:2048
	ds_read_b128 v[186:189], v181 offset:3072
	ds_read_b128 v[190:193], v181 offset:4096
	ds_read_b128 v[194:197], v181 offset:5120
	ds_read_b128 v[214:217], v181 offset:6144
	ds_read_b128 v[218:221], v181 offset:7168
	global_load_lds_dwordx4 v[158:159], off
	v_lshl_add_u64 v[158:159], s[30:31], 0, v[152:153]
	s_add_i32 m0, s43, 0xe000
	s_nop 0
	global_load_lds_dwordx4 v[158:159], off
	s_waitcnt lgkmcnt(8)
	s_barrier
	s_waitcnt lgkmcnt(0)
	s_setprio 1
	v_mfma_f32_16x16x32_bf16 v[124:127], v[128:131], v[154:157], v[124:127]
	v_mfma_f32_16x16x32_bf16 v[120:123], v[136:139], v[154:157], v[120:123]
	v_mfma_f32_16x16x32_bf16 v[108:111], v[128:131], v[182:185], v[108:111]
	v_mfma_f32_16x16x32_bf16 v[104:107], v[136:139], v[182:185], v[104:107]
	v_mfma_f32_16x16x32_bf16 v[92:95], v[128:131], v[190:193], v[92:95]
	v_mfma_f32_16x16x32_bf16 v[88:91], v[136:139], v[190:193], v[88:91]
	v_mfma_f32_16x16x32_bf16 v[76:79], v[128:131], v[214:217], v[76:79]
	v_mfma_f32_16x16x32_bf16 v[72:75], v[136:139], v[214:217], v[72:75]
	v_mfma_f32_16x16x32_bf16 v[124:127], v[132:135], v[174:177], v[124:127]
	v_mfma_f32_16x16x32_bf16 v[120:123], v[140:143], v[174:177], v[120:123]
	v_mfma_f32_16x16x32_bf16 v[108:111], v[132:135], v[186:189], v[108:111]
	v_mfma_f32_16x16x32_bf16 v[104:107], v[140:143], v[186:189], v[104:107]
	v_mfma_f32_16x16x32_bf16 v[92:95], v[132:135], v[194:197], v[92:95]
	v_mfma_f32_16x16x32_bf16 v[88:91], v[140:143], v[194:197], v[88:91]
	v_mfma_f32_16x16x32_bf16 v[76:79], v[132:135], v[218:221], v[76:79]
	v_mfma_f32_16x16x32_bf16 v[72:75], v[140:143], v[218:221], v[72:75]
	s_setprio 0
	s_barrier
	s_add_i32 s58, 0, 0x14000
	v_add_u32_e32 v158, s58, v178
	s_add_i32 s55, s55, s42
	ds_read_b128 v[222:225], v158
	ds_read_b128 v[226:229], v158 offset:1024
	ds_read_b128 v[230:233], v158 offset:2048
	ds_read_b128 v[234:237], v158 offset:3072
	v_lshl_add_u64 v[158:159], s[34:35], 0, v[160:161]
	s_mov_b32 m0, s55
	v_lshl_add_u64 v[238:239], s[34:35], 0, v[148:149]
	global_load_lds_dwordx4 v[158:159], off
	s_add_i32 m0, s55, 0x2000
	s_nop 0
	global_load_lds_dwordx4 v[238:239], off
	s_barrier
	s_waitcnt lgkmcnt(0)
	s_setprio 1
	v_mfma_f32_16x16x32_bf16 v[116:119], v[222:225], v[154:157], v[116:119]
	v_mfma_f32_16x16x32_bf16 v[112:115], v[230:233], v[154:157], v[112:115]
	v_mfma_f32_16x16x32_bf16 v[100:103], v[222:225], v[182:185], v[100:103]
	v_mfma_f32_16x16x32_bf16 v[96:99], v[230:233], v[182:185], v[96:99]
	v_mfma_f32_16x16x32_bf16 v[84:87], v[222:225], v[190:193], v[84:87]
	v_mfma_f32_16x16x32_bf16 v[80:83], v[230:233], v[190:193], v[80:83]
	v_mfma_f32_16x16x32_bf16 v[68:71], v[222:225], v[214:217], v[68:71]
	v_mfma_f32_16x16x32_bf16 v[64:67], v[230:233], v[214:217], v[64:67]
	v_mfma_f32_16x16x32_bf16 v[116:119], v[226:229], v[174:177], v[116:119]
	v_mfma_f32_16x16x32_bf16 v[112:115], v[234:237], v[174:177], v[112:115]
	v_mfma_f32_16x16x32_bf16 v[100:103], v[226:229], v[186:189], v[100:103]
	v_mfma_f32_16x16x32_bf16 v[96:99], v[234:237], v[186:189], v[96:99]
	v_mfma_f32_16x16x32_bf16 v[84:87], v[226:229], v[194:197], v[84:87]
	v_mfma_f32_16x16x32_bf16 v[80:83], v[234:237], v[194:197], v[80:83]
	v_mfma_f32_16x16x32_bf16 v[68:71], v[226:229], v[218:221], v[68:71]
	v_mfma_f32_16x16x32_bf16 v[64:67], v[234:237], v[218:221], v[64:67]
	s_setprio 0
	s_mov_b32 m0, s43
	v_lshl_add_u64 v[240:241], s[36:37], 0, v[144:145]
	s_barrier
	ds_read_b128 v[154:157], v181 offset:16384
	ds_read_b128 v[174:177], v181 offset:17408
	ds_read_b128 v[182:185], v181 offset:18432
	ds_read_b128 v[186:189], v181 offset:19456
	ds_read_b128 v[190:193], v181 offset:20480
	ds_read_b128 v[194:197], v181 offset:21504
	ds_read_b128 v[214:217], v181 offset:22528
	ds_read_b128 v[218:221], v181 offset:23552
	global_load_lds_dwordx4 v[240:241], off
	v_lshl_add_u64 v[242:243], s[36:37], 0, v[146:147]
	s_mov_b32 m0, s44
	s_nop 0
	global_load_lds_dwordx4 v[242:243], off
	s_barrier
	s_waitcnt lgkmcnt(0)
	s_setprio 1
	v_mfma_f32_16x16x32_bf16 v[60:63], v[128:131], v[154:157], v[60:63]
	v_mfma_f32_16x16x32_bf16 v[56:59], v[136:139], v[154:157], v[56:59]
	v_mfma_f32_16x16x32_bf16 v[44:47], v[128:131], v[182:185], v[44:47]
	v_mfma_f32_16x16x32_bf16 v[40:43], v[136:139], v[182:185], v[40:43]
	v_mfma_f32_16x16x32_bf16 v[28:31], v[128:131], v[190:193], v[28:31]
	v_mfma_f32_16x16x32_bf16 v[24:27], v[136:139], v[190:193], v[24:27]
	v_mfma_f32_16x16x32_bf16 v[12:15], v[128:131], v[214:217], v[12:15]
	v_mfma_f32_16x16x32_bf16 v[8:11], v[136:139], v[214:217], v[8:11]
	v_mfma_f32_16x16x32_bf16 v[60:63], v[132:135], v[174:177], v[60:63]
	v_mfma_f32_16x16x32_bf16 v[56:59], v[140:143], v[174:177], v[56:59]
	v_mfma_f32_16x16x32_bf16 v[44:47], v[132:135], v[186:189], v[44:47]
	v_mfma_f32_16x16x32_bf16 v[40:43], v[140:143], v[186:189], v[40:43]
	v_mfma_f32_16x16x32_bf16 v[28:31], v[132:135], v[194:197], v[28:31]
	v_mfma_f32_16x16x32_bf16 v[24:27], v[140:143], v[194:197], v[24:27]
	v_mfma_f32_16x16x32_bf16 v[12:15], v[132:135], v[218:221], v[12:15]
	v_mfma_f32_16x16x32_bf16 v[8:11], v[140:143], v[218:221], v[8:11]
	s_setprio 0
	s_barrier
; #define PG8_STAGE(bufoff, gbase, voff) do { _Pragma("unroll") for (int _i = 0; _i < 2; ++_i) \
;         __builtin_amdgcn_global_load_lds((const unsigned*)((const char*)(gbase) + (voff)[_i]), (LAS unsigned*)(lds + (bufoff) + ldsw + _i * 8192), 16, 0, 0); } while (0)
; #define PG8_LDA(dst, b, h) do { _Pragma("unroll") for (int m = 0; m < 4; ++m) _Pragma("unroll") for (int k = 0; k < 2; ++k) dst[m][k] = *(const LAS bf16x8*)(lds + PG8_SA(b, h) + aoff + m * 2048 + k * 1024); } while (0)
; #define PG8_LDB(dst, b, h) do { _Pragma("unroll") for (int n = 0; n < 2; ++n) _Pragma("unroll") for (int k = 0; k < 2; ++k) dst[n][k] = *(const LAS bf16x8*)(lds + PG8_SB(b, h) + boff + n * 2048 + k * 1024); } while (0)
; #define PG8_MMA(ai, bj, At, Bt) do { __builtin_amdgcn_s_setprio(1); _Pragma("unroll") for (int m = 0; m < 4; ++m) _Pragma("unroll") for (int n = 0; n < 2; ++n) _Pragma("unroll") for (int k = 0; k < 2; ++k) \
;         acc[ai][bj][m][n] = __builtin_amdgcn_mfma_f32_16x16x32_bf16(Bt[n][k], At[m][k], acc[ai][bj][m][n], 0, 0, 0); __builtin_amdgcn_s_setprio(0); } while (0)
; #define PG8_WAIT_V(n) asm volatile("s_waitcnt vmcnt(" #n ")" ::: "memory")
; #define PG8_WAIT_L(n) asm volatile("s_waitcnt lgkmcnt(" #n ")" ::: "memory")
; #define PG8_BAR __builtin_amdgcn_s_barrier()
; #define PG8_SCHED __builtin_amdgcn_sched_barrier(0)
; template <class Epi>
; DEV void gemm_phase(LAS unsigned char* lds, const Gemm g, const StaticOrder& S, const Epi& E) {
;     ...
;             PG8_STAGE(PG8_SB(0, 1), b2 + hstep, voffB);
;             PG8_WAIT_V(6); PG8_BAR; PG8_MMA(1, 1, At, B1); PG8_BAR;
;             PG8_LDB(B0, 1, 0); PG8_SCHED; PG8_LDA(At, 1, 0); PG8_STAGE(PG8_SA(0, 1), a2 + hstep, voffA);
;             PG8_WAIT_L(8); PG8_BAR; PG8_WAIT_L(0); PG8_MMA(0, 0, At, B0); PG8_BAR; PG8_SCHED;
;             PG8_LDB(B1, 1, 1); PG8_STAGE(PG8_SB(1, 0), b3, voffB);
;             PG8_BAR; PG8_WAIT_L(0); PG8_MMA(0, 1, At, B1); PG8_BAR;
;             PG8_LDA(At, 1, 1); PG8_STAGE(PG8_SA(1, 0), a3, voffA);
	s_add_u32 s56, s34, 0x20000
	s_addc_u32 s57, s35, 0
	s_add_i32 s55, s58, s42
	v_lshl_add_u64 v[128:129], s[56:57], 0, v[160:161]
	s_mov_b32 m0, s55
	s_nop 0
	global_load_lds_dwordx4 v[128:129], off
	v_lshl_add_u64 v[128:129], s[56:57], 0, v[148:149]
	s_add_i32 m0, s55, 0x2000
	s_nop 0
	global_load_lds_dwordx4 v[128:129], off
	s_waitcnt vmcnt(6)
	s_barrier
	s_setprio 1
	v_mfma_f32_16x16x32_bf16 v[52:55], v[222:225], v[154:157], v[52:55]
	v_mfma_f32_16x16x32_bf16 v[48:51], v[230:233], v[154:157], v[48:51]
	v_mfma_f32_16x16x32_bf16 v[36:39], v[222:225], v[182:185], v[36:39]
	v_mfma_f32_16x16x32_bf16 v[32:35], v[230:233], v[182:185], v[32:35]
	v_mfma_f32_16x16x32_bf16 v[20:23], v[222:225], v[190:193], v[20:23]
	v_mfma_f32_16x16x32_bf16 v[16:19], v[230:233], v[190:193], v[16:19]
	v_mfma_f32_16x16x32_bf16 v[4:7], v[222:225], v[214:217], v[4:7]
	v_mfma_f32_16x16x32_bf16 v[0:3], v[230:233], v[214:217], v[0:3]
	v_mfma_f32_16x16x32_bf16 v[52:55], v[226:229], v[174:177], v[52:55]
	v_mfma_f32_16x16x32_bf16 v[48:51], v[234:237], v[174:177], v[48:51]
	v_mfma_f32_16x16x32_bf16 v[36:39], v[226:229], v[186:189], v[36:39]
	v_mfma_f32_16x16x32_bf16 v[32:35], v[234:237], v[186:189], v[32:35]
	v_mfma_f32_16x16x32_bf16 v[20:23], v[226:229], v[194:197], v[20:23]
	v_mfma_f32_16x16x32_bf16 v[16:19], v[234:237], v[194:197], v[16:19]
	v_mfma_f32_16x16x32_bf16 v[4:7], v[226:229], v[218:221], v[4:7]
	v_mfma_f32_16x16x32_bf16 v[0:3], v[234:237], v[218:221], v[0:3]
	s_setprio 0
	s_add_i32 s55, 0, 0x18000
	v_add_u32_e32 v140, s55, v178
	s_barrier
	ds_read_b128 v[128:131], v140
	ds_read_b128 v[132:135], v140 offset:1024
	ds_read_b128 v[136:139], v140 offset:2048
	ds_read_b128 v[140:143], v140 offset:3072
	s_add_u32 s36, s36, 0x20000
	s_addc_u32 s37, s37, 0
	s_mov_b32 m0, s45
	v_lshl_add_u64 v[222:223], s[36:37], 0, v[144:145]
	ds_read_b128 v[154:157], v181 offset:32768
	ds_read_b128 v[174:177], v181 offset:33792
	ds_read_b128 v[182:185], v181 offset:34816
	ds_read_b128 v[186:189], v181 offset:35840
	ds_read_b128 v[190:193], v181 offset:36864
	ds_read_b128 v[194:197], v181 offset:37888
	ds_read_b128 v[214:217], v181 offset:38912
	ds_read_b128 v[218:221], v181 offset:39936
	global_load_lds_dwordx4 v[222:223], off
	v_lshl_add_u64 v[222:223], s[36:37], 0, v[146:147]
	s_mov_b32 m0, s46
	s_nop 0
	global_load_lds_dwordx4 v[222:223], off
	s_waitcnt lgkmcnt(8)
	s_barrier
	s_waitcnt lgkmcnt(0)
	s_setprio 1
	v_mfma_f32_16x16x32_bf16 v[124:127], v[128:131], v[154:157], v[124:127]
	v_mfma_f32_16x16x32_bf16 v[120:123], v[136:139], v[154:157], v[120:123]
	v_mfma_f32_16x16x32_bf16 v[108:111], v[128:131], v[182:185], v[108:111]
	v_mfma_f32_16x16x32_bf16 v[104:107], v[136:139], v[182:185], v[104:107]
	v_mfma_f32_16x16x32_bf16 v[92:95], v[128:131], v[190:193], v[92:95]
	v_mfma_f32_16x16x32_bf16 v[88:91], v[136:139], v[190:193], v[88:91]
	v_mfma_f32_16x16x32_bf16 v[76:79], v[128:131], v[214:217], v[76:79]
	v_mfma_f32_16x16x32_bf16 v[72:75], v[136:139], v[214:217], v[72:75]
	v_mfma_f32_16x16x32_bf16 v[124:127], v[132:135], v[174:177], v[124:127]
	v_mfma_f32_16x16x32_bf16 v[120:123], v[140:143], v[174:177], v[120:123]
	v_mfma_f32_16x16x32_bf16 v[108:111], v[132:135], v[186:189], v[108:111]
	v_mfma_f32_16x16x32_bf16 v[104:107], v[140:143], v[186:189], v[104:107]
	v_mfma_f32_16x16x32_bf16 v[92:95], v[132:135], v[194:197], v[92:95]
	v_mfma_f32_16x16x32_bf16 v[88:91], v[140:143], v[194:197], v[88:91]
	v_mfma_f32_16x16x32_bf16 v[76:79], v[132:135], v[218:221], v[76:79]
	v_mfma_f32_16x16x32_bf16 v[72:75], v[140:143], v[218:221], v[72:75]
	s_setprio 0
	s_barrier
	s_add_i32 s36, 0, 0x1c000
	s_add_i32 s37, s55, s42
	v_add_u32_e32 v234, s36, v178
	v_lshl_add_u64 v[158:159], v[158:159], 0, s[2:3]
	s_mov_b32 m0, s37
	ds_read_b128 v[222:225], v234
	ds_read_b128 v[226:229], v234 offset:1024
	ds_read_b128 v[230:233], v234 offset:2048
	ds_read_b128 v[234:237], v234 offset:3072
	global_load_lds_dwordx4 v[158:159], off
	v_lshl_add_u64 v[158:159], v[238:239], 0, s[2:3]
	s_add_i32 m0, s37, 0x2000
	s_nop 0
	global_load_lds_dwordx4 v[158:159], off
	s_barrier
	s_waitcnt lgkmcnt(0)
	s_setprio 1
	v_mfma_f32_16x16x32_bf16 v[116:119], v[222:225], v[154:157], v[116:119]
	v_mfma_f32_16x16x32_bf16 v[112:115], v[230:233], v[154:157], v[112:115]
	v_mfma_f32_16x16x32_bf16 v[100:103], v[222:225], v[182:185], v[100:103]
	v_mfma_f32_16x16x32_bf16 v[96:99], v[230:233], v[182:185], v[96:99]
	v_mfma_f32_16x16x32_bf16 v[84:87], v[222:225], v[190:193], v[84:87]
	v_mfma_f32_16x16x32_bf16 v[80:83], v[230:233], v[190:193], v[80:83]
	v_mfma_f32_16x16x32_bf16 v[68:71], v[222:225], v[214:217], v[68:71]
	v_mfma_f32_16x16x32_bf16 v[64:67], v[230:233], v[214:217], v[64:67]
	v_mfma_f32_16x16x32_bf16 v[116:119], v[226:229], v[174:177], v[116:119]
	v_mfma_f32_16x16x32_bf16 v[112:115], v[234:237], v[174:177], v[112:115]
	v_mfma_f32_16x16x32_bf16 v[100:103], v[226:229], v[186:189], v[100:103]
	v_mfma_f32_16x16x32_bf16 v[96:99], v[234:237], v[186:189], v[96:99]
	v_mfma_f32_16x16x32_bf16 v[84:87], v[226:229], v[194:197], v[84:87]
	v_mfma_f32_16x16x32_bf16 v[80:83], v[234:237], v[194:197], v[80:83]
	v_mfma_f32_16x16x32_bf16 v[68:71], v[226:229], v[218:221], v[68:71]
	v_mfma_f32_16x16x32_bf16 v[64:67], v[234:237], v[218:221], v[64:67]
	s_setprio 0
	s_mov_b32 m0, s47
	v_lshl_add_u64 v[158:159], v[240:241], 0, s[2:3]
	s_barrier
	ds_read_b128 v[154:157], v181 offset:49152
	ds_read_b128 v[174:177], v181 offset:50176
	ds_read_b128 v[182:185], v181 offset:51200
	ds_read_b128 v[186:189], v181 offset:52224
	ds_read_b128 v[190:193], v181 offset:53248
	ds_read_b128 v[194:197], v181 offset:54272
	ds_read_b128 v[214:217], v181 offset:55296
	ds_read_b128 v[218:221], v181 offset:56320
	global_load_lds_dwordx4 v[158:159], off
	v_lshl_add_u64 v[158:159], v[242:243], 0, s[2:3]
	s_mov_b32 m0, s48
	s_nop 0
	global_load_lds_dwordx4 v[158:159], off
	s_barrier
; #define PG8_STAGE(bufoff, gbase, voff) do { _Pragma("unroll") for (int _i = 0; _i < 2; ++_i) \
;         __builtin_amdgcn_global_load_lds((const unsigned*)((const char*)(gbase) + (voff)[_i]), (LAS unsigned*)(lds + (bufoff) + ldsw + _i * 8192), 16, 0, 0); } while (0)
; #define PG8_MMA(ai, bj, At, Bt) do { __builtin_amdgcn_s_setprio(1); _Pragma("unroll") for (int m = 0; m < 4; ++m) _Pragma("unroll") for (int n = 0; n < 2; ++n) _Pragma("unroll") for (int k = 0; k < 2; ++k) \
;         acc[ai][bj][m][n] = __builtin_amdgcn_mfma_f32_16x16x32_bf16(Bt[n][k], At[m][k], acc[ai][bj][m][n], 0, 0, 0); __builtin_amdgcn_s_setprio(0); } while (0)
; #define PG8_WAIT_V(n) asm volatile("s_waitcnt vmcnt(" #n ")" ::: "memory")
; #define PG8_WAIT_L(n) asm volatile("s_waitcnt lgkmcnt(" #n ")" ::: "memory")
; #define PG8_BAR __builtin_amdgcn_s_barrier()
; #define PG8_SCHED __builtin_amdgcn_sched_barrier(0)
; template <class Epi>
; DEV void gemm_phase(LAS unsigned char* lds, const Gemm g, const StaticOrder& S, const Epi& E) {
;     ...
;             PG8_BAR; PG8_WAIT_L(0); PG8_MMA(1, 0, At, B0); PG8_BAR; PG8_SCHED;
;             PG8_STAGE(PG8_SB(1, 1), b3 + hstep, voffB);
;             PG8_WAIT_V(6); PG8_BAR; PG8_MMA(1, 1, At, B1); PG8_BAR;
	s_waitcnt lgkmcnt(0)
	s_setprio 1
	v_mfma_f32_16x16x32_bf16 v[60:63], v[128:131], v[154:157], v[60:63]
	v_mfma_f32_16x16x32_bf16 v[56:59], v[136:139], v[154:157], v[56:59]
	v_mfma_f32_16x16x32_bf16 v[44:47], v[128:131], v[182:185], v[44:47]
	v_mfma_f32_16x16x32_bf16 v[40:43], v[136:139], v[182:185], v[40:43]
	v_mfma_f32_16x16x32_bf16 v[28:31], v[128:131], v[190:193], v[28:31]
	v_mfma_f32_16x16x32_bf16 v[24:27], v[136:139], v[190:193], v[24:27]
	v_mfma_f32_16x16x32_bf16 v[12:15], v[128:131], v[214:217], v[12:15]
	v_mfma_f32_16x16x32_bf16 v[8:11], v[136:139], v[214:217], v[8:11]
	v_mfma_f32_16x16x32_bf16 v[60:63], v[132:135], v[174:177], v[60:63]
	v_mfma_f32_16x16x32_bf16 v[56:59], v[140:143], v[174:177], v[56:59]
	v_mfma_f32_16x16x32_bf16 v[44:47], v[132:135], v[186:189], v[44:47]
	v_mfma_f32_16x16x32_bf16 v[40:43], v[140:143], v[186:189], v[40:43]
	v_mfma_f32_16x16x32_bf16 v[28:31], v[132:135], v[194:197], v[28:31]
	v_mfma_f32_16x16x32_bf16 v[24:27], v[140:143], v[194:197], v[24:27]
	v_mfma_f32_16x16x32_bf16 v[12:15], v[132:135], v[218:221], v[12:15]
	v_mfma_f32_16x16x32_bf16 v[8:11], v[140:143], v[218:221], v[8:11]
	s_setprio 0
	s_barrier
	s_add_u32 s34, s34, 0x20080
	s_addc_u32 s35, s35, 0
	s_add_i32 s36, s36, s42
	v_lshl_add_u64 v[128:129], s[34:35], 0, v[160:161]
	s_mov_b32 m0, s36
	s_nop 0
	global_load_lds_dwordx4 v[128:129], off
	v_lshl_add_u64 v[128:129], s[34:35], 0, v[148:149]
	s_add_i32 m0, s36, 0x2000
	s_nop 0
	global_load_lds_dwordx4 v[128:129], off
	s_waitcnt vmcnt(6)
	s_barrier
	s_setprio 1
	v_mfma_f32_16x16x32_bf16 v[52:55], v[222:225], v[154:157], v[52:55]
	v_mfma_f32_16x16x32_bf16 v[48:51], v[230:233], v[154:157], v[48:51]
	v_mfma_f32_16x16x32_bf16 v[36:39], v[222:225], v[182:185], v[36:39]
	v_mfma_f32_16x16x32_bf16 v[32:35], v[230:233], v[182:185], v[32:35]
	v_mfma_f32_16x16x32_bf16 v[20:23], v[222:225], v[190:193], v[20:23]
	v_mfma_f32_16x16x32_bf16 v[16:19], v[230:233], v[190:193], v[16:19]
	v_mfma_f32_16x16x32_bf16 v[4:7], v[222:225], v[214:217], v[4:7]
	v_mfma_f32_16x16x32_bf16 v[0:3], v[230:233], v[214:217], v[0:3]
	v_mfma_f32_16x16x32_bf16 v[52:55], v[226:229], v[174:177], v[52:55]
	v_mfma_f32_16x16x32_bf16 v[48:51], v[234:237], v[174:177], v[48:51]
	v_mfma_f32_16x16x32_bf16 v[36:39], v[226:229], v[186:189], v[36:39]
	v_mfma_f32_16x16x32_bf16 v[32:35], v[234:237], v[186:189], v[32:35]
	v_mfma_f32_16x16x32_bf16 v[20:23], v[226:229], v[194:197], v[20:23]
	v_mfma_f32_16x16x32_bf16 v[16:19], v[234:237], v[194:197], v[16:19]
	v_mfma_f32_16x16x32_bf16 v[4:7], v[226:229], v[218:221], v[4:7]
	v_mfma_f32_16x16x32_bf16 v[0:3], v[234:237], v[218:221], v[0:3]
	s_setprio 0
	s_add_i32 s54, s54, 2
	s_add_u32 s30, s30, 0x100
	s_addc_u32 s31, s31, 0
	s_add_u32 s52, s52, 0x100
	s_addc_u32 s53, s53, 0
	s_cmp_gt_u32 s54, 5
	s_barrier
	s_cbranch_scc0 .LBB0_260
; DEV bf16x8 pack8(f32x4 a, f32x4 b) { u32x4 w; w.x = cvt_pk_bf16(a[0], a[1]); w.y = cvt_pk_bf16(a[2], a[3]); w.z = cvt_pk_bf16(b[0], b[1]); w.w = cvt_pk_bf16(b[2], b[3]); return __builtin_bit_cast(bf16x8, w); }
;     DEV void operator()(AccRef acc, const pg8::Unit& u, int wr, int wc, int fr, int fq) const {
;         const int row0 = u.pm * 256 + wr * 64 + fr, col0 = u.pn * 256 + wc * 32 + 8 * fq;
; #pragma unroll
;         for (int am = 0; am < 4; ++am) { const int ai = am >> 1, m0 = (am & 1) * 2;
;             f32x4 bv[4][2][2];
; #pragma unroll
;             for (int m = m0; m < m0 + 2; ++m)
; #pragma unroll
;                 for (int bj = 0; bj < 2; ++bj)
; #pragma unroll
;                     for (int n = 0; n < 2; ++n) bv[m][bj][n] = *(const f32x4*)(base + (size_t)(row0 + ai * 128 + m * 16) * 2048 + col0 + bj * 128 + n * 4);
; #pragma unroll
;             for (int m = m0; m < m0 + 2; ++m) { const size_t off = (size_t)(row0 + ai * 128 + m * 16) * 2048 + col0; float sq = 0.f;
; #pragma unroll
;                 for (int bj = 0; bj < 2; ++bj) { const f32x4 o0 = bv[m][bj][0] + scale * acc[ai][bj][m][0], o1 = bv[m][bj][1] + scale * acc[ai][bj][m][1];
;                     *(f32x4*)(out + off + bj * 128) = o0; *(f32x4*)(out + off + bj * 128 + 4) = o1;
;                     if (xb) { *(u32x4*)(xb + off + bj * 128) = __builtin_bit_cast(u32x4, pack8(o0, o1));
;                         sq += (o0[0] * o0[0] + o0[1] * o0[1] + o0[2] * o0[2] + o0[3] * o0[3]) + (o1[0] * o1[0] + o1[1] * o1[1] + o1[2] * o1[2] + o1[3] * o1[3]); } }
;                 if (ssout) { sq += __shfl_xor(sq, 16); sq += __shfl_xor(sq, 32);
;                     if (fq == 0) { if (red) red[(ai * 128 + wr * 64 + m * 16 + fr) * 4 + wc] = sq; else atomicAdd(ssout + (size_t)(row0 + ai * 128 + m * 16) * 8 + u.pn, sq); } } }
	v_lshl_add_u32 v156, s28, 8, v167
	v_lshl_or_b32 v154, s18, 8, v179
	v_readlane_b32 s28, v254, 16
	v_ashrrev_i32_e32 v155, 31, v154
	v_readlane_b32 s29, v254, 17
	v_ashrrev_i32_e32 v157, 31, v156
	v_lshlrev_b64 v[128:129], 13, v[156:157]
	v_lshl_add_u64 v[158:159], v[154:155], 2, s[28:29]
	v_lshl_add_u64 v[214:215], v[158:159], 0, v[128:129]
	global_load_dwordx4 v[182:185], v[214:215], off offset:16
	global_load_dwordx4 v[186:189], v[214:215], off
	global_load_dwordx4 v[190:193], v[214:215], off offset:528
	global_load_dwordx4 v[194:197], v[214:215], off offset:512
	v_or_b32_e32 v174, 16, v156
	v_ashrrev_i32_e32 v175, 31, v174
	v_lshlrev_b64 v[128:129], 13, v[174:175]
	v_lshl_add_u64 v[176:177], v[158:159], 0, v[128:129]
	global_load_dwordx4 v[136:139], v[176:177], off offset:16
	global_load_dwordx4 v[140:143], v[176:177], off
	global_load_dwordx4 v[128:131], v[176:177], off offset:528
	global_load_dwordx4 v[132:135], v[176:177], off offset:512
	v_add_u32_e32 v255, 32, v156
	v_lshlrev_b32_e32 v255, 13, v255
	v_lshl_add_u32 v255, v154, 2, v255
	global_load_dwordx4 v[218:221], v255, s[28:29]
	global_load_dwordx4 v[222:225], v255, s[28:29] offset:16
	global_load_dwordx4 v[226:229], v255, s[28:29] offset:512
	global_load_dwordx4 v[230:233], v255, s[28:29] offset:528
	v_add_u32_e32 v255, 48, v156
	v_lshlrev_b32_e32 v255, 13, v255
	v_lshl_add_u32 v255, v154, 2, v255
	global_load_dwordx4 v[234:237], v255, s[28:29] offset:16
	global_load_dwordx4 v[238:241], v255, s[28:29]
	global_load_dwordx4 v[242:245], v255, s[28:29] offset:528
	global_load_dwordx4 v[246:249], v255, s[28:29] offset:512
	v_lshlrev_b64 v[216:217], 11, v[156:157]
	v_readlane_b32 s28, v250, 9
	v_lshl_add_u64 v[216:217], v[216:217], 0, v[154:155]
	v_readlane_b32 s29, v250, 10
	v_cmp_lt_i32_e32 vcc, v208, v206
	s_ashr_i32 s19, s18, 31
	s_waitcnt vmcnt(0)
	v_pk_add_f32 v[120:121], v[120:121], v[182:183]
	v_pk_add_f32 v[126:127], v[126:127], v[188:189]
	v_pk_add_f32 v[124:125], v[124:125], v[186:187]
	v_pk_add_f32 v[122:123], v[122:123], v[184:185]
	global_store_dwordx4 v[214:215], v[124:127], off
	global_store_dwordx4 v[214:215], v[120:123], off offset:16
	v_cvt_pk_bf16_f32 v184, v120, v121
	v_cvt_pk_bf16_f32 v182, v124, v125
	v_mul_f32_e32 v121, v121, v121
	v_cvt_pk_bf16_f32 v183, v126, v127
	v_cvt_pk_bf16_f32 v185, v122, v123
	v_lshl_add_u64 v[186:187], v[216:217], 1, s[28:29]
	v_fmac_f32_e32 v121, v120, v120
	v_pk_add_f32 v[118:119], v[118:119], v[196:197]
	v_pk_add_f32 v[116:117], v[116:117], v[194:195]
	v_pk_add_f32 v[112:113], v[112:113], v[190:191]
	global_store_dwordx4 v[186:187], v[182:185], off
	v_mul_f32_e32 v125, v125, v125
	v_fmac_f32_e32 v121, v122, v122
	v_pk_add_f32 v[114:115], v[114:115], v[192:193]
	global_store_dwordx4 v[214:215], v[116:119], off offset:512
	global_store_dwordx4 v[214:215], v[112:115], off offset:528
	v_cvt_pk_bf16_f32 v120, v116, v117
	v_cvt_pk_bf16_f32 v122, v112, v113
	v_mul_f32_e32 v117, v117, v117
	v_mul_f32_e32 v113, v113, v113
	v_fmac_f32_e32 v125, v124, v124
	v_fmac_f32_e32 v117, v116, v116
	v_fmac_f32_e32 v113, v112, v112
	v_fmac_f32_e32 v125, v126, v126
	v_fmac_f32_e32 v117, v118, v118
	v_fmac_f32_e32 v113, v114, v114
	v_fmac_f32_e32 v125, v127, v127
	v_fmac_f32_e32 v121, v123, v123
	v_fmac_f32_e32 v117, v119, v119
	v_fmac_f32_e32 v113, v115, v115
	v_add_f32_e32 v124, v125, v121
	v_add_f32_e32 v112, v117, v113
	v_cndmask_b32_e32 v113, v204, v208, vcc
	v_cvt_pk_bf16_f32 v121, v118, v119
	v_add_f32_e32 v112, v124, v112
	v_lshlrev_b32_e32 v118, 2, v113
	ds_bpermute_b32 v113, v118, v112
	v_cmp_lt_i32_e32 vcc, v207, v206
	v_cvt_pk_bf16_f32 v123, v114, v115
	global_store_dwordx4 v[186:187], v[120:123], off offset:256
	s_waitcnt lgkmcnt(0)
	v_add_f32_e32 v112, v112, v113
	v_cndmask_b32_e32 v113, v204, v207, vcc
	v_lshlrev_b32_e32 v119, 2, v113
	ds_bpermute_b32 v113, v119, v112
	s_and_saveexec_b64 s[28:29], s[6:7]
	s_cbranch_execz .LBB0_266
	s_waitcnt lgkmcnt(0)
	v_add_f32_e32 v112, v112, v113
	s_mov_b64 s[30:31], -1
	s_and_b64 vcc, exec, s[16:17]
	s_cbranch_vccz .LBB0_264
	v_lshlrev_b64 v[114:115], 5, v[156:157]
	v_lshl_add_u64 v[114:115], s[12:13], 0, v[114:115]
	v_lshl_add_u64 v[114:115], s[18:19], 2, v[114:115]
	global_atomic_add_f32 v[114:115], v112, off
	s_mov_b64 s[30:31], 0

; DEV bf16x8 pack8(f32x4 a, f32x4 b) { u32x4 w; w.x = cvt_pk_bf16(a[0], a[1]); w.y = cvt_pk_bf16(a[2], a[3]); w.z = cvt_pk_bf16(b[0], b[1]); w.w = cvt_pk_bf16(b[2], b[3]); return __builtin_bit_cast(bf16x8, w); }
;     DEV void operator()(AccRef acc, const pg8::Unit& u, int wr, int wc, int fr, int fq) const {
;     ...
;         for (int am = 0; am < 4; ++am) { const int ai = am >> 1, m0 = (am & 1) * 2;
;             f32x4 bv[4][2][2];
; #pragma unroll
;             for (int m = m0; m < m0 + 2; ++m)
; #pragma unroll
;                 for (int bj = 0; bj < 2; ++bj)
; #pragma unroll
;                     for (int n = 0; n < 2; ++n) bv[m][bj][n] = *(const f32x4*)(base + (size_t)(row0 + ai * 128 + m * 16) * 2048 + col0 + bj * 128 + n * 4);
; #pragma unroll
;             for (int m = m0; m < m0 + 2; ++m) { const size_t off = (size_t)(row0 + ai * 128 + m * 16) * 2048 + col0; float sq = 0.f;
; #pragma unroll
;                 for (int bj = 0; bj < 2; ++bj) { const f32x4 o0 = bv[m][bj][0] + scale * acc[ai][bj][m][0], o1 = bv[m][bj][1] + scale * acc[ai][bj][m][1];
;                     *(f32x4*)(out + off + bj * 128) = o0; *(f32x4*)(out + off + bj * 128 + 4) = o1;
;                     if (xb) { *(u32x4*)(xb + off + bj * 128) = __builtin_bit_cast(u32x4, pack8(o0, o1));
;                         sq += (o0[0] * o0[0] + o0[1] * o0[1] + o0[2] * o0[2] + o0[3] * o0[3]) + (o1[0] * o1[0] + o1[1] * o1[1] + o1[2] * o1[2] + o1[3] * o1[3]); } }
;                 if (ssout) { sq += __shfl_xor(sq, 16); sq += __shfl_xor(sq, 32);
;                     if (fq == 0) { if (red) red[(ai * 128 + wr * 64 + m * 16 + fr) * 4 + wc] = sq; else atomicAdd(ssout + (size_t)(row0 + ai * 128 + m * 16) * 8 + u.pn, sq); } } }
.LBB0_271:
	s_or_b64 exec, exec, s[28:29]
	v_or_b32_e32 v116, 32, v156
	v_ashrrev_i32_e32 v117, 31, v116
	s_waitcnt lgkmcnt(0)
	v_lshlrev_b64 v[96:97], 13, v[116:117]
	v_lshl_add_u64 v[136:137], v[158:159], 0, v[96:97]
	v_mov_b32_e32 v120, v218
	v_mov_b32_e32 v121, v219
	v_mov_b32_e32 v122, v220
	v_mov_b32_e32 v123, v221
	v_mov_b32_e32 v124, v222
	v_mov_b32_e32 v125, v223
	v_mov_b32_e32 v126, v224
	v_mov_b32_e32 v127, v225
	v_mov_b32_e32 v128, v226
	v_mov_b32_e32 v129, v227
	v_mov_b32_e32 v130, v228
	v_mov_b32_e32 v131, v229
	v_mov_b32_e32 v132, v230
	v_mov_b32_e32 v133, v231
	v_mov_b32_e32 v134, v232
	v_mov_b32_e32 v135, v233
	v_or_b32_e32 v112, 48, v156
	v_ashrrev_i32_e32 v113, 31, v112
	v_lshlrev_b64 v[96:97], 13, v[112:113]
	v_lshl_add_u64 v[114:115], v[158:159], 0, v[96:97]
	v_mov_b32_e32 v104, v234
	v_mov_b32_e32 v105, v235
	v_mov_b32_e32 v106, v236
	v_mov_b32_e32 v107, v237
	v_mov_b32_e32 v108, v238
	v_mov_b32_e32 v109, v239
	v_mov_b32_e32 v110, v240
	v_mov_b32_e32 v111, v241
	v_mov_b32_e32 v96, v242
	v_mov_b32_e32 v97, v243
	v_mov_b32_e32 v98, v244
	v_mov_b32_e32 v99, v245
	v_mov_b32_e32 v100, v246
	v_mov_b32_e32 v101, v247
	v_mov_b32_e32 v102, v248
	v_mov_b32_e32 v103, v249
	v_readlane_b32 s28, v254, 16
	v_readlane_b32 s29, v254, 17
	v_add_u32_e32 v255, 128, v156
	v_lshlrev_b32_e32 v255, 13, v255
	v_lshl_add_u32 v255, v154, 2, v255
	s_nop 1
	global_load_dwordx4 v[218:221], v255, s[28:29]
	global_load_dwordx4 v[222:225], v255, s[28:29] offset:16
	global_load_dwordx4 v[226:229], v255, s[28:29] offset:512
	global_load_dwordx4 v[230:233], v255, s[28:29] offset:528
	v_add_u32_e32 v255, 144, v156
	v_lshlrev_b32_e32 v255, 13, v255
	v_lshl_add_u32 v255, v154, 2, v255
	global_load_dwordx4 v[234:237], v255, s[28:29] offset:16
	global_load_dwordx4 v[238:241], v255, s[28:29]
	global_load_dwordx4 v[242:245], v255, s[28:29] offset:528
	global_load_dwordx4 v[246:249], v255, s[28:29] offset:512
	v_lshlrev_b64 v[138:139], 11, v[116:117]
	v_readlane_b32 s28, v250, 9
	v_lshl_add_u64 v[138:139], v[138:139], 0, v[154:155]
	v_readlane_b32 s29, v250, 10
	v_pk_add_f32 v[94:95], v[94:95], v[122:123]
	v_pk_add_f32 v[92:93], v[92:93], v[120:121]
	v_pk_add_f32 v[88:89], v[88:89], v[124:125]
	v_pk_add_f32 v[84:85], v[84:85], v[128:129]
	v_pk_add_f32 v[120:121], v[80:81], v[132:133]
	v_pk_add_f32 v[90:91], v[90:91], v[126:127]
	v_pk_add_f32 v[122:123], v[82:83], v[134:135]
	global_store_dwordx4 v[136:137], v[92:95], off
	global_store_dwordx4 v[136:137], v[88:91], off offset:16
	v_cvt_pk_bf16_f32 v80, v92, v93
	v_cvt_pk_bf16_f32 v82, v88, v89
	v_mul_f32_e32 v93, v93, v93
	v_mul_f32_e32 v89, v89, v89
	v_mul_f32_e32 v124, v85, v85
	v_mul_f32_e32 v125, v121, v121
	v_pk_add_f32 v[86:87], v[86:87], v[130:131]
	v_fmac_f32_e32 v93, v92, v92
	v_fmac_f32_e32 v89, v88, v88
	v_fmac_f32_e32 v124, v84, v84
	v_fmac_f32_e32 v125, v120, v120
	v_fmac_f32_e32 v93, v94, v94
	v_fmac_f32_e32 v89, v90, v90
	v_fmac_f32_e32 v124, v86, v86
	v_fmac_f32_e32 v125, v122, v122
	v_fmac_f32_e32 v93, v95, v95
	v_fmac_f32_e32 v89, v91, v91
	v_fmac_f32_e32 v124, v87, v87
	v_fmac_f32_e32 v125, v123, v123
	v_add_f32_e32 v88, v93, v89
	v_add_f32_e32 v89, v124, v125
	v_add_f32_e32 v88, v88, v89
	ds_bpermute_b32 v89, v118, v88
	v_lshl_add_u64 v[138:139], v[138:139], 1, s[28:29]
	v_cvt_pk_bf16_f32 v81, v94, v95
	v_cvt_pk_bf16_f32 v83, v90, v91
	global_store_dwordx4 v[138:139], v[80:83], off
	global_store_dwordx4 v[136:137], v[84:87], off offset:512
	global_store_dwordx4 v[136:137], v[120:123], off offset:528
	s_waitcnt lgkmcnt(0)
	v_add_f32_e32 v80, v88, v89
	ds_bpermute_b32 v81, v119, v80
	v_cvt_pk_bf16_f32 v82, v84, v85
	v_cvt_pk_bf16_f32 v83, v86, v87
	v_cvt_pk_bf16_f32 v84, v120, v121
	v_cvt_pk_bf16_f32 v85, v122, v123
	global_store_dwordx4 v[138:139], v[82:85], off offset:256
	s_and_saveexec_b64 s[28:29], s[6:7]
	s_cbranch_execz .LBB0_276
	s_waitcnt lgkmcnt(0)
	v_add_f32_e32 v80, v80, v81
	s_mov_b64 s[30:31], -1
	s_and_b64 vcc, exec, s[16:17]
	s_cbranch_vccz .LBB0_274
	v_lshlrev_b64 v[82:83], 5, v[116:117]
	v_lshl_add_u64 v[82:83], s[12:13], 0, v[82:83]
	v_lshl_add_u64 v[82:83], s[18:19], 2, v[82:83]
	global_atomic_add_f32 v[82:83], v80, off
	s_mov_b64 s[30:31], 0

; DEV bf16x8 pack8(f32x4 a, f32x4 b) { u32x4 w; w.x = cvt_pk_bf16(a[0], a[1]); w.y = cvt_pk_bf16(a[2], a[3]); w.z = cvt_pk_bf16(b[0], b[1]); w.w = cvt_pk_bf16(b[2], b[3]); return __builtin_bit_cast(bf16x8, w); }
;     DEV void operator()(AccRef acc, const pg8::Unit& u, int wr, int wc, int fr, int fq) const {
;     ...
;             for (int m = m0; m < m0 + 2; ++m) { const size_t off = (size_t)(row0 + ai * 128 + m * 16) * 2048 + col0; float sq = 0.f;
; #pragma unroll
;                 for (int bj = 0; bj < 2; ++bj) { const f32x4 o0 = bv[m][bj][0] + scale * acc[ai][bj][m][0], o1 = bv[m][bj][1] + scale * acc[ai][bj][m][1];
;                     *(f32x4*)(out + off + bj * 128) = o0; *(f32x4*)(out + off + bj * 128 + 4) = o1;
;                     if (xb) { *(u32x4*)(xb + off + bj * 128) = __builtin_bit_cast(u32x4, pack8(o0, o1));
;                         sq += (o0[0] * o0[0] + o0[1] * o0[1] + o0[2] * o0[2] + o0[3] * o0[3]) + (o1[0] * o1[0] + o1[1] * o1[1] + o1[2] * o1[2] + o1[3] * o1[3]); } }
;                 if (ssout) { sq += __shfl_xor(sq, 16); sq += __shfl_xor(sq, 32);
;                     if (fq == 0) { if (red) red[(ai * 128 + wr * 64 + m * 16 + fr) * 4 + wc] = sq; else atomicAdd(ssout + (size_t)(row0 + ai * 128 + m * 16) * 8 + u.pn, sq); } } }
.LBB0_276:
	s_or_b64 exec, exec, s[28:29]
	s_waitcnt lgkmcnt(0)
	v_lshlrev_b64 v[80:81], 11, v[112:113]
	v_pk_add_f32 v[78:79], v[78:79], v[110:111]
	v_pk_add_f32 v[76:77], v[76:77], v[108:109]
	v_pk_add_f32 v[72:73], v[72:73], v[104:105]
	v_lshl_add_u64 v[84:85], v[80:81], 0, v[154:155]
	v_pk_add_f32 v[74:75], v[74:75], v[106:107]
	global_store_dwordx4 v[114:115], v[76:79], off
	global_store_dwordx4 v[114:115], v[72:75], off offset:16
	v_cvt_pk_bf16_f32 v80, v76, v77
	v_cvt_pk_bf16_f32 v82, v72, v73
	v_mul_f32_e32 v77, v77, v77
	v_mul_f32_e32 v73, v73, v73
	v_fmac_f32_e32 v77, v76, v76
	v_fmac_f32_e32 v73, v72, v72
	v_fmac_f32_e32 v77, v78, v78
	v_fmac_f32_e32 v73, v74, v74
	v_fmac_f32_e32 v77, v79, v79
	v_fmac_f32_e32 v73, v75, v75
	v_add_f32_e32 v76, v77, v73
	v_pk_add_f32 v[68:69], v[68:69], v[100:101]
	v_pk_add_f32 v[72:73], v[64:65], v[96:97]
	v_mul_f32_e32 v64, v69, v69
	v_mul_f32_e32 v65, v73, v73
	v_cvt_pk_bf16_f32 v83, v74, v75
	v_pk_add_f32 v[70:71], v[70:71], v[102:103]
	v_pk_add_f32 v[74:75], v[66:67], v[98:99]
	v_fmac_f32_e32 v64, v68, v68
	v_fmac_f32_e32 v65, v72, v72
	v_fmac_f32_e32 v64, v70, v70
	v_fmac_f32_e32 v65, v74, v74
	v_fmac_f32_e32 v64, v71, v71
	v_fmac_f32_e32 v65, v75, v75
	v_add_f32_e32 v64, v64, v65
	v_add_f32_e32 v64, v76, v64
	ds_bpermute_b32 v65, v118, v64
	v_readlane_b32 s28, v250, 9
	v_readlane_b32 s29, v250, 10
	v_cvt_pk_bf16_f32 v81, v78, v79
	v_cvt_pk_bf16_f32 v66, v68, v69
	s_waitcnt lgkmcnt(0)
	v_add_f32_e32 v64, v64, v65
	ds_bpermute_b32 v65, v119, v64
	v_lshl_add_u64 v[84:85], v[84:85], 1, s[28:29]
	global_store_dwordx4 v[84:85], v[80:83], off
	global_store_dwordx4 v[114:115], v[68:71], off offset:512
	global_store_dwordx4 v[114:115], v[72:75], off offset:528
	v_cvt_pk_bf16_f32 v67, v70, v71
	v_cvt_pk_bf16_f32 v68, v72, v73
	v_cvt_pk_bf16_f32 v69, v74, v75
	global_store_dwordx4 v[84:85], v[66:69], off offset:256
	s_and_saveexec_b64 s[28:29], s[6:7]
	s_cbranch_execz .LBB0_281
	s_waitcnt lgkmcnt(0)
	v_add_f32_e32 v64, v64, v65
	s_mov_b64 s[30:31], -1
	s_and_b64 vcc, exec, s[16:17]
	s_cbranch_vccz .LBB0_279
	v_lshlrev_b64 v[66:67], 5, v[112:113]
	v_lshl_add_u64 v[66:67], s[12:13], 0, v[66:67]
	v_lshl_add_u64 v[66:67], s[18:19], 2, v[66:67]
	global_atomic_add_f32 v[66:67], v64, off
	s_mov_b64 s[30:31], 0

; DEV bf16x8 pack8(f32x4 a, f32x4 b) { u32x4 w; w.x = cvt_pk_bf16(a[0], a[1]); w.y = cvt_pk_bf16(a[2], a[3]); w.z = cvt_pk_bf16(b[0], b[1]); w.w = cvt_pk_bf16(b[2], b[3]); return __builtin_bit_cast(bf16x8, w); }
;     DEV void operator()(AccRef acc, const pg8::Unit& u, int wr, int wc, int fr, int fq) const {
;     ...
;         for (int am = 0; am < 4; ++am) { const int ai = am >> 1, m0 = (am & 1) * 2;
;             f32x4 bv[4][2][2];
; #pragma unroll
;             for (int m = m0; m < m0 + 2; ++m)
; #pragma unroll
;                 for (int bj = 0; bj < 2; ++bj)
; #pragma unroll
;                     for (int n = 0; n < 2; ++n) bv[m][bj][n] = *(const f32x4*)(base + (size_t)(row0 + ai * 128 + m * 16) * 2048 + col0 + bj * 128 + n * 4);
; #pragma unroll
;             for (int m = m0; m < m0 + 2; ++m) { const size_t off = (size_t)(row0 + ai * 128 + m * 16) * 2048 + col0; float sq = 0.f;
; #pragma unroll
;                 for (int bj = 0; bj < 2; ++bj) { const f32x4 o0 = bv[m][bj][0] + scale * acc[ai][bj][m][0], o1 = bv[m][bj][1] + scale * acc[ai][bj][m][1];
;                     *(f32x4*)(out + off + bj * 128) = o0; *(f32x4*)(out + off + bj * 128 + 4) = o1;
;                     if (xb) { *(u32x4*)(xb + off + bj * 128) = __builtin_bit_cast(u32x4, pack8(o0, o1));
;                         sq += (o0[0] * o0[0] + o0[1] * o0[1] + o0[2] * o0[2] + o0[3] * o0[3]) + (o1[0] * o1[0] + o1[1] * o1[1] + o1[2] * o1[2] + o1[3] * o1[3]); } }
;                 if (ssout) { sq += __shfl_xor(sq, 16); sq += __shfl_xor(sq, 32);
;                     if (fq == 0) { if (red) red[(ai * 128 + wr * 64 + m * 16 + fr) * 4 + wc] = sq; else atomicAdd(ssout + (size_t)(row0 + ai * 128 + m * 16) * 8 + u.pn, sq); } } }
.LBB0_281:
	s_or_b64 exec, exec, s[28:29]
	v_add_u32_e32 v84, 0x80, v156
	v_ashrrev_i32_e32 v85, 31, v84
	s_waitcnt lgkmcnt(0)
	v_lshlrev_b64 v[64:65], 13, v[84:85]
	v_lshl_add_u64 v[102:103], v[158:159], 0, v[64:65]
	s_waitcnt vmcnt(4)
	v_mov_b32_e32 v86, v218
	v_mov_b32_e32 v87, v219
	v_mov_b32_e32 v88, v220
	v_mov_b32_e32 v89, v221
	v_mov_b32_e32 v90, v222
	v_mov_b32_e32 v91, v223
	v_mov_b32_e32 v92, v224
	v_mov_b32_e32 v93, v225
	v_mov_b32_e32 v94, v226
	v_mov_b32_e32 v95, v227
	v_mov_b32_e32 v96, v228
	v_mov_b32_e32 v97, v229
	v_mov_b32_e32 v98, v230
	v_mov_b32_e32 v99, v231
	v_mov_b32_e32 v100, v232
	v_mov_b32_e32 v101, v233
	v_add_u32_e32 v80, 0x90, v156
	v_ashrrev_i32_e32 v81, 31, v80
	v_lshlrev_b64 v[64:65], 13, v[80:81]
	v_lshl_add_u64 v[82:83], v[158:159], 0, v[64:65]
	v_mov_b32_e32 v72, v234
	v_mov_b32_e32 v73, v235
	v_mov_b32_e32 v74, v236
	v_mov_b32_e32 v75, v237
	v_mov_b32_e32 v76, v238
	v_mov_b32_e32 v77, v239
	v_mov_b32_e32 v78, v240
	v_mov_b32_e32 v79, v241
	v_mov_b32_e32 v64, v242
	v_mov_b32_e32 v65, v243
	v_mov_b32_e32 v66, v244
	v_mov_b32_e32 v67, v245
	v_mov_b32_e32 v68, v246
	v_mov_b32_e32 v69, v247
	v_mov_b32_e32 v70, v248
	v_mov_b32_e32 v71, v249
	v_readlane_b32 s28, v254, 16
	v_readlane_b32 s29, v254, 17
	v_add_u32_e32 v255, 160, v156
	v_lshlrev_b32_e32 v255, 13, v255
	v_lshl_add_u32 v255, v154, 2, v255
	s_nop 1
	global_load_dwordx4 v[218:221], v255, s[28:29]
	global_load_dwordx4 v[222:225], v255, s[28:29] offset:16
	global_load_dwordx4 v[226:229], v255, s[28:29] offset:512
	global_load_dwordx4 v[230:233], v255, s[28:29] offset:528
	v_add_u32_e32 v255, 176, v156
	v_lshlrev_b32_e32 v255, 13, v255
	v_lshl_add_u32 v255, v154, 2, v255
	global_load_dwordx4 v[234:237], v255, s[28:29] offset:16
	global_load_dwordx4 v[238:241], v255, s[28:29]
	global_load_dwordx4 v[242:245], v255, s[28:29] offset:528
	global_load_dwordx4 v[246:249], v255, s[28:29] offset:512
	v_lshlrev_b64 v[104:105], 11, v[84:85]
	v_readlane_b32 s28, v250, 9
	v_lshl_add_u64 v[104:105], v[104:105], 0, v[154:155]
	v_readlane_b32 s29, v250, 10
	v_pk_add_f32 v[62:63], v[62:63], v[88:89]
	v_pk_add_f32 v[60:61], v[60:61], v[86:87]
	v_pk_add_f32 v[56:57], v[56:57], v[90:91]
	v_pk_add_f32 v[52:53], v[52:53], v[94:95]
	v_pk_add_f32 v[86:87], v[48:49], v[98:99]
	v_pk_add_f32 v[58:59], v[58:59], v[92:93]
	v_pk_add_f32 v[88:89], v[50:51], v[100:101]
	global_store_dwordx4 v[102:103], v[60:63], off
	global_store_dwordx4 v[102:103], v[56:59], off offset:16
	v_cvt_pk_bf16_f32 v48, v60, v61
	v_cvt_pk_bf16_f32 v50, v56, v57
	v_mul_f32_e32 v61, v61, v61
	v_mul_f32_e32 v57, v57, v57
	v_mul_f32_e32 v90, v53, v53
	v_mul_f32_e32 v91, v87, v87
	v_pk_add_f32 v[54:55], v[54:55], v[96:97]
	v_fmac_f32_e32 v61, v60, v60
	v_fmac_f32_e32 v57, v56, v56
	v_fmac_f32_e32 v90, v52, v52
	v_fmac_f32_e32 v91, v86, v86
	v_fmac_f32_e32 v61, v62, v62
	v_fmac_f32_e32 v57, v58, v58
	v_fmac_f32_e32 v90, v54, v54
	v_fmac_f32_e32 v91, v88, v88
	v_fmac_f32_e32 v61, v63, v63
	v_fmac_f32_e32 v57, v59, v59
	v_fmac_f32_e32 v90, v55, v55
	v_fmac_f32_e32 v91, v89, v89
	v_add_f32_e32 v56, v61, v57
	v_add_f32_e32 v57, v90, v91
	v_add_f32_e32 v56, v56, v57
	ds_bpermute_b32 v57, v118, v56
	v_lshl_add_u64 v[104:105], v[104:105], 1, s[28:29]
	v_cvt_pk_bf16_f32 v49, v62, v63
	v_cvt_pk_bf16_f32 v51, v58, v59
	global_store_dwordx4 v[104:105], v[48:51], off
	global_store_dwordx4 v[102:103], v[52:55], off offset:512
	global_store_dwordx4 v[102:103], v[86:89], off offset:528
	s_waitcnt lgkmcnt(0)
	v_add_f32_e32 v48, v56, v57
	ds_bpermute_b32 v49, v119, v48
	v_cvt_pk_bf16_f32 v50, v52, v53
	v_cvt_pk_bf16_f32 v51, v54, v55
	v_cvt_pk_bf16_f32 v52, v86, v87
	v_cvt_pk_bf16_f32 v53, v88, v89
	global_store_dwordx4 v[104:105], v[50:53], off offset:256
	s_and_saveexec_b64 s[28:29], s[6:7]
	s_cbranch_execz .LBB0_286
	s_waitcnt lgkmcnt(0)
	v_add_f32_e32 v48, v48, v49
	s_mov_b64 s[30:31], -1
	s_and_b64 vcc, exec, s[16:17]
	s_cbranch_vccz .LBB0_284
	v_lshlrev_b64 v[50:51], 5, v[84:85]
	v_lshl_add_u64 v[50:51], s[12:13], 0, v[50:51]
	v_lshl_add_u64 v[50:51], s[18:19], 2, v[50:51]
	global_atomic_add_f32 v[50:51], v48, off
	s_mov_b64 s[30:31], 0

; DEV bf16x8 pack8(f32x4 a, f32x4 b) { u32x4 w; w.x = cvt_pk_bf16(a[0], a[1]); w.y = cvt_pk_bf16(a[2], a[3]); w.z = cvt_pk_bf16(b[0], b[1]); w.w = cvt_pk_bf16(b[2], b[3]); return __builtin_bit_cast(bf16x8, w); }
;     DEV void operator()(AccRef acc, const pg8::Unit& u, int wr, int wc, int fr, int fq) const {
;     ...
;             for (int m = m0; m < m0 + 2; ++m) { const size_t off = (size_t)(row0 + ai * 128 + m * 16) * 2048 + col0; float sq = 0.f;
; #pragma unroll
;                 for (int bj = 0; bj < 2; ++bj) { const f32x4 o0 = bv[m][bj][0] + scale * acc[ai][bj][m][0], o1 = bv[m][bj][1] + scale * acc[ai][bj][m][1];
;                     *(f32x4*)(out + off + bj * 128) = o0; *(f32x4*)(out + off + bj * 128 + 4) = o1;
;                     if (xb) { *(u32x4*)(xb + off + bj * 128) = __builtin_bit_cast(u32x4, pack8(o0, o1));
;                         sq += (o0[0] * o0[0] + o0[1] * o0[1] + o0[2] * o0[2] + o0[3] * o0[3]) + (o1[0] * o1[0] + o1[1] * o1[1] + o1[2] * o1[2] + o1[3] * o1[3]); } }
;                 if (ssout) { sq += __shfl_xor(sq, 16); sq += __shfl_xor(sq, 32);
;                     if (fq == 0) { if (red) red[(ai * 128 + wr * 64 + m * 16 + fr) * 4 + wc] = sq; else atomicAdd(ssout + (size_t)(row0 + ai * 128 + m * 16) * 8 + u.pn, sq); } } }
.LBB0_286:
	s_or_b64 exec, exec, s[28:29]
	s_waitcnt lgkmcnt(0)
	v_lshlrev_b64 v[48:49], 11, v[80:81]
	v_pk_add_f32 v[46:47], v[46:47], v[78:79]
	v_pk_add_f32 v[44:45], v[44:45], v[76:77]
	v_pk_add_f32 v[40:41], v[40:41], v[72:73]
	v_lshl_add_u64 v[52:53], v[48:49], 0, v[154:155]
	v_pk_add_f32 v[42:43], v[42:43], v[74:75]
	global_store_dwordx4 v[82:83], v[44:47], off
	global_store_dwordx4 v[82:83], v[40:43], off offset:16
	v_cvt_pk_bf16_f32 v48, v44, v45
	v_cvt_pk_bf16_f32 v50, v40, v41
	v_mul_f32_e32 v45, v45, v45
	v_mul_f32_e32 v41, v41, v41
	v_fmac_f32_e32 v45, v44, v44
	v_fmac_f32_e32 v41, v40, v40
	v_fmac_f32_e32 v45, v46, v46
	v_fmac_f32_e32 v41, v42, v42
	v_fmac_f32_e32 v45, v47, v47
	v_fmac_f32_e32 v41, v43, v43
	v_add_f32_e32 v44, v45, v41
	v_pk_add_f32 v[36:37], v[36:37], v[68:69]
	v_pk_add_f32 v[40:41], v[32:33], v[64:65]
	v_mul_f32_e32 v32, v37, v37
	v_mul_f32_e32 v33, v41, v41
	v_cvt_pk_bf16_f32 v51, v42, v43
	v_pk_add_f32 v[38:39], v[38:39], v[70:71]
	v_pk_add_f32 v[42:43], v[34:35], v[66:67]
	v_fmac_f32_e32 v32, v36, v36
	v_fmac_f32_e32 v33, v40, v40
	v_fmac_f32_e32 v32, v38, v38
	v_fmac_f32_e32 v33, v42, v42
	v_fmac_f32_e32 v32, v39, v39
	v_fmac_f32_e32 v33, v43, v43
	v_add_f32_e32 v32, v32, v33
	v_add_f32_e32 v32, v44, v32
	ds_bpermute_b32 v33, v118, v32
	v_readlane_b32 s28, v250, 9
	v_readlane_b32 s29, v250, 10
	v_cvt_pk_bf16_f32 v49, v46, v47
	v_cvt_pk_bf16_f32 v34, v36, v37
	s_waitcnt lgkmcnt(0)
	v_add_f32_e32 v32, v32, v33
	ds_bpermute_b32 v33, v119, v32
	v_lshl_add_u64 v[52:53], v[52:53], 1, s[28:29]
	global_store_dwordx4 v[52:53], v[48:51], off
	global_store_dwordx4 v[82:83], v[36:39], off offset:512
	global_store_dwordx4 v[82:83], v[40:43], off offset:528
	v_cvt_pk_bf16_f32 v35, v38, v39
	v_cvt_pk_bf16_f32 v36, v40, v41
	v_cvt_pk_bf16_f32 v37, v42, v43
	global_store_dwordx4 v[52:53], v[34:37], off offset:256
	s_and_saveexec_b64 s[28:29], s[6:7]
	s_cbranch_execz .LBB0_291
	s_waitcnt lgkmcnt(0)
	v_add_f32_e32 v32, v32, v33
	s_mov_b64 s[30:31], -1
	s_and_b64 vcc, exec, s[16:17]
	s_cbranch_vccz .LBB0_289
	v_lshlrev_b64 v[34:35], 5, v[80:81]
	v_lshl_add_u64 v[34:35], s[12:13], 0, v[34:35]
	v_lshl_add_u64 v[34:35], s[18:19], 2, v[34:35]
	global_atomic_add_f32 v[34:35], v32, off
	s_mov_b64 s[30:31], 0

; DEV bf16x8 pack8(f32x4 a, f32x4 b) { u32x4 w; w.x = cvt_pk_bf16(a[0], a[1]); w.y = cvt_pk_bf16(a[2], a[3]); w.z = cvt_pk_bf16(b[0], b[1]); w.w = cvt_pk_bf16(b[2], b[3]); return __builtin_bit_cast(bf16x8, w); }
;     DEV void operator()(AccRef acc, const pg8::Unit& u, int wr, int wc, int fr, int fq) const {
;     ...
;         for (int am = 0; am < 4; ++am) { const int ai = am >> 1, m0 = (am & 1) * 2;
;             f32x4 bv[4][2][2];
; #pragma unroll
;             for (int m = m0; m < m0 + 2; ++m)
; #pragma unroll
;                 for (int bj = 0; bj < 2; ++bj)
; #pragma unroll
;                     for (int n = 0; n < 2; ++n) bv[m][bj][n] = *(const f32x4*)(base + (size_t)(row0 + ai * 128 + m * 16) * 2048 + col0 + bj * 128 + n * 4);
; #pragma unroll
;             for (int m = m0; m < m0 + 2; ++m) { const size_t off = (size_t)(row0 + ai * 128 + m * 16) * 2048 + col0; float sq = 0.f;
; #pragma unroll
;                 for (int bj = 0; bj < 2; ++bj) { const f32x4 o0 = bv[m][bj][0] + scale * acc[ai][bj][m][0], o1 = bv[m][bj][1] + scale * acc[ai][bj][m][1];
;                     *(f32x4*)(out + off + bj * 128) = o0; *(f32x4*)(out + off + bj * 128 + 4) = o1;
;                     if (xb) { *(u32x4*)(xb + off + bj * 128) = __builtin_bit_cast(u32x4, pack8(o0, o1));
;                         sq += (o0[0] * o0[0] + o0[1] * o0[1] + o0[2] * o0[2] + o0[3] * o0[3]) + (o1[0] * o1[0] + o1[1] * o1[1] + o1[2] * o1[2] + o1[3] * o1[3]); } }
;                 if (ssout) { sq += __shfl_xor(sq, 16); sq += __shfl_xor(sq, 32);
;                     if (fq == 0) { if (red) red[(ai * 128 + wr * 64 + m * 16 + fr) * 4 + wc] = sq; else atomicAdd(ssout + (size_t)(row0 + ai * 128 + m * 16) * 8 + u.pn, sq); } } }
.LBB0_291:
	s_or_b64 exec, exec, s[28:29]
	v_add_u32_e32 v52, 0xa0, v156
	v_ashrrev_i32_e32 v53, 31, v52
	s_waitcnt lgkmcnt(0)
	v_lshlrev_b64 v[32:33], 13, v[52:53]
	v_lshl_add_u64 v[70:71], v[158:159], 0, v[32:33]
	s_waitcnt vmcnt(4)
	v_mov_b32_e32 v54, v218
	v_mov_b32_e32 v55, v219
	v_mov_b32_e32 v56, v220
	v_mov_b32_e32 v57, v221
	v_mov_b32_e32 v58, v222
	v_mov_b32_e32 v59, v223
	v_mov_b32_e32 v60, v224
	v_mov_b32_e32 v61, v225
	v_mov_b32_e32 v62, v226
	v_mov_b32_e32 v63, v227
	v_mov_b32_e32 v64, v228
	v_mov_b32_e32 v65, v229
	v_mov_b32_e32 v66, v230
	v_mov_b32_e32 v67, v231
	v_mov_b32_e32 v68, v232
	v_mov_b32_e32 v69, v233
	v_add_u32_e32 v48, 0xb0, v156
	v_ashrrev_i32_e32 v49, 31, v48
	v_lshlrev_b64 v[32:33], 13, v[48:49]
	v_lshl_add_u64 v[50:51], v[158:159], 0, v[32:33]
	v_mov_b32_e32 v40, v234
	v_mov_b32_e32 v41, v235
	v_mov_b32_e32 v42, v236
	v_mov_b32_e32 v43, v237
	v_mov_b32_e32 v44, v238
	v_mov_b32_e32 v45, v239
	v_mov_b32_e32 v46, v240
	v_mov_b32_e32 v47, v241
	v_mov_b32_e32 v32, v242
	v_mov_b32_e32 v33, v243
	v_mov_b32_e32 v34, v244
	v_mov_b32_e32 v35, v245
	v_mov_b32_e32 v36, v246
	v_mov_b32_e32 v37, v247
	v_mov_b32_e32 v38, v248
	v_mov_b32_e32 v39, v249
	v_lshlrev_b64 v[72:73], 11, v[52:53]
	v_readlane_b32 s28, v250, 9
	v_lshl_add_u64 v[72:73], v[72:73], 0, v[154:155]
	v_readlane_b32 s29, v250, 10
	v_pk_add_f32 v[30:31], v[30:31], v[56:57]
	v_pk_add_f32 v[28:29], v[28:29], v[54:55]
	v_pk_add_f32 v[24:25], v[24:25], v[58:59]
	v_pk_add_f32 v[20:21], v[20:21], v[62:63]
	v_pk_add_f32 v[54:55], v[16:17], v[66:67]
	v_pk_add_f32 v[26:27], v[26:27], v[60:61]
	v_pk_add_f32 v[56:57], v[18:19], v[68:69]
	global_store_dwordx4 v[70:71], v[28:31], off
	global_store_dwordx4 v[70:71], v[24:27], off offset:16
	v_cvt_pk_bf16_f32 v16, v28, v29
	v_cvt_pk_bf16_f32 v18, v24, v25
	v_mul_f32_e32 v29, v29, v29
	v_mul_f32_e32 v25, v25, v25
	v_mul_f32_e32 v58, v21, v21
	v_mul_f32_e32 v59, v55, v55
	v_pk_add_f32 v[22:23], v[22:23], v[64:65]
	v_fmac_f32_e32 v29, v28, v28
	v_fmac_f32_e32 v25, v24, v24
	v_fmac_f32_e32 v58, v20, v20
	v_fmac_f32_e32 v59, v54, v54
	v_fmac_f32_e32 v29, v30, v30
	v_fmac_f32_e32 v25, v26, v26
	v_fmac_f32_e32 v58, v22, v22
	v_fmac_f32_e32 v59, v56, v56
	v_fmac_f32_e32 v29, v31, v31
	v_fmac_f32_e32 v25, v27, v27
	v_fmac_f32_e32 v58, v23, v23
	v_fmac_f32_e32 v59, v57, v57
	v_add_f32_e32 v24, v29, v25
	v_add_f32_e32 v25, v58, v59
	v_add_f32_e32 v24, v24, v25
	ds_bpermute_b32 v25, v118, v24
	v_lshl_add_u64 v[72:73], v[72:73], 1, s[28:29]
	v_cvt_pk_bf16_f32 v17, v30, v31
	v_cvt_pk_bf16_f32 v19, v26, v27
	global_store_dwordx4 v[72:73], v[16:19], off
	global_store_dwordx4 v[70:71], v[20:23], off offset:512
	global_store_dwordx4 v[70:71], v[54:57], off offset:528
	s_waitcnt lgkmcnt(0)
	v_add_f32_e32 v16, v24, v25
	ds_bpermute_b32 v17, v119, v16
	v_cvt_pk_bf16_f32 v18, v20, v21
	v_cvt_pk_bf16_f32 v19, v22, v23
	v_cvt_pk_bf16_f32 v20, v54, v55
	v_cvt_pk_bf16_f32 v21, v56, v57
	global_store_dwordx4 v[72:73], v[18:21], off offset:256
	s_and_saveexec_b64 s[28:29], s[6:7]
	s_cbranch_execz .LBB0_296
	s_waitcnt lgkmcnt(0)
	v_add_f32_e32 v16, v16, v17
	s_mov_b64 s[30:31], -1
	s_and_b64 vcc, exec, s[16:17]
	s_cbranch_vccz .LBB0_294
	v_lshlrev_b64 v[18:19], 5, v[52:53]
	v_lshl_add_u64 v[18:19], s[12:13], 0, v[18:19]
	v_lshl_add_u64 v[18:19], s[18:19], 2, v[18:19]
	global_atomic_add_f32 v[18:19], v16, off
	s_mov_b64 s[30:31], 0

; DEV bf16x8 pack8(f32x4 a, f32x4 b) { u32x4 w; w.x = cvt_pk_bf16(a[0], a[1]); w.y = cvt_pk_bf16(a[2], a[3]); w.z = cvt_pk_bf16(b[0], b[1]); w.w = cvt_pk_bf16(b[2], b[3]); return __builtin_bit_cast(bf16x8, w); }
;     DEV void operator()(AccRef acc, const pg8::Unit& u, int wr, int wc, int fr, int fq) const {
;     ...
;             for (int m = m0; m < m0 + 2; ++m) { const size_t off = (size_t)(row0 + ai * 128 + m * 16) * 2048 + col0; float sq = 0.f;
; #pragma unroll
;                 for (int bj = 0; bj < 2; ++bj) { const f32x4 o0 = bv[m][bj][0] + scale * acc[ai][bj][m][0], o1 = bv[m][bj][1] + scale * acc[ai][bj][m][1];
;                     *(f32x4*)(out + off + bj * 128) = o0; *(f32x4*)(out + off + bj * 128 + 4) = o1;
;                     if (xb) { *(u32x4*)(xb + off + bj * 128) = __builtin_bit_cast(u32x4, pack8(o0, o1));
;                         sq += (o0[0] * o0[0] + o0[1] * o0[1] + o0[2] * o0[2] + o0[3] * o0[3]) + (o1[0] * o1[0] + o1[1] * o1[1] + o1[2] * o1[2] + o1[3] * o1[3]); } }
;                 if (ssout) { sq += __shfl_xor(sq, 16); sq += __shfl_xor(sq, 32);
;                     if (fq == 0) { if (red) red[(ai * 128 + wr * 64 + m * 16 + fr) * 4 + wc] = sq; else atomicAdd(ssout + (size_t)(row0 + ai * 128 + m * 16) * 8 + u.pn, sq); } } }
.LBB0_296:
	s_or_b64 exec, exec, s[28:29]
	s_waitcnt lgkmcnt(0)
	v_lshlrev_b64 v[16:17], 11, v[48:49]
	v_pk_add_f32 v[14:15], v[14:15], v[46:47]
	v_pk_add_f32 v[12:13], v[12:13], v[44:45]
	v_pk_add_f32 v[8:9], v[8:9], v[40:41]
	v_lshl_add_u64 v[20:21], v[16:17], 0, v[154:155]
	v_pk_add_f32 v[10:11], v[10:11], v[42:43]
	global_store_dwordx4 v[50:51], v[12:15], off
	global_store_dwordx4 v[50:51], v[8:11], off offset:16
	v_cvt_pk_bf16_f32 v16, v12, v13
	v_cvt_pk_bf16_f32 v18, v8, v9
	v_mul_f32_e32 v13, v13, v13
	v_mul_f32_e32 v9, v9, v9
	v_fmac_f32_e32 v13, v12, v12
	v_fmac_f32_e32 v9, v8, v8
	v_fmac_f32_e32 v13, v14, v14
	v_fmac_f32_e32 v9, v10, v10
	v_fmac_f32_e32 v13, v15, v15
	v_fmac_f32_e32 v9, v11, v11
	v_add_f32_e32 v12, v13, v9
	v_pk_add_f32 v[4:5], v[4:5], v[36:37]
	v_pk_add_f32 v[8:9], v[0:1], v[32:33]
	v_mul_f32_e32 v0, v5, v5
	v_mul_f32_e32 v1, v9, v9
	v_cvt_pk_bf16_f32 v19, v10, v11
	v_pk_add_f32 v[6:7], v[6:7], v[38:39]
	v_pk_add_f32 v[10:11], v[2:3], v[34:35]
	v_fmac_f32_e32 v0, v4, v4
	v_fmac_f32_e32 v1, v8, v8
	v_fmac_f32_e32 v0, v6, v6
	v_fmac_f32_e32 v1, v10, v10
	v_fmac_f32_e32 v0, v7, v7
	v_fmac_f32_e32 v1, v11, v11
	v_add_f32_e32 v0, v0, v1
	v_add_f32_e32 v0, v12, v0
	ds_bpermute_b32 v1, v118, v0
	v_readlane_b32 s28, v250, 9
	v_readlane_b32 s29, v250, 10
	v_cvt_pk_bf16_f32 v17, v14, v15
	v_cvt_pk_bf16_f32 v2, v4, v5
	s_waitcnt lgkmcnt(0)
	v_add_f32_e32 v0, v0, v1
	ds_bpermute_b32 v1, v119, v0
	v_lshl_add_u64 v[20:21], v[20:21], 1, s[28:29]
	global_store_dwordx4 v[20:21], v[16:19], off
	global_store_dwordx4 v[50:51], v[4:7], off offset:512
	global_store_dwordx4 v[50:51], v[8:11], off offset:528
	v_cvt_pk_bf16_f32 v3, v6, v7
	v_cvt_pk_bf16_f32 v4, v8, v9
	v_cvt_pk_bf16_f32 v5, v10, v11
	global_store_dwordx4 v[20:21], v[2:5], off offset:256
	s_and_saveexec_b64 s[28:29], s[6:7]
	s_cbranch_execz .LBB0_301
	s_waitcnt lgkmcnt(0)
	v_add_f32_e32 v0, v0, v1
	s_mov_b64 s[30:31], -1
	s_and_b64 vcc, exec, s[16:17]
	s_cbranch_vccz .LBB0_299
	v_lshlrev_b64 v[2:3], 5, v[48:49]
	v_lshl_add_u64 v[2:3], s[12:13], 0, v[2:3]
	v_lshl_add_u64 v[2:3], s[18:19], 2, v[2:3]
	global_atomic_add_f32 v[2:3], v0, off
	s_mov_b64 s[30:31], 0

; #define PG8_STAGE(bufoff, gbase, voff) do { _Pragma("unroll") for (int _i = 0; _i < 2; ++_i) \
;         __builtin_amdgcn_global_load_lds((const unsigned*)((const char*)(gbase) + (voff)[_i]), (LAS unsigned*)(lds + (bufoff) + ldsw + _i * 8192), 16, 0, 0); } while (0)
; #define PG8_LDA(dst, b, h) do { _Pragma("unroll") for (int m = 0; m < 4; ++m) _Pragma("unroll") for (int k = 0; k < 2; ++k) dst[m][k] = *(const LAS bf16x8*)(lds + PG8_SA(b, h) + aoff + m * 2048 + k * 1024); } while (0)
; #define PG8_LDB(dst, b, h) do { _Pragma("unroll") for (int n = 0; n < 2; ++n) _Pragma("unroll") for (int k = 0; k < 2; ++k) dst[n][k] = *(const LAS bf16x8*)(lds + PG8_SB(b, h) + boff + n * 2048 + k * 1024); } while (0)
; #define PG8_MMA(ai, bj, At, Bt) do { __builtin_amdgcn_s_setprio(1); _Pragma("unroll") for (int m = 0; m < 4; ++m) _Pragma("unroll") for (int n = 0; n < 2; ++n) _Pragma("unroll") for (int k = 0; k < 2; ++k) \
;         acc[ai][bj][m][n] = __builtin_amdgcn_mfma_f32_16x16x32_bf16(Bt[n][k], At[m][k], acc[ai][bj][m][n], 0, 0, 0); __builtin_amdgcn_s_setprio(0); } while (0)
; #define PG8_WAIT_L(n) asm volatile("s_waitcnt lgkmcnt(" #n ")" ::: "memory")
; #define PG8_BAR __builtin_amdgcn_s_barrier()
; #define PG8_SCHED __builtin_amdgcn_sched_barrier(0)
; template <class Epi>
; DEV void gemm_phase(LAS unsigned char* lds, const Gemm g, const StaticOrder& S, const Epi& E) {
;     ...
;             PG8_LDB(B0, 0, 0); PG8_SCHED; PG8_LDA(At, 0, 0); PG8_STAGE(PG8_SA(1, 1), a1 + hstep, voffA);
;             PG8_WAIT_L(8); PG8_BAR; PG8_WAIT_L(0); PG8_MMA(0, 0, At, B0); PG8_BAR; PG8_SCHED;
;             PG8_LDB(B1, 0, 1); PG8_STAGE(PG8_SB(0, 0), b2, voffB);
;             PG8_BAR; PG8_WAIT_L(0); PG8_MMA(0, 1, At, B1); PG8_BAR;
;             PG8_LDA(At, 0, 1); PG8_STAGE(PG8_SA(0, 0), a2, voffA);
;             PG8_BAR; PG8_WAIT_L(0); PG8_MMA(1, 0, At, B0); PG8_BAR; PG8_SCHED;
.LBB0_404:
	s_add_u32 s28, s26, 0xfff00080
	s_addc_u32 s29, s27, -1
	s_add_i32 s49, 0, 0x10000
	v_add_u32_e32 v140, s49, v178
	ds_read_b128 v[128:131], v140
	ds_read_b128 v[132:135], v140 offset:1024
	ds_read_b128 v[136:139], v140 offset:2048
	ds_read_b128 v[140:143], v140 offset:3072
	s_cmp_eq_u32 s48, 60
	s_cselect_b32 s31, s15, s29
	s_cselect_b32 s30, s19, s28
	s_cselect_b32 s29, s17, s47
	s_cselect_b32 s28, s25, s46
	v_lshl_add_u64 v[158:159], s[26:27], 0, v[150:151]
	s_add_i32 m0, s37, 0xc000
	ds_read_b128 v[154:157], v181
	ds_read_b128 v[174:177], v181 offset:1024
	ds_read_b128 v[182:185], v181 offset:2048
	ds_read_b128 v[186:189], v181 offset:3072
	ds_read_b128 v[190:193], v181 offset:4096
	ds_read_b128 v[194:197], v181 offset:5120
	ds_read_b128 v[214:217], v181 offset:6144
	ds_read_b128 v[218:221], v181 offset:7168
	global_load_lds_dwordx4 v[158:159], off
	v_lshl_add_u64 v[158:159], s[26:27], 0, v[152:153]
	s_add_i32 m0, s37, 0xe000
	s_nop 0
	global_load_lds_dwordx4 v[158:159], off
	s_waitcnt lgkmcnt(8)
	s_barrier
	s_waitcnt lgkmcnt(0)
	s_setprio 1
	v_mfma_f32_16x16x32_bf16 v[124:127], v[128:131], v[154:157], v[124:127]
	v_mfma_f32_16x16x32_bf16 v[120:123], v[136:139], v[154:157], v[120:123]
	v_mfma_f32_16x16x32_bf16 v[108:111], v[128:131], v[182:185], v[108:111]
	v_mfma_f32_16x16x32_bf16 v[104:107], v[136:139], v[182:185], v[104:107]
	v_mfma_f32_16x16x32_bf16 v[92:95], v[128:131], v[190:193], v[92:95]
	v_mfma_f32_16x16x32_bf16 v[88:91], v[136:139], v[190:193], v[88:91]
	v_mfma_f32_16x16x32_bf16 v[76:79], v[128:131], v[214:217], v[76:79]
	v_mfma_f32_16x16x32_bf16 v[72:75], v[136:139], v[214:217], v[72:75]
	v_mfma_f32_16x16x32_bf16 v[124:127], v[132:135], v[174:177], v[124:127]
	v_mfma_f32_16x16x32_bf16 v[120:123], v[140:143], v[174:177], v[120:123]
	v_mfma_f32_16x16x32_bf16 v[108:111], v[132:135], v[186:189], v[108:111]
	v_mfma_f32_16x16x32_bf16 v[104:107], v[140:143], v[186:189], v[104:107]
	v_mfma_f32_16x16x32_bf16 v[92:95], v[132:135], v[194:197], v[92:95]
	v_mfma_f32_16x16x32_bf16 v[88:91], v[140:143], v[194:197], v[88:91]
	v_mfma_f32_16x16x32_bf16 v[76:79], v[132:135], v[218:221], v[76:79]
	v_mfma_f32_16x16x32_bf16 v[72:75], v[140:143], v[218:221], v[72:75]
	s_setprio 0
	s_barrier
	s_add_i32 s52, 0, 0x14000
	v_add_u32_e32 v158, s52, v178
	s_add_i32 s49, s49, s36
	ds_read_b128 v[222:225], v158
	ds_read_b128 v[226:229], v158 offset:1024
	ds_read_b128 v[230:233], v158 offset:2048
	ds_read_b128 v[234:237], v158 offset:3072
	v_lshl_add_u64 v[158:159], s[28:29], 0, v[160:161]
	s_mov_b32 m0, s49
	v_lshl_add_u64 v[238:239], s[28:29], 0, v[148:149]
	global_load_lds_dwordx4 v[158:159], off
	s_add_i32 m0, s49, 0x2000
	s_nop 0
	global_load_lds_dwordx4 v[238:239], off
	s_barrier
	s_waitcnt lgkmcnt(0)
	s_setprio 1
	v_mfma_f32_16x16x32_bf16 v[116:119], v[222:225], v[154:157], v[116:119]
	v_mfma_f32_16x16x32_bf16 v[112:115], v[230:233], v[154:157], v[112:115]
	v_mfma_f32_16x16x32_bf16 v[100:103], v[222:225], v[182:185], v[100:103]
	v_mfma_f32_16x16x32_bf16 v[96:99], v[230:233], v[182:185], v[96:99]
	v_mfma_f32_16x16x32_bf16 v[84:87], v[222:225], v[190:193], v[84:87]
	v_mfma_f32_16x16x32_bf16 v[80:83], v[230:233], v[190:193], v[80:83]
	v_mfma_f32_16x16x32_bf16 v[68:71], v[222:225], v[214:217], v[68:71]
	v_mfma_f32_16x16x32_bf16 v[64:67], v[230:233], v[214:217], v[64:67]
	v_mfma_f32_16x16x32_bf16 v[116:119], v[226:229], v[174:177], v[116:119]
	v_mfma_f32_16x16x32_bf16 v[112:115], v[234:237], v[174:177], v[112:115]
	v_mfma_f32_16x16x32_bf16 v[100:103], v[226:229], v[186:189], v[100:103]
	v_mfma_f32_16x16x32_bf16 v[96:99], v[234:237], v[186:189], v[96:99]
	v_mfma_f32_16x16x32_bf16 v[84:87], v[226:229], v[194:197], v[84:87]
	v_mfma_f32_16x16x32_bf16 v[80:83], v[234:237], v[194:197], v[80:83]
	v_mfma_f32_16x16x32_bf16 v[68:71], v[226:229], v[218:221], v[68:71]
	v_mfma_f32_16x16x32_bf16 v[64:67], v[234:237], v[218:221], v[64:67]
	s_setprio 0
	s_mov_b32 m0, s37
	v_lshl_add_u64 v[240:241], s[30:31], 0, v[144:145]
	s_barrier
	ds_read_b128 v[154:157], v181 offset:16384
	ds_read_b128 v[174:177], v181 offset:17408
	ds_read_b128 v[182:185], v181 offset:18432
	ds_read_b128 v[186:189], v181 offset:19456
	ds_read_b128 v[190:193], v181 offset:20480
	ds_read_b128 v[194:197], v181 offset:21504
	ds_read_b128 v[214:217], v181 offset:22528
	ds_read_b128 v[218:221], v181 offset:23552
	global_load_lds_dwordx4 v[240:241], off
	v_lshl_add_u64 v[242:243], s[30:31], 0, v[146:147]
	s_mov_b32 m0, s38
	s_nop 0
	global_load_lds_dwordx4 v[242:243], off
	s_barrier
	s_waitcnt lgkmcnt(0)
	s_setprio 1
	v_mfma_f32_16x16x32_bf16 v[60:63], v[128:131], v[154:157], v[60:63]
	v_mfma_f32_16x16x32_bf16 v[56:59], v[136:139], v[154:157], v[56:59]
	v_mfma_f32_16x16x32_bf16 v[44:47], v[128:131], v[182:185], v[44:47]
	v_mfma_f32_16x16x32_bf16 v[40:43], v[136:139], v[182:185], v[40:43]
	v_mfma_f32_16x16x32_bf16 v[28:31], v[128:131], v[190:193], v[28:31]
	v_mfma_f32_16x16x32_bf16 v[24:27], v[136:139], v[190:193], v[24:27]
	v_mfma_f32_16x16x32_bf16 v[12:15], v[128:131], v[214:217], v[12:15]
	v_mfma_f32_16x16x32_bf16 v[8:11], v[136:139], v[214:217], v[8:11]
	v_mfma_f32_16x16x32_bf16 v[60:63], v[132:135], v[174:177], v[60:63]
	v_mfma_f32_16x16x32_bf16 v[56:59], v[140:143], v[174:177], v[56:59]
	v_mfma_f32_16x16x32_bf16 v[44:47], v[132:135], v[186:189], v[44:47]
	v_mfma_f32_16x16x32_bf16 v[40:43], v[140:143], v[186:189], v[40:43]
	v_mfma_f32_16x16x32_bf16 v[28:31], v[132:135], v[194:197], v[28:31]
	v_mfma_f32_16x16x32_bf16 v[24:27], v[140:143], v[194:197], v[24:27]
	v_mfma_f32_16x16x32_bf16 v[12:15], v[132:135], v[218:221], v[12:15]
	v_mfma_f32_16x16x32_bf16 v[8:11], v[140:143], v[218:221], v[8:11]
	s_setprio 0
	s_barrier
; #define PG8_STAGE(bufoff, gbase, voff) do { _Pragma("unroll") for (int _i = 0; _i < 2; ++_i) \
;         __builtin_amdgcn_global_load_lds((const unsigned*)((const char*)(gbase) + (voff)[_i]), (LAS unsigned*)(lds + (bufoff) + ldsw + _i * 8192), 16, 0, 0); } while (0)
; #define PG8_LDA(dst, b, h) do { _Pragma("unroll") for (int m = 0; m < 4; ++m) _Pragma("unroll") for (int k = 0; k < 2; ++k) dst[m][k] = *(const LAS bf16x8*)(lds + PG8_SA(b, h) + aoff + m * 2048 + k * 1024); } while (0)
; #define PG8_LDB(dst, b, h) do { _Pragma("unroll") for (int n = 0; n < 2; ++n) _Pragma("unroll") for (int k = 0; k < 2; ++k) dst[n][k] = *(const LAS bf16x8*)(lds + PG8_SB(b, h) + boff + n * 2048 + k * 1024); } while (0)
; #define PG8_MMA(ai, bj, At, Bt) do { __builtin_amdgcn_s_setprio(1); _Pragma("unroll") for (int m = 0; m < 4; ++m) _Pragma("unroll") for (int n = 0; n < 2; ++n) _Pragma("unroll") for (int k = 0; k < 2; ++k) \
;         acc[ai][bj][m][n] = __builtin_amdgcn_mfma_f32_16x16x32_bf16(Bt[n][k], At[m][k], acc[ai][bj][m][n], 0, 0, 0); __builtin_amdgcn_s_setprio(0); } while (0)
; #define PG8_WAIT_V(n) asm volatile("s_waitcnt vmcnt(" #n ")" ::: "memory")
; #define PG8_WAIT_L(n) asm volatile("s_waitcnt lgkmcnt(" #n ")" ::: "memory")
; #define PG8_BAR __builtin_amdgcn_s_barrier()
; #define PG8_SCHED __builtin_amdgcn_sched_barrier(0)
; template <class Epi>
; DEV void gemm_phase(LAS unsigned char* lds, const Gemm g, const StaticOrder& S, const Epi& E) {
;     ...
;             PG8_BAR; PG8_WAIT_L(0); PG8_MMA(1, 0, At, B0); PG8_BAR; PG8_SCHED;
;             PG8_STAGE(PG8_SB(0, 1), b2 + hstep, voffB);
;             PG8_WAIT_V(6); PG8_BAR; PG8_MMA(1, 1, At, B1); PG8_BAR;
;             PG8_LDB(B0, 1, 0); PG8_SCHED; PG8_LDA(At, 1, 0); PG8_STAGE(PG8_SA(0, 1), a2 + hstep, voffA);
;             PG8_WAIT_L(8); PG8_BAR; PG8_WAIT_L(0); PG8_MMA(0, 0, At, B0); PG8_BAR; PG8_SCHED;
;             PG8_LDB(B1, 1, 1); PG8_STAGE(PG8_SB(1, 0), b3, voffB);
;             PG8_BAR; PG8_WAIT_L(0); PG8_MMA(0, 1, At, B1); PG8_BAR;
;             PG8_LDA(At, 1, 1); PG8_STAGE(PG8_SA(1, 0), a3, voffA);
	s_add_u32 s50, s28, 0x100000
	s_addc_u32 s51, s29, 0
	s_add_i32 s49, s52, s36
	v_lshl_add_u64 v[128:129], s[50:51], 0, v[160:161]
	s_mov_b32 m0, s49
	s_nop 0
	global_load_lds_dwordx4 v[128:129], off
	v_lshl_add_u64 v[128:129], s[50:51], 0, v[148:149]
	s_add_i32 m0, s49, 0x2000
	s_nop 0
	global_load_lds_dwordx4 v[128:129], off
	s_waitcnt vmcnt(6)
	s_barrier
	s_setprio 1
	v_mfma_f32_16x16x32_bf16 v[52:55], v[222:225], v[154:157], v[52:55]
	v_mfma_f32_16x16x32_bf16 v[48:51], v[230:233], v[154:157], v[48:51]
	v_mfma_f32_16x16x32_bf16 v[36:39], v[222:225], v[182:185], v[36:39]
	v_mfma_f32_16x16x32_bf16 v[32:35], v[230:233], v[182:185], v[32:35]
	v_mfma_f32_16x16x32_bf16 v[20:23], v[222:225], v[190:193], v[20:23]
	v_mfma_f32_16x16x32_bf16 v[16:19], v[230:233], v[190:193], v[16:19]
	v_mfma_f32_16x16x32_bf16 v[4:7], v[222:225], v[214:217], v[4:7]
	v_mfma_f32_16x16x32_bf16 v[0:3], v[230:233], v[214:217], v[0:3]
	v_mfma_f32_16x16x32_bf16 v[52:55], v[226:229], v[174:177], v[52:55]
	v_mfma_f32_16x16x32_bf16 v[48:51], v[234:237], v[174:177], v[48:51]
	v_mfma_f32_16x16x32_bf16 v[36:39], v[226:229], v[186:189], v[36:39]
	v_mfma_f32_16x16x32_bf16 v[32:35], v[234:237], v[186:189], v[32:35]
	v_mfma_f32_16x16x32_bf16 v[20:23], v[226:229], v[194:197], v[20:23]
	v_mfma_f32_16x16x32_bf16 v[16:19], v[234:237], v[194:197], v[16:19]
	v_mfma_f32_16x16x32_bf16 v[4:7], v[226:229], v[218:221], v[4:7]
	v_mfma_f32_16x16x32_bf16 v[0:3], v[234:237], v[218:221], v[0:3]
	s_setprio 0
	s_add_i32 s49, 0, 0x18000
	v_add_u32_e32 v140, s49, v178
	s_barrier
	ds_read_b128 v[128:131], v140
	ds_read_b128 v[132:135], v140 offset:1024
	ds_read_b128 v[136:139], v140 offset:2048
	ds_read_b128 v[140:143], v140 offset:3072
	s_add_u32 s30, s30, 0x100000
	s_addc_u32 s31, s31, 0
	s_mov_b32 m0, s39
	v_lshl_add_u64 v[222:223], s[30:31], 0, v[144:145]
	ds_read_b128 v[154:157], v181 offset:32768
	ds_read_b128 v[174:177], v181 offset:33792
	ds_read_b128 v[182:185], v181 offset:34816
	ds_read_b128 v[186:189], v181 offset:35840
	ds_read_b128 v[190:193], v181 offset:36864
	ds_read_b128 v[194:197], v181 offset:37888
	ds_read_b128 v[214:217], v181 offset:38912
	ds_read_b128 v[218:221], v181 offset:39936
	global_load_lds_dwordx4 v[222:223], off
	v_lshl_add_u64 v[222:223], s[30:31], 0, v[146:147]
	s_mov_b32 m0, s40
	s_nop 0
	global_load_lds_dwordx4 v[222:223], off
	s_waitcnt lgkmcnt(8)
	s_barrier
	s_waitcnt lgkmcnt(0)
	s_setprio 1
	v_mfma_f32_16x16x32_bf16 v[124:127], v[128:131], v[154:157], v[124:127]
	v_mfma_f32_16x16x32_bf16 v[120:123], v[136:139], v[154:157], v[120:123]
	v_mfma_f32_16x16x32_bf16 v[108:111], v[128:131], v[182:185], v[108:111]
	v_mfma_f32_16x16x32_bf16 v[104:107], v[136:139], v[182:185], v[104:107]
	v_mfma_f32_16x16x32_bf16 v[92:95], v[128:131], v[190:193], v[92:95]
	v_mfma_f32_16x16x32_bf16 v[88:91], v[136:139], v[190:193], v[88:91]
	v_mfma_f32_16x16x32_bf16 v[76:79], v[128:131], v[214:217], v[76:79]
	v_mfma_f32_16x16x32_bf16 v[72:75], v[136:139], v[214:217], v[72:75]
	v_mfma_f32_16x16x32_bf16 v[124:127], v[132:135], v[174:177], v[124:127]
	v_mfma_f32_16x16x32_bf16 v[120:123], v[140:143], v[174:177], v[120:123]
	v_mfma_f32_16x16x32_bf16 v[108:111], v[132:135], v[186:189], v[108:111]
	v_mfma_f32_16x16x32_bf16 v[104:107], v[140:143], v[186:189], v[104:107]
	v_mfma_f32_16x16x32_bf16 v[92:95], v[132:135], v[194:197], v[92:95]
	v_mfma_f32_16x16x32_bf16 v[88:91], v[140:143], v[194:197], v[88:91]
	v_mfma_f32_16x16x32_bf16 v[76:79], v[132:135], v[218:221], v[76:79]
	v_mfma_f32_16x16x32_bf16 v[72:75], v[140:143], v[218:221], v[72:75]
	s_setprio 0
	s_barrier
	s_add_i32 s30, 0, 0x1c000
	s_add_i32 s31, s49, s36
	v_add_u32_e32 v234, s30, v178
	v_lshl_add_u64 v[158:159], v[158:159], 0, s[2:3]
	s_mov_b32 m0, s31
	ds_read_b128 v[222:225], v234
	ds_read_b128 v[226:229], v234 offset:1024
	ds_read_b128 v[230:233], v234 offset:2048
	ds_read_b128 v[234:237], v234 offset:3072
	global_load_lds_dwordx4 v[158:159], off
	v_lshl_add_u64 v[158:159], v[238:239], 0, s[2:3]
	s_add_i32 m0, s31, 0x2000
	s_nop 0
	global_load_lds_dwordx4 v[158:159], off
	s_barrier
	s_waitcnt lgkmcnt(0)
	s_setprio 1
	v_mfma_f32_16x16x32_bf16 v[116:119], v[222:225], v[154:157], v[116:119]
	v_mfma_f32_16x16x32_bf16 v[112:115], v[230:233], v[154:157], v[112:115]
	v_mfma_f32_16x16x32_bf16 v[100:103], v[222:225], v[182:185], v[100:103]
	v_mfma_f32_16x16x32_bf16 v[96:99], v[230:233], v[182:185], v[96:99]
	v_mfma_f32_16x16x32_bf16 v[84:87], v[222:225], v[190:193], v[84:87]
	v_mfma_f32_16x16x32_bf16 v[80:83], v[230:233], v[190:193], v[80:83]
	v_mfma_f32_16x16x32_bf16 v[68:71], v[222:225], v[214:217], v[68:71]
	v_mfma_f32_16x16x32_bf16 v[64:67], v[230:233], v[214:217], v[64:67]
	v_mfma_f32_16x16x32_bf16 v[116:119], v[226:229], v[174:177], v[116:119]
	v_mfma_f32_16x16x32_bf16 v[112:115], v[234:237], v[174:177], v[112:115]
	v_mfma_f32_16x16x32_bf16 v[100:103], v[226:229], v[186:189], v[100:103]
	v_mfma_f32_16x16x32_bf16 v[96:99], v[234:237], v[186:189], v[96:99]
	v_mfma_f32_16x16x32_bf16 v[84:87], v[226:229], v[194:197], v[84:87]
	v_mfma_f32_16x16x32_bf16 v[80:83], v[234:237], v[194:197], v[80:83]
	v_mfma_f32_16x16x32_bf16 v[68:71], v[226:229], v[218:221], v[68:71]
	v_mfma_f32_16x16x32_bf16 v[64:67], v[234:237], v[218:221], v[64:67]
	s_setprio 0
	s_mov_b32 m0, s41
	v_lshl_add_u64 v[158:159], v[240:241], 0, s[2:3]
	s_barrier
	ds_read_b128 v[154:157], v181 offset:49152
	ds_read_b128 v[174:177], v181 offset:50176
	ds_read_b128 v[182:185], v181 offset:51200
	ds_read_b128 v[186:189], v181 offset:52224
	ds_read_b128 v[190:193], v181 offset:53248
	ds_read_b128 v[194:197], v181 offset:54272
	ds_read_b128 v[214:217], v181 offset:55296
	ds_read_b128 v[218:221], v181 offset:56320
	global_load_lds_dwordx4 v[158:159], off
	v_lshl_add_u64 v[158:159], v[242:243], 0, s[2:3]
	s_mov_b32 m0, s42
	s_nop 0
	global_load_lds_dwordx4 v[158:159], off
	s_barrier
; #define PG8_STAGE(bufoff, gbase, voff) do { _Pragma("unroll") for (int _i = 0; _i < 2; ++_i) \
;         __builtin_amdgcn_global_load_lds((const unsigned*)((const char*)(gbase) + (voff)[_i]), (LAS unsigned*)(lds + (bufoff) + ldsw + _i * 8192), 16, 0, 0); } while (0)
; #define PG8_LDA(dst, b, h) do { _Pragma("unroll") for (int m = 0; m < 4; ++m) _Pragma("unroll") for (int k = 0; k < 2; ++k) dst[m][k] = *(const LAS bf16x8*)(lds + PG8_SA(b, h) + aoff + m * 2048 + k * 1024); } while (0)
; #define PG8_MMA(ai, bj, At, Bt) do { __builtin_amdgcn_s_setprio(1); _Pragma("unroll") for (int m = 0; m < 4; ++m) _Pragma("unroll") for (int n = 0; n < 2; ++n) _Pragma("unroll") for (int k = 0; k < 2; ++k) \
;         acc[ai][bj][m][n] = __builtin_amdgcn_mfma_f32_16x16x32_bf16(Bt[n][k], At[m][k], acc[ai][bj][m][n], 0, 0, 0); __builtin_amdgcn_s_setprio(0); } while (0)
; #define PG8_WAIT_V(n) asm volatile("s_waitcnt vmcnt(" #n ")" ::: "memory")
; #define PG8_WAIT_L(n) asm volatile("s_waitcnt lgkmcnt(" #n ")" ::: "memory")
; #define PG8_BAR __builtin_amdgcn_s_barrier()
; #define PG8_SCHED __builtin_amdgcn_sched_barrier(0)
; template <class Epi>
; DEV void gemm_phase(LAS unsigned char* lds, const Gemm g, const StaticOrder& S, const Epi& E) {
;     ...
;             PG8_LDA(At, 1, 1); PG8_STAGE(PG8_SA(1, 0), a3, voffA);
;             PG8_BAR; PG8_WAIT_L(0); PG8_MMA(1, 0, At, B0); PG8_BAR; PG8_SCHED;
;             PG8_STAGE(PG8_SB(1, 1), b3 + hstep, voffB);
;             PG8_WAIT_V(6); PG8_BAR; PG8_MMA(1, 1, At, B1); PG8_BAR;
	s_waitcnt lgkmcnt(0)
	s_setprio 1
	v_mfma_f32_16x16x32_bf16 v[60:63], v[128:131], v[154:157], v[60:63]
	v_mfma_f32_16x16x32_bf16 v[56:59], v[136:139], v[154:157], v[56:59]
	v_mfma_f32_16x16x32_bf16 v[44:47], v[128:131], v[182:185], v[44:47]
	v_mfma_f32_16x16x32_bf16 v[40:43], v[136:139], v[182:185], v[40:43]
	v_mfma_f32_16x16x32_bf16 v[28:31], v[128:131], v[190:193], v[28:31]
	v_mfma_f32_16x16x32_bf16 v[24:27], v[136:139], v[190:193], v[24:27]
	v_mfma_f32_16x16x32_bf16 v[12:15], v[128:131], v[214:217], v[12:15]
	v_mfma_f32_16x16x32_bf16 v[8:11], v[136:139], v[214:217], v[8:11]
	v_mfma_f32_16x16x32_bf16 v[60:63], v[132:135], v[174:177], v[60:63]
	v_mfma_f32_16x16x32_bf16 v[56:59], v[140:143], v[174:177], v[56:59]
	v_mfma_f32_16x16x32_bf16 v[44:47], v[132:135], v[186:189], v[44:47]
	v_mfma_f32_16x16x32_bf16 v[40:43], v[140:143], v[186:189], v[40:43]
	v_mfma_f32_16x16x32_bf16 v[28:31], v[132:135], v[194:197], v[28:31]
	v_mfma_f32_16x16x32_bf16 v[24:27], v[140:143], v[194:197], v[24:27]
	v_mfma_f32_16x16x32_bf16 v[12:15], v[132:135], v[218:221], v[12:15]
	v_mfma_f32_16x16x32_bf16 v[8:11], v[140:143], v[218:221], v[8:11]
	s_setprio 0
	s_barrier
	s_add_u32 s28, s28, 0x100080
	s_addc_u32 s29, s29, 0
	s_add_i32 s30, s30, s36
	v_lshl_add_u64 v[128:129], s[28:29], 0, v[160:161]
	s_mov_b32 m0, s30
	s_nop 0
	global_load_lds_dwordx4 v[128:129], off
	v_lshl_add_u64 v[128:129], s[28:29], 0, v[148:149]
	s_add_i32 m0, s30, 0x2000
	s_nop 0
	global_load_lds_dwordx4 v[128:129], off
	s_waitcnt vmcnt(6)
	s_barrier
	s_setprio 1
	v_mfma_f32_16x16x32_bf16 v[52:55], v[222:225], v[154:157], v[52:55]
	v_mfma_f32_16x16x32_bf16 v[48:51], v[230:233], v[154:157], v[48:51]
	v_mfma_f32_16x16x32_bf16 v[36:39], v[222:225], v[182:185], v[36:39]
	v_mfma_f32_16x16x32_bf16 v[32:35], v[230:233], v[182:185], v[32:35]
	v_mfma_f32_16x16x32_bf16 v[20:23], v[222:225], v[190:193], v[20:23]
	v_mfma_f32_16x16x32_bf16 v[16:19], v[230:233], v[190:193], v[16:19]
	v_mfma_f32_16x16x32_bf16 v[4:7], v[222:225], v[214:217], v[4:7]
	v_mfma_f32_16x16x32_bf16 v[0:3], v[230:233], v[214:217], v[0:3]
	v_mfma_f32_16x16x32_bf16 v[52:55], v[226:229], v[174:177], v[52:55]
	v_mfma_f32_16x16x32_bf16 v[48:51], v[234:237], v[174:177], v[48:51]
	v_mfma_f32_16x16x32_bf16 v[36:39], v[226:229], v[186:189], v[36:39]
	v_mfma_f32_16x16x32_bf16 v[32:35], v[234:237], v[186:189], v[32:35]
	v_mfma_f32_16x16x32_bf16 v[20:23], v[226:229], v[194:197], v[20:23]
	v_mfma_f32_16x16x32_bf16 v[16:19], v[234:237], v[194:197], v[16:19]
	v_mfma_f32_16x16x32_bf16 v[4:7], v[226:229], v[218:221], v[4:7]
	v_mfma_f32_16x16x32_bf16 v[0:3], v[234:237], v[218:221], v[0:3]
	s_setprio 0
	s_add_i32 s48, s48, 2
	s_add_u32 s26, s26, 0x100
	s_addc_u32 s27, s27, 0
	s_add_u32 s46, s46, 0x100
	s_addc_u32 s47, s47, 0
	s_cmp_gt_u32 s48, 61
	s_barrier
	s_cbranch_scc0 .LBB0_404
; DEV bf16x8 pack8(f32x4 a, f32x4 b) { u32x4 w; w.x = cvt_pk_bf16(a[0], a[1]); w.y = cvt_pk_bf16(a[2], a[3]); w.z = cvt_pk_bf16(b[0], b[1]); w.w = cvt_pk_bf16(b[2], b[3]); return __builtin_bit_cast(bf16x8, w); }
;     DEV void operator()(AccRef acc, const pg8::Unit& u, int wr, int wc, int fr, int fq) const {
;         const int row0 = u.pm * 256 + wr * 64 + fr, col0 = u.pn * 256 + wc * 32 + 8 * fq;
; #pragma unroll
;         for (int am = 0; am < 4; ++am) { const int ai = am >> 1, m0 = (am & 1) * 2;
;             f32x4 bv[4][2][2];
; #pragma unroll
;             for (int m = m0; m < m0 + 2; ++m)
; #pragma unroll
;                 for (int bj = 0; bj < 2; ++bj)
; #pragma unroll
;                     for (int n = 0; n < 2; ++n) bv[m][bj][n] = *(const f32x4*)(base + (size_t)(row0 + ai * 128 + m * 16) * 2048 + col0 + bj * 128 + n * 4);
; #pragma unroll
;             for (int m = m0; m < m0 + 2; ++m) { const size_t off = (size_t)(row0 + ai * 128 + m * 16) * 2048 + col0; float sq = 0.f;
; #pragma unroll
;                 for (int bj = 0; bj < 2; ++bj) { const f32x4 o0 = bv[m][bj][0] + scale * acc[ai][bj][m][0], o1 = bv[m][bj][1] + scale * acc[ai][bj][m][1];
;                     *(f32x4*)(out + off + bj * 128) = o0; *(f32x4*)(out + off + bj * 128 + 4) = o1;
;                     if (xb) { *(u32x4*)(xb + off + bj * 128) = __builtin_bit_cast(u32x4, pack8(o0, o1));
;                         sq += (o0[0] * o0[0] + o0[1] * o0[1] + o0[2] * o0[2] + o0[3] * o0[3]) + (o1[0] * o1[0] + o1[1] * o1[1] + o1[2] * o1[2] + o1[3] * o1[3]); } }
;                 if (ssout) { sq += __shfl_xor(sq, 16); sq += __shfl_xor(sq, 32);
;                     if (fq == 0) { if (red) red[(ai * 128 + wr * 64 + m * 16 + fr) * 4 + wc] = sq; else atomicAdd(ssout + (size_t)(row0 + ai * 128 + m * 16) * 8 + u.pn, sq); } } }
	v_lshl_add_u32 v156, s24, 8, v167
	v_lshl_or_b32 v154, s14, 8, v179
	v_readlane_b32 s24, v254, 16
	v_ashrrev_i32_e32 v155, 31, v154
	v_readlane_b32 s25, v254, 17
	v_ashrrev_i32_e32 v157, 31, v156
	v_lshlrev_b64 v[128:129], 13, v[156:157]
	v_lshl_add_u64 v[158:159], v[154:155], 2, s[24:25]
	v_lshl_add_u64 v[214:215], v[158:159], 0, v[128:129]
	global_load_dwordx4 v[182:185], v[214:215], off offset:16
	global_load_dwordx4 v[186:189], v[214:215], off
	global_load_dwordx4 v[190:193], v[214:215], off offset:528
	global_load_dwordx4 v[194:197], v[214:215], off offset:512
	v_or_b32_e32 v174, 16, v156
	v_ashrrev_i32_e32 v175, 31, v174
	v_lshlrev_b64 v[128:129], 13, v[174:175]
	v_lshl_add_u64 v[176:177], v[158:159], 0, v[128:129]
	global_load_dwordx4 v[136:139], v[176:177], off offset:16
	global_load_dwordx4 v[140:143], v[176:177], off
	global_load_dwordx4 v[128:131], v[176:177], off offset:528
	global_load_dwordx4 v[132:135], v[176:177], off offset:512
	v_add_u32_e32 v255, 32, v156
	v_lshlrev_b32_e32 v255, 13, v255
	v_lshl_add_u32 v255, v154, 2, v255
	global_load_dwordx4 v[218:221], v255, s[24:25]
	global_load_dwordx4 v[222:225], v255, s[24:25] offset:16
	global_load_dwordx4 v[226:229], v255, s[24:25] offset:512
	global_load_dwordx4 v[230:233], v255, s[24:25] offset:528
	v_add_u32_e32 v255, 48, v156
	v_lshlrev_b32_e32 v255, 13, v255
	v_lshl_add_u32 v255, v154, 2, v255
	global_load_dwordx4 v[234:237], v255, s[24:25] offset:16
	global_load_dwordx4 v[238:241], v255, s[24:25]
	global_load_dwordx4 v[242:245], v255, s[24:25] offset:528
	global_load_dwordx4 v[246:249], v255, s[24:25] offset:512
	v_lshlrev_b64 v[216:217], 11, v[156:157]
	v_readlane_b32 s24, v250, 9
	v_lshl_add_u64 v[216:217], v[216:217], 0, v[154:155]
	v_readlane_b32 s25, v250, 10
	v_cmp_lt_i32_e32 vcc, v208, v206
	s_ashr_i32 s15, s14, 31
	s_waitcnt vmcnt(0)
	v_pk_add_f32 v[120:121], v[120:121], v[182:183]
	v_pk_add_f32 v[126:127], v[126:127], v[188:189]
	v_pk_add_f32 v[124:125], v[124:125], v[186:187]
	v_pk_add_f32 v[122:123], v[122:123], v[184:185]
	global_store_dwordx4 v[214:215], v[124:127], off
	global_store_dwordx4 v[214:215], v[120:123], off offset:16
	v_cvt_pk_bf16_f32 v184, v120, v121
	v_cvt_pk_bf16_f32 v182, v124, v125
	v_mul_f32_e32 v121, v121, v121
	v_cvt_pk_bf16_f32 v183, v126, v127
	v_cvt_pk_bf16_f32 v185, v122, v123
	v_lshl_add_u64 v[186:187], v[216:217], 1, s[24:25]
	v_fmac_f32_e32 v121, v120, v120
	v_pk_add_f32 v[118:119], v[118:119], v[196:197]
	v_pk_add_f32 v[116:117], v[116:117], v[194:195]
	v_pk_add_f32 v[112:113], v[112:113], v[190:191]
	global_store_dwordx4 v[186:187], v[182:185], off
	v_mul_f32_e32 v125, v125, v125
	v_fmac_f32_e32 v121, v122, v122
	v_pk_add_f32 v[114:115], v[114:115], v[192:193]
	global_store_dwordx4 v[214:215], v[116:119], off offset:512
	global_store_dwordx4 v[214:215], v[112:115], off offset:528
	v_cvt_pk_bf16_f32 v120, v116, v117
	v_cvt_pk_bf16_f32 v122, v112, v113
	v_mul_f32_e32 v117, v117, v117
	v_mul_f32_e32 v113, v113, v113
	v_fmac_f32_e32 v125, v124, v124
	v_fmac_f32_e32 v117, v116, v116
	v_fmac_f32_e32 v113, v112, v112
	v_fmac_f32_e32 v125, v126, v126
	v_fmac_f32_e32 v117, v118, v118
	v_fmac_f32_e32 v113, v114, v114
	v_fmac_f32_e32 v125, v127, v127
	v_fmac_f32_e32 v121, v123, v123
	v_fmac_f32_e32 v117, v119, v119
	v_fmac_f32_e32 v113, v115, v115
	v_add_f32_e32 v124, v125, v121
	v_add_f32_e32 v112, v117, v113
	v_cndmask_b32_e32 v113, v204, v208, vcc
	v_cvt_pk_bf16_f32 v121, v118, v119
	v_add_f32_e32 v112, v124, v112
	v_lshlrev_b32_e32 v118, 2, v113
	ds_bpermute_b32 v113, v118, v112
	v_cmp_lt_i32_e32 vcc, v207, v206
	v_cvt_pk_bf16_f32 v123, v114, v115
	global_store_dwordx4 v[186:187], v[120:123], off offset:256
	s_waitcnt lgkmcnt(0)
	v_add_f32_e32 v112, v112, v113
	v_cndmask_b32_e32 v113, v204, v207, vcc
	v_lshlrev_b32_e32 v119, 2, v113
	ds_bpermute_b32 v113, v119, v112
	s_and_saveexec_b64 s[24:25], s[6:7]
	s_cbranch_execz .LBB0_410
	s_waitcnt lgkmcnt(0)
	v_add_f32_e32 v112, v112, v113
	s_mov_b64 s[26:27], -1
	s_and_b64 vcc, exec, s[12:13]
	s_cbranch_vccz .LBB0_408
	v_readlane_b32 s26, v250, 59
	v_lshlrev_b64 v[114:115], 5, v[156:157]
	v_readlane_b32 s27, v250, 60
	s_nop 1
	v_lshl_add_u64 v[114:115], s[26:27], 0, v[114:115]
	v_lshl_add_u64 v[114:115], s[14:15], 2, v[114:115]
	global_atomic_add_f32 v[114:115], v112, off
	s_mov_b64 s[26:27], 0

; DEV bf16x8 pack8(f32x4 a, f32x4 b) { u32x4 w; w.x = cvt_pk_bf16(a[0], a[1]); w.y = cvt_pk_bf16(a[2], a[3]); w.z = cvt_pk_bf16(b[0], b[1]); w.w = cvt_pk_bf16(b[2], b[3]); return __builtin_bit_cast(bf16x8, w); }
;     DEV void operator()(AccRef acc, const pg8::Unit& u, int wr, int wc, int fr, int fq) const {
;     ...
;         for (int am = 0; am < 4; ++am) { const int ai = am >> 1, m0 = (am & 1) * 2;
;             f32x4 bv[4][2][2];
; #pragma unroll
;             for (int m = m0; m < m0 + 2; ++m)
; #pragma unroll
;                 for (int bj = 0; bj < 2; ++bj)
; #pragma unroll
;                     for (int n = 0; n < 2; ++n) bv[m][bj][n] = *(const f32x4*)(base + (size_t)(row0 + ai * 128 + m * 16) * 2048 + col0 + bj * 128 + n * 4);
; #pragma unroll
;             for (int m = m0; m < m0 + 2; ++m) { const size_t off = (size_t)(row0 + ai * 128 + m * 16) * 2048 + col0; float sq = 0.f;
; #pragma unroll
;                 for (int bj = 0; bj < 2; ++bj) { const f32x4 o0 = bv[m][bj][0] + scale * acc[ai][bj][m][0], o1 = bv[m][bj][1] + scale * acc[ai][bj][m][1];
;                     *(f32x4*)(out + off + bj * 128) = o0; *(f32x4*)(out + off + bj * 128 + 4) = o1;
;                     if (xb) { *(u32x4*)(xb + off + bj * 128) = __builtin_bit_cast(u32x4, pack8(o0, o1));
;                         sq += (o0[0] * o0[0] + o0[1] * o0[1] + o0[2] * o0[2] + o0[3] * o0[3]) + (o1[0] * o1[0] + o1[1] * o1[1] + o1[2] * o1[2] + o1[3] * o1[3]); } }
;                 if (ssout) { sq += __shfl_xor(sq, 16); sq += __shfl_xor(sq, 32);
;                     if (fq == 0) { if (red) red[(ai * 128 + wr * 64 + m * 16 + fr) * 4 + wc] = sq; else atomicAdd(ssout + (size_t)(row0 + ai * 128 + m * 16) * 8 + u.pn, sq); } } }
.LBB0_415:
	s_or_b64 exec, exec, s[24:25]
	v_or_b32_e32 v116, 32, v156
	v_ashrrev_i32_e32 v117, 31, v116
	s_waitcnt lgkmcnt(0)
	v_lshlrev_b64 v[96:97], 13, v[116:117]
	v_lshl_add_u64 v[136:137], v[158:159], 0, v[96:97]
	v_mov_b32_e32 v120, v218
	v_mov_b32_e32 v121, v219
	v_mov_b32_e32 v122, v220
	v_mov_b32_e32 v123, v221
	v_mov_b32_e32 v124, v222
	v_mov_b32_e32 v125, v223
	v_mov_b32_e32 v126, v224
	v_mov_b32_e32 v127, v225
	v_mov_b32_e32 v128, v226
	v_mov_b32_e32 v129, v227
	v_mov_b32_e32 v130, v228
	v_mov_b32_e32 v131, v229
	v_mov_b32_e32 v132, v230
	v_mov_b32_e32 v133, v231
	v_mov_b32_e32 v134, v232
	v_mov_b32_e32 v135, v233
	v_or_b32_e32 v112, 48, v156
	v_ashrrev_i32_e32 v113, 31, v112
	v_lshlrev_b64 v[96:97], 13, v[112:113]
	v_lshl_add_u64 v[114:115], v[158:159], 0, v[96:97]
	v_mov_b32_e32 v104, v234
	v_mov_b32_e32 v105, v235
	v_mov_b32_e32 v106, v236
	v_mov_b32_e32 v107, v237
	v_mov_b32_e32 v108, v238
	v_mov_b32_e32 v109, v239
	v_mov_b32_e32 v110, v240
	v_mov_b32_e32 v111, v241
	v_mov_b32_e32 v96, v242
	v_mov_b32_e32 v97, v243
	v_mov_b32_e32 v98, v244
	v_mov_b32_e32 v99, v245
	v_mov_b32_e32 v100, v246
	v_mov_b32_e32 v101, v247
	v_mov_b32_e32 v102, v248
	v_mov_b32_e32 v103, v249
	v_readlane_b32 s24, v254, 16
	v_readlane_b32 s25, v254, 17
	v_add_u32_e32 v255, 128, v156
	v_lshlrev_b32_e32 v255, 13, v255
	v_lshl_add_u32 v255, v154, 2, v255
	s_nop 1
	global_load_dwordx4 v[218:221], v255, s[24:25]
	global_load_dwordx4 v[222:225], v255, s[24:25] offset:16
	global_load_dwordx4 v[226:229], v255, s[24:25] offset:512
	global_load_dwordx4 v[230:233], v255, s[24:25] offset:528
	v_add_u32_e32 v255, 144, v156
	v_lshlrev_b32_e32 v255, 13, v255
	v_lshl_add_u32 v255, v154, 2, v255
	global_load_dwordx4 v[234:237], v255, s[24:25] offset:16
	global_load_dwordx4 v[238:241], v255, s[24:25]
	global_load_dwordx4 v[242:245], v255, s[24:25] offset:528
	global_load_dwordx4 v[246:249], v255, s[24:25] offset:512
	v_lshlrev_b64 v[138:139], 11, v[116:117]
	v_readlane_b32 s24, v250, 9
	v_lshl_add_u64 v[138:139], v[138:139], 0, v[154:155]
	v_readlane_b32 s25, v250, 10
	v_pk_add_f32 v[94:95], v[94:95], v[122:123]
	v_pk_add_f32 v[92:93], v[92:93], v[120:121]
	v_pk_add_f32 v[88:89], v[88:89], v[124:125]
	v_pk_add_f32 v[84:85], v[84:85], v[128:129]
	v_pk_add_f32 v[120:121], v[80:81], v[132:133]
	v_pk_add_f32 v[90:91], v[90:91], v[126:127]
	v_pk_add_f32 v[122:123], v[82:83], v[134:135]
	global_store_dwordx4 v[136:137], v[92:95], off
	global_store_dwordx4 v[136:137], v[88:91], off offset:16
	v_cvt_pk_bf16_f32 v80, v92, v93
	v_cvt_pk_bf16_f32 v82, v88, v89
	v_mul_f32_e32 v93, v93, v93
	v_mul_f32_e32 v89, v89, v89
	v_mul_f32_e32 v124, v85, v85
	v_mul_f32_e32 v125, v121, v121
	v_pk_add_f32 v[86:87], v[86:87], v[130:131]
	v_fmac_f32_e32 v93, v92, v92
	v_fmac_f32_e32 v89, v88, v88
	v_fmac_f32_e32 v124, v84, v84
	v_fmac_f32_e32 v125, v120, v120
	v_fmac_f32_e32 v93, v94, v94
	v_fmac_f32_e32 v89, v90, v90
	v_fmac_f32_e32 v124, v86, v86
	v_fmac_f32_e32 v125, v122, v122
	v_fmac_f32_e32 v93, v95, v95
	v_fmac_f32_e32 v89, v91, v91
	v_fmac_f32_e32 v124, v87, v87
	v_fmac_f32_e32 v125, v123, v123
	v_add_f32_e32 v88, v93, v89
	v_add_f32_e32 v89, v124, v125
	v_add_f32_e32 v88, v88, v89
	ds_bpermute_b32 v89, v118, v88
	v_lshl_add_u64 v[138:139], v[138:139], 1, s[24:25]
	v_cvt_pk_bf16_f32 v81, v94, v95
	v_cvt_pk_bf16_f32 v83, v90, v91
	global_store_dwordx4 v[138:139], v[80:83], off
	global_store_dwordx4 v[136:137], v[84:87], off offset:512
	global_store_dwordx4 v[136:137], v[120:123], off offset:528
	s_waitcnt lgkmcnt(0)
	v_add_f32_e32 v80, v88, v89
	ds_bpermute_b32 v81, v119, v80
	v_cvt_pk_bf16_f32 v82, v84, v85
	v_cvt_pk_bf16_f32 v83, v86, v87
	v_cvt_pk_bf16_f32 v84, v120, v121
	v_cvt_pk_bf16_f32 v85, v122, v123
	global_store_dwordx4 v[138:139], v[82:85], off offset:256
	s_and_saveexec_b64 s[24:25], s[6:7]
	s_cbranch_execz .LBB0_420
	s_waitcnt lgkmcnt(0)
	v_add_f32_e32 v80, v80, v81
	s_mov_b64 s[26:27], -1
	s_and_b64 vcc, exec, s[12:13]
	s_cbranch_vccz .LBB0_418
	v_readlane_b32 s26, v250, 59
	v_lshlrev_b64 v[82:83], 5, v[116:117]
	v_readlane_b32 s27, v250, 60
	s_nop 1
	v_lshl_add_u64 v[82:83], s[26:27], 0, v[82:83]
	v_lshl_add_u64 v[82:83], s[14:15], 2, v[82:83]
	global_atomic_add_f32 v[82:83], v80, off
	s_mov_b64 s[26:27], 0

; DEV bf16x8 pack8(f32x4 a, f32x4 b) { u32x4 w; w.x = cvt_pk_bf16(a[0], a[1]); w.y = cvt_pk_bf16(a[2], a[3]); w.z = cvt_pk_bf16(b[0], b[1]); w.w = cvt_pk_bf16(b[2], b[3]); return __builtin_bit_cast(bf16x8, w); }
;     DEV void operator()(AccRef acc, const pg8::Unit& u, int wr, int wc, int fr, int fq) const {
;     ...
;             for (int m = m0; m < m0 + 2; ++m) { const size_t off = (size_t)(row0 + ai * 128 + m * 16) * 2048 + col0; float sq = 0.f;
; #pragma unroll
;                 for (int bj = 0; bj < 2; ++bj) { const f32x4 o0 = bv[m][bj][0] + scale * acc[ai][bj][m][0], o1 = bv[m][bj][1] + scale * acc[ai][bj][m][1];
;                     *(f32x4*)(out + off + bj * 128) = o0; *(f32x4*)(out + off + bj * 128 + 4) = o1;
;                     if (xb) { *(u32x4*)(xb + off + bj * 128) = __builtin_bit_cast(u32x4, pack8(o0, o1));
;                         sq += (o0[0] * o0[0] + o0[1] * o0[1] + o0[2] * o0[2] + o0[3] * o0[3]) + (o1[0] * o1[0] + o1[1] * o1[1] + o1[2] * o1[2] + o1[3] * o1[3]); } }
;                 if (ssout) { sq += __shfl_xor(sq, 16); sq += __shfl_xor(sq, 32);
;                     if (fq == 0) { if (red) red[(ai * 128 + wr * 64 + m * 16 + fr) * 4 + wc] = sq; else atomicAdd(ssout + (size_t)(row0 + ai * 128 + m * 16) * 8 + u.pn, sq); } } }
.LBB0_420:
	s_or_b64 exec, exec, s[24:25]
	s_waitcnt lgkmcnt(0)
	v_lshlrev_b64 v[80:81], 11, v[112:113]
	v_pk_add_f32 v[78:79], v[78:79], v[110:111]
	v_pk_add_f32 v[76:77], v[76:77], v[108:109]
	v_pk_add_f32 v[72:73], v[72:73], v[104:105]
	v_lshl_add_u64 v[84:85], v[80:81], 0, v[154:155]
	v_pk_add_f32 v[74:75], v[74:75], v[106:107]
	global_store_dwordx4 v[114:115], v[76:79], off
	global_store_dwordx4 v[114:115], v[72:75], off offset:16
	v_cvt_pk_bf16_f32 v80, v76, v77
	v_cvt_pk_bf16_f32 v82, v72, v73
	v_mul_f32_e32 v77, v77, v77
	v_mul_f32_e32 v73, v73, v73
	v_fmac_f32_e32 v77, v76, v76
	v_fmac_f32_e32 v73, v72, v72
	v_fmac_f32_e32 v77, v78, v78
	v_fmac_f32_e32 v73, v74, v74
	v_fmac_f32_e32 v77, v79, v79
	v_fmac_f32_e32 v73, v75, v75
	v_add_f32_e32 v76, v77, v73
	v_pk_add_f32 v[68:69], v[68:69], v[100:101]
	v_pk_add_f32 v[72:73], v[64:65], v[96:97]
	v_mul_f32_e32 v64, v69, v69
	v_mul_f32_e32 v65, v73, v73
	v_cvt_pk_bf16_f32 v83, v74, v75
	v_pk_add_f32 v[70:71], v[70:71], v[102:103]
	v_pk_add_f32 v[74:75], v[66:67], v[98:99]
	v_fmac_f32_e32 v64, v68, v68
	v_fmac_f32_e32 v65, v72, v72
	v_fmac_f32_e32 v64, v70, v70
	v_fmac_f32_e32 v65, v74, v74
	v_fmac_f32_e32 v64, v71, v71
	v_fmac_f32_e32 v65, v75, v75
	v_add_f32_e32 v64, v64, v65
	v_add_f32_e32 v64, v76, v64
	ds_bpermute_b32 v65, v118, v64
	v_readlane_b32 s24, v250, 9
	v_readlane_b32 s25, v250, 10
	v_cvt_pk_bf16_f32 v81, v78, v79
	v_cvt_pk_bf16_f32 v66, v68, v69
	s_waitcnt lgkmcnt(0)
	v_add_f32_e32 v64, v64, v65
	ds_bpermute_b32 v65, v119, v64
	v_lshl_add_u64 v[84:85], v[84:85], 1, s[24:25]
	global_store_dwordx4 v[84:85], v[80:83], off
	global_store_dwordx4 v[114:115], v[68:71], off offset:512
	global_store_dwordx4 v[114:115], v[72:75], off offset:528
	v_cvt_pk_bf16_f32 v67, v70, v71
	v_cvt_pk_bf16_f32 v68, v72, v73
	v_cvt_pk_bf16_f32 v69, v74, v75
	global_store_dwordx4 v[84:85], v[66:69], off offset:256
	s_and_saveexec_b64 s[24:25], s[6:7]
	s_cbranch_execz .LBB0_425
	s_waitcnt lgkmcnt(0)
	v_add_f32_e32 v64, v64, v65
	s_mov_b64 s[26:27], -1
	s_and_b64 vcc, exec, s[12:13]
	s_cbranch_vccz .LBB0_423
	v_readlane_b32 s26, v250, 59
	v_lshlrev_b64 v[66:67], 5, v[112:113]
	v_readlane_b32 s27, v250, 60
	s_nop 1
	v_lshl_add_u64 v[66:67], s[26:27], 0, v[66:67]
	v_lshl_add_u64 v[66:67], s[14:15], 2, v[66:67]
	global_atomic_add_f32 v[66:67], v64, off
	s_mov_b64 s[26:27], 0

; DEV bf16x8 pack8(f32x4 a, f32x4 b) { u32x4 w; w.x = cvt_pk_bf16(a[0], a[1]); w.y = cvt_pk_bf16(a[2], a[3]); w.z = cvt_pk_bf16(b[0], b[1]); w.w = cvt_pk_bf16(b[2], b[3]); return __builtin_bit_cast(bf16x8, w); }
;     DEV void operator()(AccRef acc, const pg8::Unit& u, int wr, int wc, int fr, int fq) const {
;     ...
;         for (int am = 0; am < 4; ++am) { const int ai = am >> 1, m0 = (am & 1) * 2;
;             f32x4 bv[4][2][2];
; #pragma unroll
;             for (int m = m0; m < m0 + 2; ++m)
; #pragma unroll
;                 for (int bj = 0; bj < 2; ++bj)
; #pragma unroll
;                     for (int n = 0; n < 2; ++n) bv[m][bj][n] = *(const f32x4*)(base + (size_t)(row0 + ai * 128 + m * 16) * 2048 + col0 + bj * 128 + n * 4);
; #pragma unroll
;             for (int m = m0; m < m0 + 2; ++m) { const size_t off = (size_t)(row0 + ai * 128 + m * 16) * 2048 + col0; float sq = 0.f;
; #pragma unroll
;                 for (int bj = 0; bj < 2; ++bj) { const f32x4 o0 = bv[m][bj][0] + scale * acc[ai][bj][m][0], o1 = bv[m][bj][1] + scale * acc[ai][bj][m][1];
;                     *(f32x4*)(out + off + bj * 128) = o0; *(f32x4*)(out + off + bj * 128 + 4) = o1;
;                     if (xb) { *(u32x4*)(xb + off + bj * 128) = __builtin_bit_cast(u32x4, pack8(o0, o1));
;                         sq += (o0[0] * o0[0] + o0[1] * o0[1] + o0[2] * o0[2] + o0[3] * o0[3]) + (o1[0] * o1[0] + o1[1] * o1[1] + o1[2] * o1[2] + o1[3] * o1[3]); } }
;                 if (ssout) { sq += __shfl_xor(sq, 16); sq += __shfl_xor(sq, 32);
;                     if (fq == 0) { if (red) red[(ai * 128 + wr * 64 + m * 16 + fr) * 4 + wc] = sq; else atomicAdd(ssout + (size_t)(row0 + ai * 128 + m * 16) * 8 + u.pn, sq); } } }
.LBB0_425:
	s_or_b64 exec, exec, s[24:25]
	v_add_u32_e32 v84, 0x80, v156
	v_ashrrev_i32_e32 v85, 31, v84
	s_waitcnt lgkmcnt(0)
	v_lshlrev_b64 v[64:65], 13, v[84:85]
	v_lshl_add_u64 v[102:103], v[158:159], 0, v[64:65]
	s_waitcnt vmcnt(4)
	v_mov_b32_e32 v86, v218
	v_mov_b32_e32 v87, v219
	v_mov_b32_e32 v88, v220
	v_mov_b32_e32 v89, v221
	v_mov_b32_e32 v90, v222
	v_mov_b32_e32 v91, v223
	v_mov_b32_e32 v92, v224
	v_mov_b32_e32 v93, v225
	v_mov_b32_e32 v94, v226
	v_mov_b32_e32 v95, v227
	v_mov_b32_e32 v96, v228
	v_mov_b32_e32 v97, v229
	v_mov_b32_e32 v98, v230
	v_mov_b32_e32 v99, v231
	v_mov_b32_e32 v100, v232
	v_mov_b32_e32 v101, v233
	v_add_u32_e32 v80, 0x90, v156
	v_ashrrev_i32_e32 v81, 31, v80
	v_lshlrev_b64 v[64:65], 13, v[80:81]
	v_lshl_add_u64 v[82:83], v[158:159], 0, v[64:65]
	v_mov_b32_e32 v72, v234
	v_mov_b32_e32 v73, v235
	v_mov_b32_e32 v74, v236
	v_mov_b32_e32 v75, v237
	v_mov_b32_e32 v76, v238
	v_mov_b32_e32 v77, v239
	v_mov_b32_e32 v78, v240
	v_mov_b32_e32 v79, v241
	v_mov_b32_e32 v64, v242
	v_mov_b32_e32 v65, v243
	v_mov_b32_e32 v66, v244
	v_mov_b32_e32 v67, v245
	v_mov_b32_e32 v68, v246
	v_mov_b32_e32 v69, v247
	v_mov_b32_e32 v70, v248
	v_mov_b32_e32 v71, v249
	v_readlane_b32 s24, v254, 16
	v_readlane_b32 s25, v254, 17
	v_add_u32_e32 v255, 160, v156
	v_lshlrev_b32_e32 v255, 13, v255
	v_lshl_add_u32 v255, v154, 2, v255
	s_nop 1
	global_load_dwordx4 v[218:221], v255, s[24:25]
	global_load_dwordx4 v[222:225], v255, s[24:25] offset:16
	global_load_dwordx4 v[226:229], v255, s[24:25] offset:512
	global_load_dwordx4 v[230:233], v255, s[24:25] offset:528
	v_add_u32_e32 v255, 176, v156
	v_lshlrev_b32_e32 v255, 13, v255
	v_lshl_add_u32 v255, v154, 2, v255
	global_load_dwordx4 v[234:237], v255, s[24:25] offset:16
	global_load_dwordx4 v[238:241], v255, s[24:25]
	global_load_dwordx4 v[242:245], v255, s[24:25] offset:528
	global_load_dwordx4 v[246:249], v255, s[24:25] offset:512
	v_lshlrev_b64 v[104:105], 11, v[84:85]
	v_readlane_b32 s24, v250, 9
	v_lshl_add_u64 v[104:105], v[104:105], 0, v[154:155]
	v_readlane_b32 s25, v250, 10
	v_pk_add_f32 v[62:63], v[62:63], v[88:89]
	v_pk_add_f32 v[60:61], v[60:61], v[86:87]
	v_pk_add_f32 v[56:57], v[56:57], v[90:91]
	v_pk_add_f32 v[52:53], v[52:53], v[94:95]
	v_pk_add_f32 v[86:87], v[48:49], v[98:99]
	v_pk_add_f32 v[58:59], v[58:59], v[92:93]
	v_pk_add_f32 v[88:89], v[50:51], v[100:101]
	global_store_dwordx4 v[102:103], v[60:63], off
	global_store_dwordx4 v[102:103], v[56:59], off offset:16
	v_cvt_pk_bf16_f32 v48, v60, v61
	v_cvt_pk_bf16_f32 v50, v56, v57
	v_mul_f32_e32 v61, v61, v61
	v_mul_f32_e32 v57, v57, v57
	v_mul_f32_e32 v90, v53, v53
	v_mul_f32_e32 v91, v87, v87
	v_pk_add_f32 v[54:55], v[54:55], v[96:97]
	v_fmac_f32_e32 v61, v60, v60
	v_fmac_f32_e32 v57, v56, v56
	v_fmac_f32_e32 v90, v52, v52
	v_fmac_f32_e32 v91, v86, v86
	v_fmac_f32_e32 v61, v62, v62
	v_fmac_f32_e32 v57, v58, v58
	v_fmac_f32_e32 v90, v54, v54
	v_fmac_f32_e32 v91, v88, v88
	v_fmac_f32_e32 v61, v63, v63
	v_fmac_f32_e32 v57, v59, v59
	v_fmac_f32_e32 v90, v55, v55
	v_fmac_f32_e32 v91, v89, v89
	v_add_f32_e32 v56, v61, v57
	v_add_f32_e32 v57, v90, v91
	v_add_f32_e32 v56, v56, v57
	ds_bpermute_b32 v57, v118, v56
	v_lshl_add_u64 v[104:105], v[104:105], 1, s[24:25]
	v_cvt_pk_bf16_f32 v49, v62, v63
	v_cvt_pk_bf16_f32 v51, v58, v59
	global_store_dwordx4 v[104:105], v[48:51], off
	global_store_dwordx4 v[102:103], v[52:55], off offset:512
	global_store_dwordx4 v[102:103], v[86:89], off offset:528
	s_waitcnt lgkmcnt(0)
	v_add_f32_e32 v48, v56, v57
	ds_bpermute_b32 v49, v119, v48
	v_cvt_pk_bf16_f32 v50, v52, v53
	v_cvt_pk_bf16_f32 v51, v54, v55
	v_cvt_pk_bf16_f32 v52, v86, v87
	v_cvt_pk_bf16_f32 v53, v88, v89
	global_store_dwordx4 v[104:105], v[50:53], off offset:256
	s_and_saveexec_b64 s[24:25], s[6:7]
	s_cbranch_execz .LBB0_430
	s_waitcnt lgkmcnt(0)
	v_add_f32_e32 v48, v48, v49
	s_mov_b64 s[26:27], -1
	s_and_b64 vcc, exec, s[12:13]
	s_cbranch_vccz .LBB0_428
	v_readlane_b32 s26, v250, 59
	v_lshlrev_b64 v[50:51], 5, v[84:85]
	v_readlane_b32 s27, v250, 60
	s_nop 1
	v_lshl_add_u64 v[50:51], s[26:27], 0, v[50:51]
	v_lshl_add_u64 v[50:51], s[14:15], 2, v[50:51]
	global_atomic_add_f32 v[50:51], v48, off
	s_mov_b64 s[26:27], 0

; DEV bf16x8 pack8(f32x4 a, f32x4 b) { u32x4 w; w.x = cvt_pk_bf16(a[0], a[1]); w.y = cvt_pk_bf16(a[2], a[3]); w.z = cvt_pk_bf16(b[0], b[1]); w.w = cvt_pk_bf16(b[2], b[3]); return __builtin_bit_cast(bf16x8, w); }
;     DEV void operator()(AccRef acc, const pg8::Unit& u, int wr, int wc, int fr, int fq) const {
;     ...
;             for (int m = m0; m < m0 + 2; ++m) { const size_t off = (size_t)(row0 + ai * 128 + m * 16) * 2048 + col0; float sq = 0.f;
; #pragma unroll
;                 for (int bj = 0; bj < 2; ++bj) { const f32x4 o0 = bv[m][bj][0] + scale * acc[ai][bj][m][0], o1 = bv[m][bj][1] + scale * acc[ai][bj][m][1];
;                     *(f32x4*)(out + off + bj * 128) = o0; *(f32x4*)(out + off + bj * 128 + 4) = o1;
;                     if (xb) { *(u32x4*)(xb + off + bj * 128) = __builtin_bit_cast(u32x4, pack8(o0, o1));
;                         sq += (o0[0] * o0[0] + o0[1] * o0[1] + o0[2] * o0[2] + o0[3] * o0[3]) + (o1[0] * o1[0] + o1[1] * o1[1] + o1[2] * o1[2] + o1[3] * o1[3]); } }
;                 if (ssout) { sq += __shfl_xor(sq, 16); sq += __shfl_xor(sq, 32);
;                     if (fq == 0) { if (red) red[(ai * 128 + wr * 64 + m * 16 + fr) * 4 + wc] = sq; else atomicAdd(ssout + (size_t)(row0 + ai * 128 + m * 16) * 8 + u.pn, sq); } } }
.LBB0_430:
	s_or_b64 exec, exec, s[24:25]
	s_waitcnt lgkmcnt(0)
	v_lshlrev_b64 v[48:49], 11, v[80:81]
	v_pk_add_f32 v[46:47], v[46:47], v[78:79]
	v_pk_add_f32 v[44:45], v[44:45], v[76:77]
	v_pk_add_f32 v[40:41], v[40:41], v[72:73]
	v_lshl_add_u64 v[52:53], v[48:49], 0, v[154:155]
	v_pk_add_f32 v[42:43], v[42:43], v[74:75]
	global_store_dwordx4 v[82:83], v[44:47], off
	global_store_dwordx4 v[82:83], v[40:43], off offset:16
	v_cvt_pk_bf16_f32 v48, v44, v45
	v_cvt_pk_bf16_f32 v50, v40, v41
	v_mul_f32_e32 v45, v45, v45
	v_mul_f32_e32 v41, v41, v41
	v_fmac_f32_e32 v45, v44, v44
	v_fmac_f32_e32 v41, v40, v40
	v_fmac_f32_e32 v45, v46, v46
	v_fmac_f32_e32 v41, v42, v42
	v_fmac_f32_e32 v45, v47, v47
	v_fmac_f32_e32 v41, v43, v43
	v_add_f32_e32 v44, v45, v41
	v_pk_add_f32 v[36:37], v[36:37], v[68:69]
	v_pk_add_f32 v[40:41], v[32:33], v[64:65]
	v_mul_f32_e32 v32, v37, v37
	v_mul_f32_e32 v33, v41, v41
	v_cvt_pk_bf16_f32 v51, v42, v43
	v_pk_add_f32 v[38:39], v[38:39], v[70:71]
	v_pk_add_f32 v[42:43], v[34:35], v[66:67]
	v_fmac_f32_e32 v32, v36, v36
	v_fmac_f32_e32 v33, v40, v40
	v_fmac_f32_e32 v32, v38, v38
	v_fmac_f32_e32 v33, v42, v42
	v_fmac_f32_e32 v32, v39, v39
	v_fmac_f32_e32 v33, v43, v43
	v_add_f32_e32 v32, v32, v33
	v_add_f32_e32 v32, v44, v32
	ds_bpermute_b32 v33, v118, v32
	v_readlane_b32 s24, v250, 9
	v_readlane_b32 s25, v250, 10
	v_cvt_pk_bf16_f32 v49, v46, v47
	v_cvt_pk_bf16_f32 v34, v36, v37
	s_waitcnt lgkmcnt(0)
	v_add_f32_e32 v32, v32, v33
	ds_bpermute_b32 v33, v119, v32
	v_lshl_add_u64 v[52:53], v[52:53], 1, s[24:25]
	global_store_dwordx4 v[52:53], v[48:51], off
	global_store_dwordx4 v[82:83], v[36:39], off offset:512
	global_store_dwordx4 v[82:83], v[40:43], off offset:528
	v_cvt_pk_bf16_f32 v35, v38, v39
	v_cvt_pk_bf16_f32 v36, v40, v41
	v_cvt_pk_bf16_f32 v37, v42, v43
	global_store_dwordx4 v[52:53], v[34:37], off offset:256
	s_and_saveexec_b64 s[24:25], s[6:7]
	s_cbranch_execz .LBB0_435
	s_waitcnt lgkmcnt(0)
	v_add_f32_e32 v32, v32, v33
	s_mov_b64 s[26:27], -1
	s_and_b64 vcc, exec, s[12:13]
	s_cbranch_vccz .LBB0_433
	v_readlane_b32 s26, v250, 59
	v_lshlrev_b64 v[34:35], 5, v[80:81]
	v_readlane_b32 s27, v250, 60
	s_nop 1
	v_lshl_add_u64 v[34:35], s[26:27], 0, v[34:35]
	v_lshl_add_u64 v[34:35], s[14:15], 2, v[34:35]
	global_atomic_add_f32 v[34:35], v32, off
	s_mov_b64 s[26:27], 0

; DEV bf16x8 pack8(f32x4 a, f32x4 b) { u32x4 w; w.x = cvt_pk_bf16(a[0], a[1]); w.y = cvt_pk_bf16(a[2], a[3]); w.z = cvt_pk_bf16(b[0], b[1]); w.w = cvt_pk_bf16(b[2], b[3]); return __builtin_bit_cast(bf16x8, w); }
;     DEV void operator()(AccRef acc, const pg8::Unit& u, int wr, int wc, int fr, int fq) const {
;     ...
;         for (int am = 0; am < 4; ++am) { const int ai = am >> 1, m0 = (am & 1) * 2;
;             f32x4 bv[4][2][2];
; #pragma unroll
;             for (int m = m0; m < m0 + 2; ++m)
; #pragma unroll
;                 for (int bj = 0; bj < 2; ++bj)
; #pragma unroll
;                     for (int n = 0; n < 2; ++n) bv[m][bj][n] = *(const f32x4*)(base + (size_t)(row0 + ai * 128 + m * 16) * 2048 + col0 + bj * 128 + n * 4);
; #pragma unroll
;             for (int m = m0; m < m0 + 2; ++m) { const size_t off = (size_t)(row0 + ai * 128 + m * 16) * 2048 + col0; float sq = 0.f;
; #pragma unroll
;                 for (int bj = 0; bj < 2; ++bj) { const f32x4 o0 = bv[m][bj][0] + scale * acc[ai][bj][m][0], o1 = bv[m][bj][1] + scale * acc[ai][bj][m][1];
;                     *(f32x4*)(out + off + bj * 128) = o0; *(f32x4*)(out + off + bj * 128 + 4) = o1;
;                     if (xb) { *(u32x4*)(xb + off + bj * 128) = __builtin_bit_cast(u32x4, pack8(o0, o1));
;                         sq += (o0[0] * o0[0] + o0[1] * o0[1] + o0[2] * o0[2] + o0[3] * o0[3]) + (o1[0] * o1[0] + o1[1] * o1[1] + o1[2] * o1[2] + o1[3] * o1[3]); } }
;                 if (ssout) { sq += __shfl_xor(sq, 16); sq += __shfl_xor(sq, 32);
;                     if (fq == 0) { if (red) red[(ai * 128 + wr * 64 + m * 16 + fr) * 4 + wc] = sq; else atomicAdd(ssout + (size_t)(row0 + ai * 128 + m * 16) * 8 + u.pn, sq); } } }
.LBB0_435:
	s_or_b64 exec, exec, s[24:25]
	v_add_u32_e32 v52, 0xa0, v156
	v_ashrrev_i32_e32 v53, 31, v52
	s_waitcnt lgkmcnt(0)
	v_lshlrev_b64 v[32:33], 13, v[52:53]
	v_lshl_add_u64 v[70:71], v[158:159], 0, v[32:33]
	s_waitcnt vmcnt(4)
	v_mov_b32_e32 v54, v218
	v_mov_b32_e32 v55, v219
	v_mov_b32_e32 v56, v220
	v_mov_b32_e32 v57, v221
	v_mov_b32_e32 v58, v222
	v_mov_b32_e32 v59, v223
	v_mov_b32_e32 v60, v224
	v_mov_b32_e32 v61, v225
	v_mov_b32_e32 v62, v226
	v_mov_b32_e32 v63, v227
	v_mov_b32_e32 v64, v228
	v_mov_b32_e32 v65, v229
	v_mov_b32_e32 v66, v230
	v_mov_b32_e32 v67, v231
	v_mov_b32_e32 v68, v232
	v_mov_b32_e32 v69, v233
	v_add_u32_e32 v48, 0xb0, v156
	v_ashrrev_i32_e32 v49, 31, v48
	v_lshlrev_b64 v[32:33], 13, v[48:49]
	v_lshl_add_u64 v[50:51], v[158:159], 0, v[32:33]
	v_mov_b32_e32 v40, v234
	v_mov_b32_e32 v41, v235
	v_mov_b32_e32 v42, v236
	v_mov_b32_e32 v43, v237
	v_mov_b32_e32 v44, v238
	v_mov_b32_e32 v45, v239
	v_mov_b32_e32 v46, v240
	v_mov_b32_e32 v47, v241
	v_mov_b32_e32 v32, v242
	v_mov_b32_e32 v33, v243
	v_mov_b32_e32 v34, v244
	v_mov_b32_e32 v35, v245
	v_mov_b32_e32 v36, v246
	v_mov_b32_e32 v37, v247
	v_mov_b32_e32 v38, v248
	v_mov_b32_e32 v39, v249
	v_lshlrev_b64 v[72:73], 11, v[52:53]
	v_readlane_b32 s24, v250, 9
	v_lshl_add_u64 v[72:73], v[72:73], 0, v[154:155]
	v_readlane_b32 s25, v250, 10
	v_pk_add_f32 v[30:31], v[30:31], v[56:57]
	v_pk_add_f32 v[28:29], v[28:29], v[54:55]
	v_pk_add_f32 v[24:25], v[24:25], v[58:59]
	v_pk_add_f32 v[20:21], v[20:21], v[62:63]
	v_pk_add_f32 v[54:55], v[16:17], v[66:67]
	v_pk_add_f32 v[26:27], v[26:27], v[60:61]
	v_pk_add_f32 v[56:57], v[18:19], v[68:69]
	global_store_dwordx4 v[70:71], v[28:31], off
	global_store_dwordx4 v[70:71], v[24:27], off offset:16
	v_cvt_pk_bf16_f32 v16, v28, v29
	v_cvt_pk_bf16_f32 v18, v24, v25
	v_mul_f32_e32 v29, v29, v29
	v_mul_f32_e32 v25, v25, v25
	v_mul_f32_e32 v58, v21, v21
	v_mul_f32_e32 v59, v55, v55
	v_pk_add_f32 v[22:23], v[22:23], v[64:65]
	v_fmac_f32_e32 v29, v28, v28
	v_fmac_f32_e32 v25, v24, v24
	v_fmac_f32_e32 v58, v20, v20
	v_fmac_f32_e32 v59, v54, v54
	v_fmac_f32_e32 v29, v30, v30
	v_fmac_f32_e32 v25, v26, v26
	v_fmac_f32_e32 v58, v22, v22
	v_fmac_f32_e32 v59, v56, v56
	v_fmac_f32_e32 v29, v31, v31
	v_fmac_f32_e32 v25, v27, v27
	v_fmac_f32_e32 v58, v23, v23
	v_fmac_f32_e32 v59, v57, v57
	v_add_f32_e32 v24, v29, v25
	v_add_f32_e32 v25, v58, v59
	v_add_f32_e32 v24, v24, v25
	ds_bpermute_b32 v25, v118, v24
	v_lshl_add_u64 v[72:73], v[72:73], 1, s[24:25]
	v_cvt_pk_bf16_f32 v17, v30, v31
	v_cvt_pk_bf16_f32 v19, v26, v27
	global_store_dwordx4 v[72:73], v[16:19], off
	global_store_dwordx4 v[70:71], v[20:23], off offset:512
	global_store_dwordx4 v[70:71], v[54:57], off offset:528
	s_waitcnt lgkmcnt(0)
	v_add_f32_e32 v16, v24, v25
	ds_bpermute_b32 v17, v119, v16
	v_cvt_pk_bf16_f32 v18, v20, v21
	v_cvt_pk_bf16_f32 v19, v22, v23
	v_cvt_pk_bf16_f32 v20, v54, v55
	v_cvt_pk_bf16_f32 v21, v56, v57
	global_store_dwordx4 v[72:73], v[18:21], off offset:256
	s_and_saveexec_b64 s[24:25], s[6:7]
	s_cbranch_execz .LBB0_440
	s_waitcnt lgkmcnt(0)
	v_add_f32_e32 v16, v16, v17
	s_mov_b64 s[26:27], -1
	s_and_b64 vcc, exec, s[12:13]
	s_cbranch_vccz .LBB0_438
	v_readlane_b32 s26, v250, 59
	v_lshlrev_b64 v[18:19], 5, v[52:53]
	v_readlane_b32 s27, v250, 60
	s_nop 1
	v_lshl_add_u64 v[18:19], s[26:27], 0, v[18:19]
	v_lshl_add_u64 v[18:19], s[14:15], 2, v[18:19]
	global_atomic_add_f32 v[18:19], v16, off
	s_mov_b64 s[26:27], 0

; DEV bf16x8 pack8(f32x4 a, f32x4 b) { u32x4 w; w.x = cvt_pk_bf16(a[0], a[1]); w.y = cvt_pk_bf16(a[2], a[3]); w.z = cvt_pk_bf16(b[0], b[1]); w.w = cvt_pk_bf16(b[2], b[3]); return __builtin_bit_cast(bf16x8, w); }
;     DEV void operator()(AccRef acc, const pg8::Unit& u, int wr, int wc, int fr, int fq) const {
;     ...
;             for (int m = m0; m < m0 + 2; ++m) { const size_t off = (size_t)(row0 + ai * 128 + m * 16) * 2048 + col0; float sq = 0.f;
; #pragma unroll
;                 for (int bj = 0; bj < 2; ++bj) { const f32x4 o0 = bv[m][bj][0] + scale * acc[ai][bj][m][0], o1 = bv[m][bj][1] + scale * acc[ai][bj][m][1];
;                     *(f32x4*)(out + off + bj * 128) = o0; *(f32x4*)(out + off + bj * 128 + 4) = o1;
;                     if (xb) { *(u32x4*)(xb + off + bj * 128) = __builtin_bit_cast(u32x4, pack8(o0, o1));
;                         sq += (o0[0] * o0[0] + o0[1] * o0[1] + o0[2] * o0[2] + o0[3] * o0[3]) + (o1[0] * o1[0] + o1[1] * o1[1] + o1[2] * o1[2] + o1[3] * o1[3]); } }
;                 if (ssout) { sq += __shfl_xor(sq, 16); sq += __shfl_xor(sq, 32);
;                     if (fq == 0) { if (red) red[(ai * 128 + wr * 64 + m * 16 + fr) * 4 + wc] = sq; else atomicAdd(ssout + (size_t)(row0 + ai * 128 + m * 16) * 8 + u.pn, sq); } } }
.LBB0_440:
	s_or_b64 exec, exec, s[24:25]
	s_waitcnt lgkmcnt(0)
	v_lshlrev_b64 v[16:17], 11, v[48:49]
	v_pk_add_f32 v[14:15], v[14:15], v[46:47]
	v_pk_add_f32 v[12:13], v[12:13], v[44:45]
	v_pk_add_f32 v[8:9], v[8:9], v[40:41]
	v_lshl_add_u64 v[20:21], v[16:17], 0, v[154:155]
	v_pk_add_f32 v[10:11], v[10:11], v[42:43]
	global_store_dwordx4 v[50:51], v[12:15], off
	global_store_dwordx4 v[50:51], v[8:11], off offset:16
	v_cvt_pk_bf16_f32 v16, v12, v13
	v_cvt_pk_bf16_f32 v18, v8, v9
	v_mul_f32_e32 v13, v13, v13
	v_mul_f32_e32 v9, v9, v9
	v_fmac_f32_e32 v13, v12, v12
	v_fmac_f32_e32 v9, v8, v8
	v_fmac_f32_e32 v13, v14, v14
	v_fmac_f32_e32 v9, v10, v10
	v_fmac_f32_e32 v13, v15, v15
	v_fmac_f32_e32 v9, v11, v11
	v_add_f32_e32 v12, v13, v9
	v_pk_add_f32 v[4:5], v[4:5], v[36:37]
	v_pk_add_f32 v[8:9], v[0:1], v[32:33]
	v_mul_f32_e32 v0, v5, v5
	v_mul_f32_e32 v1, v9, v9
	v_cvt_pk_bf16_f32 v19, v10, v11
	v_pk_add_f32 v[6:7], v[6:7], v[38:39]
	v_pk_add_f32 v[10:11], v[2:3], v[34:35]
	v_fmac_f32_e32 v0, v4, v4
	v_fmac_f32_e32 v1, v8, v8
	v_fmac_f32_e32 v0, v6, v6
	v_fmac_f32_e32 v1, v10, v10
	v_fmac_f32_e32 v0, v7, v7
	v_fmac_f32_e32 v1, v11, v11
	v_add_f32_e32 v0, v0, v1
	v_add_f32_e32 v0, v12, v0
	ds_bpermute_b32 v1, v118, v0
	v_readlane_b32 s24, v250, 9
	v_readlane_b32 s25, v250, 10
	v_cvt_pk_bf16_f32 v17, v14, v15
	v_cvt_pk_bf16_f32 v2, v4, v5
	s_waitcnt lgkmcnt(0)
	v_add_f32_e32 v0, v0, v1
	ds_bpermute_b32 v1, v119, v0
	v_lshl_add_u64 v[20:21], v[20:21], 1, s[24:25]
	global_store_dwordx4 v[20:21], v[16:19], off
	global_store_dwordx4 v[50:51], v[4:7], off offset:512
	global_store_dwordx4 v[50:51], v[8:11], off offset:528
	v_cvt_pk_bf16_f32 v3, v6, v7
	v_cvt_pk_bf16_f32 v4, v8, v9
	v_cvt_pk_bf16_f32 v5, v10, v11
	global_store_dwordx4 v[20:21], v[2:5], off offset:256
	s_and_saveexec_b64 s[24:25], s[6:7]
	s_cbranch_execz .LBB0_445
	s_waitcnt lgkmcnt(0)
	v_add_f32_e32 v0, v0, v1
	s_mov_b64 s[26:27], -1
	s_and_b64 vcc, exec, s[12:13]
	s_cbranch_vccz .LBB0_443
	v_readlane_b32 s26, v250, 59
	v_lshlrev_b64 v[2:3], 5, v[48:49]
	v_readlane_b32 s27, v250, 60
	s_nop 1
	v_lshl_add_u64 v[2:3], s[26:27], 0, v[2:3]
	v_lshl_add_u64 v[2:3], s[14:15], 2, v[2:3]
	global_atomic_add_f32 v[2:3], v0, off
	s_mov_b64 s[26:27], 0

; #define PG8_STAGE(bufoff, gbase, voff) do { _Pragma("unroll") for (int _i = 0; _i < 2; ++_i) \
;         __builtin_amdgcn_global_load_lds((const unsigned*)((const char*)(gbase) + (voff)[_i]), (LAS unsigned*)(lds + (bufoff) + ldsw + _i * 8192), 16, 0, 0); } while (0)
; #define PG8_LDA(dst, b, h) do { _Pragma("unroll") for (int m = 0; m < 4; ++m) _Pragma("unroll") for (int k = 0; k < 2; ++k) dst[m][k] = *(const LAS bf16x8*)(lds + PG8_SA(b, h) + aoff + m * 2048 + k * 1024); } while (0)
; #define PG8_LDB(dst, b, h) do { _Pragma("unroll") for (int n = 0; n < 2; ++n) _Pragma("unroll") for (int k = 0; k < 2; ++k) dst[n][k] = *(const LAS bf16x8*)(lds + PG8_SB(b, h) + boff + n * 2048 + k * 1024); } while (0)
; #define PG8_MMA(ai, bj, At, Bt) do { __builtin_amdgcn_s_setprio(1); _Pragma("unroll") for (int m = 0; m < 4; ++m) _Pragma("unroll") for (int n = 0; n < 2; ++n) _Pragma("unroll") for (int k = 0; k < 2; ++k) \
;         acc[ai][bj][m][n] = __builtin_amdgcn_mfma_f32_16x16x32_bf16(Bt[n][k], At[m][k], acc[ai][bj][m][n], 0, 0, 0); __builtin_amdgcn_s_setprio(0); } while (0)
; #define PG8_WAIT_L(n) asm volatile("s_waitcnt lgkmcnt(" #n ")" ::: "memory")
; #define PG8_BAR __builtin_amdgcn_s_barrier()
; #define PG8_SCHED __builtin_amdgcn_sched_barrier(0)
; template <class Epi>
; DEV void gemm_phase(LAS unsigned char* lds, const Gemm g, const StaticOrder& S, const Epi& E) {
;     ...
;             PG8_LDB(B0, 0, 0); PG8_SCHED; PG8_LDA(At, 0, 0); PG8_STAGE(PG8_SA(1, 1), a1 + hstep, voffA);
;             PG8_WAIT_L(8); PG8_BAR; PG8_WAIT_L(0); PG8_MMA(0, 0, At, B0); PG8_BAR; PG8_SCHED;
;             PG8_LDB(B1, 0, 1); PG8_STAGE(PG8_SB(0, 0), b2, voffB);
;             PG8_BAR; PG8_WAIT_L(0); PG8_MMA(0, 1, At, B1); PG8_BAR;
;             PG8_LDA(At, 0, 1); PG8_STAGE(PG8_SA(0, 0), a2, voffA);
;             PG8_BAR; PG8_WAIT_L(0); PG8_MMA(1, 0, At, B0); PG8_BAR; PG8_SCHED;
.LBB0_657:
	s_add_u32 s6, s28, 0x100
	s_addc_u32 s7, s29, 0
	s_add_i32 s55, 0, 0x10000
	v_add_u32_e32 v140, s55, v196
	ds_read_b128 v[128:131], v140
	ds_read_b128 v[132:135], v140 offset:1024
	ds_read_b128 v[136:139], v140 offset:2048
	ds_read_b128 v[140:143], v140 offset:3072
	s_cmpk_eq_i32 s54, 0x54
	s_cselect_b32 s35, s27, s7
	s_cselect_b32 s34, s26, s6
	s_cselect_b32 s31, s9, s53
	s_cselect_b32 s30, s8, s52
	v_lshl_add_u64 v[214:215], s[28:29], 0, v[180:181]
	s_add_i32 m0, s41, 0xc000
	ds_read_b128 v[144:147], v219
	ds_read_b128 v[148:151], v219 offset:1024
	ds_read_b128 v[152:155], v219 offset:2048
	ds_read_b128 v[156:159], v219 offset:3072
	ds_read_b128 v[184:187], v219 offset:4096
	ds_read_b128 v[188:191], v219 offset:5120
	ds_read_b128 v[192:195], v219 offset:6144
	ds_read_b128 v[220:223], v219 offset:7168
	global_load_lds_dwordx4 v[214:215], off
	v_lshl_add_u64 v[214:215], s[28:29], 0, v[182:183]
	s_add_i32 m0, s41, 0xe000
	s_nop 0
	global_load_lds_dwordx4 v[214:215], off
	s_waitcnt lgkmcnt(8)
	s_barrier
	s_waitcnt lgkmcnt(0)
	s_setprio 1
	v_mfma_f32_16x16x32_bf16 v[124:127], v[128:131], v[144:147], v[124:127]
	v_mfma_f32_16x16x32_bf16 v[120:123], v[136:139], v[144:147], v[120:123]
	v_mfma_f32_16x16x32_bf16 v[112:115], v[128:131], v[152:155], v[112:115]
	v_mfma_f32_16x16x32_bf16 v[104:107], v[136:139], v[152:155], v[104:107]
	v_mfma_f32_16x16x32_bf16 v[92:95], v[128:131], v[184:187], v[92:95]
	v_mfma_f32_16x16x32_bf16 v[88:91], v[136:139], v[184:187], v[88:91]
	v_mfma_f32_16x16x32_bf16 v[80:83], v[128:131], v[192:195], v[80:83]
	v_mfma_f32_16x16x32_bf16 v[72:75], v[136:139], v[192:195], v[72:75]
	v_mfma_f32_16x16x32_bf16 v[124:127], v[132:135], v[148:151], v[124:127]
	v_mfma_f32_16x16x32_bf16 v[120:123], v[140:143], v[148:151], v[120:123]
	v_mfma_f32_16x16x32_bf16 v[112:115], v[132:135], v[156:159], v[112:115]
	v_mfma_f32_16x16x32_bf16 v[104:107], v[140:143], v[156:159], v[104:107]
	v_mfma_f32_16x16x32_bf16 v[92:95], v[132:135], v[188:191], v[92:95]
	v_mfma_f32_16x16x32_bf16 v[88:91], v[140:143], v[188:191], v[88:91]
	v_mfma_f32_16x16x32_bf16 v[80:83], v[132:135], v[220:223], v[80:83]
	v_mfma_f32_16x16x32_bf16 v[72:75], v[140:143], v[220:223], v[72:75]
	s_setprio 0
	s_barrier
	s_add_i32 s56, 0, 0x14000
	v_add_u32_e32 v214, s56, v196
	s_add_i32 s28, s55, s40
	ds_read_b128 v[224:227], v214
	ds_read_b128 v[228:231], v214 offset:1024
	ds_read_b128 v[232:235], v214 offset:2048
	ds_read_b128 v[236:239], v214 offset:3072
	v_lshl_add_u64 v[214:215], s[30:31], 0, v[160:161]
	s_mov_b32 m0, s28
	v_lshl_add_u64 v[216:217], s[30:31], 0, v[178:179]
	global_load_lds_dwordx4 v[214:215], off
	s_add_i32 m0, s28, 0x2000
	s_nop 0
	global_load_lds_dwordx4 v[216:217], off
	s_barrier
	s_waitcnt lgkmcnt(0)
	s_setprio 1
	v_mfma_f32_16x16x32_bf16 v[116:119], v[224:227], v[144:147], v[116:119]
	v_mfma_f32_16x16x32_bf16 v[108:111], v[232:235], v[144:147], v[108:111]
	v_mfma_f32_16x16x32_bf16 v[100:103], v[224:227], v[152:155], v[100:103]
	v_mfma_f32_16x16x32_bf16 v[96:99], v[232:235], v[152:155], v[96:99]
	v_mfma_f32_16x16x32_bf16 v[84:87], v[224:227], v[184:187], v[84:87]
	v_mfma_f32_16x16x32_bf16 v[76:79], v[232:235], v[184:187], v[76:79]
	v_mfma_f32_16x16x32_bf16 v[68:71], v[224:227], v[192:195], v[68:71]
	v_mfma_f32_16x16x32_bf16 v[64:67], v[232:235], v[192:195], v[64:67]
	v_mfma_f32_16x16x32_bf16 v[116:119], v[228:231], v[148:151], v[116:119]
	v_mfma_f32_16x16x32_bf16 v[108:111], v[236:239], v[148:151], v[108:111]
	v_mfma_f32_16x16x32_bf16 v[100:103], v[228:231], v[156:159], v[100:103]
	v_mfma_f32_16x16x32_bf16 v[96:99], v[236:239], v[156:159], v[96:99]
	v_mfma_f32_16x16x32_bf16 v[84:87], v[228:231], v[188:191], v[84:87]
	v_mfma_f32_16x16x32_bf16 v[76:79], v[236:239], v[188:191], v[76:79]
	v_mfma_f32_16x16x32_bf16 v[68:71], v[228:231], v[220:223], v[68:71]
	v_mfma_f32_16x16x32_bf16 v[64:67], v[236:239], v[220:223], v[64:67]
	s_setprio 0
	s_mov_b32 m0, s41
	v_lshl_add_u64 v[240:241], s[34:35], 0, v[174:175]
	s_barrier
	ds_read_b128 v[144:147], v219 offset:16384
	ds_read_b128 v[148:151], v219 offset:17408
	ds_read_b128 v[152:155], v219 offset:18432
	ds_read_b128 v[156:159], v219 offset:19456
	ds_read_b128 v[184:187], v219 offset:20480
	ds_read_b128 v[188:191], v219 offset:21504
	ds_read_b128 v[192:195], v219 offset:22528
	ds_read_b128 v[220:223], v219 offset:23552
	global_load_lds_dwordx4 v[240:241], off
	v_lshl_add_u64 v[242:243], s[34:35], 0, v[176:177]
	s_mov_b32 m0, s42
	s_nop 0
	global_load_lds_dwordx4 v[242:243], off
	s_barrier
	s_waitcnt lgkmcnt(0)
	s_setprio 1
	v_mfma_f32_16x16x32_bf16 v[60:63], v[128:131], v[144:147], v[60:63]
	v_mfma_f32_16x16x32_bf16 v[56:59], v[136:139], v[144:147], v[56:59]
	v_mfma_f32_16x16x32_bf16 v[48:51], v[128:131], v[152:155], v[48:51]
	v_mfma_f32_16x16x32_bf16 v[40:43], v[136:139], v[152:155], v[40:43]
	v_mfma_f32_16x16x32_bf16 v[28:31], v[128:131], v[184:187], v[28:31]
	v_mfma_f32_16x16x32_bf16 v[24:27], v[136:139], v[184:187], v[24:27]
	v_mfma_f32_16x16x32_bf16 v[16:19], v[128:131], v[192:195], v[16:19]
	v_mfma_f32_16x16x32_bf16 v[8:11], v[136:139], v[192:195], v[8:11]
	v_mfma_f32_16x16x32_bf16 v[60:63], v[132:135], v[148:151], v[60:63]
	v_mfma_f32_16x16x32_bf16 v[56:59], v[140:143], v[148:151], v[56:59]
	v_mfma_f32_16x16x32_bf16 v[48:51], v[132:135], v[156:159], v[48:51]
	v_mfma_f32_16x16x32_bf16 v[40:43], v[140:143], v[156:159], v[40:43]
	v_mfma_f32_16x16x32_bf16 v[28:31], v[132:135], v[188:191], v[28:31]
	v_mfma_f32_16x16x32_bf16 v[24:27], v[140:143], v[188:191], v[24:27]
	v_mfma_f32_16x16x32_bf16 v[16:19], v[132:135], v[220:223], v[16:19]
	v_mfma_f32_16x16x32_bf16 v[8:11], v[140:143], v[220:223], v[8:11]
	s_setprio 0
	s_barrier
; #define PG8_STAGE(bufoff, gbase, voff) do { _Pragma("unroll") for (int _i = 0; _i < 2; ++_i) \
;         __builtin_amdgcn_global_load_lds((const unsigned*)((const char*)(gbase) + (voff)[_i]), (LAS unsigned*)(lds + (bufoff) + ldsw + _i * 8192), 16, 0, 0); } while (0)
; #define PG8_LDA(dst, b, h) do { _Pragma("unroll") for (int m = 0; m < 4; ++m) _Pragma("unroll") for (int k = 0; k < 2; ++k) dst[m][k] = *(const LAS bf16x8*)(lds + PG8_SA(b, h) + aoff + m * 2048 + k * 1024); } while (0)
; #define PG8_LDB(dst, b, h) do { _Pragma("unroll") for (int n = 0; n < 2; ++n) _Pragma("unroll") for (int k = 0; k < 2; ++k) dst[n][k] = *(const LAS bf16x8*)(lds + PG8_SB(b, h) + boff + n * 2048 + k * 1024); } while (0)
; #define PG8_MMA(ai, bj, At, Bt) do { __builtin_amdgcn_s_setprio(1); _Pragma("unroll") for (int m = 0; m < 4; ++m) _Pragma("unroll") for (int n = 0; n < 2; ++n) _Pragma("unroll") for (int k = 0; k < 2; ++k) \
;         acc[ai][bj][m][n] = __builtin_amdgcn_mfma_f32_16x16x32_bf16(Bt[n][k], At[m][k], acc[ai][bj][m][n], 0, 0, 0); __builtin_amdgcn_s_setprio(0); } while (0)
; #define PG8_WAIT_V(n) asm volatile("s_waitcnt vmcnt(" #n ")" ::: "memory")
; #define PG8_WAIT_L(n) asm volatile("s_waitcnt lgkmcnt(" #n ")" ::: "memory")
; #define PG8_BAR __builtin_amdgcn_s_barrier()
; #define PG8_SCHED __builtin_amdgcn_sched_barrier(0)
; template <class Epi>
; DEV void gemm_phase(LAS unsigned char* lds, const Gemm g, const StaticOrder& S, const Epi& E) {
;     ...
;             PG8_BAR; PG8_WAIT_L(0); PG8_MMA(1, 0, At, B0); PG8_BAR; PG8_SCHED;
;             PG8_STAGE(PG8_SB(0, 1), b2 + hstep, voffB);
;             PG8_WAIT_V(6); PG8_BAR; PG8_MMA(1, 1, At, B1); PG8_BAR;
;             PG8_LDB(B0, 1, 0); PG8_SCHED; PG8_LDA(At, 1, 0); PG8_STAGE(PG8_SA(0, 1), a2 + hstep, voffA);
;             PG8_WAIT_L(8); PG8_BAR; PG8_WAIT_L(0); PG8_MMA(0, 0, At, B0); PG8_BAR; PG8_SCHED;
;             PG8_LDB(B1, 1, 1); PG8_STAGE(PG8_SB(1, 0), b3, voffB);
;             PG8_BAR; PG8_WAIT_L(0); PG8_MMA(0, 1, At, B1); PG8_BAR;
;             PG8_LDA(At, 1, 1); PG8_STAGE(PG8_SA(1, 0), a3, voffA);
	s_add_u32 s28, s30, 0x160000
	s_addc_u32 s29, s31, 0
	s_add_i32 s55, s56, s40
	v_lshl_add_u64 v[128:129], s[28:29], 0, v[160:161]
	s_mov_b32 m0, s55
	s_nop 0
	global_load_lds_dwordx4 v[128:129], off
	v_lshl_add_u64 v[128:129], s[28:29], 0, v[178:179]
	s_add_i32 m0, s55, 0x2000
	s_nop 0
	global_load_lds_dwordx4 v[128:129], off
	s_waitcnt vmcnt(6)
	s_barrier
	s_setprio 1
	v_mfma_f32_16x16x32_bf16 v[52:55], v[224:227], v[144:147], v[52:55]
	v_mfma_f32_16x16x32_bf16 v[44:47], v[232:235], v[144:147], v[44:47]
	v_mfma_f32_16x16x32_bf16 v[36:39], v[224:227], v[152:155], v[36:39]
	v_mfma_f32_16x16x32_bf16 v[32:35], v[232:235], v[152:155], v[32:35]
	v_mfma_f32_16x16x32_bf16 v[20:23], v[224:227], v[184:187], v[20:23]
	v_mfma_f32_16x16x32_bf16 v[12:15], v[232:235], v[184:187], v[12:15]
	v_mfma_f32_16x16x32_bf16 v[4:7], v[224:227], v[192:195], v[4:7]
	v_mfma_f32_16x16x32_bf16 v[0:3], v[232:235], v[192:195], v[0:3]
	v_mfma_f32_16x16x32_bf16 v[52:55], v[228:231], v[148:151], v[52:55]
	v_mfma_f32_16x16x32_bf16 v[44:47], v[236:239], v[148:151], v[44:47]
	v_mfma_f32_16x16x32_bf16 v[36:39], v[228:231], v[156:159], v[36:39]
	v_mfma_f32_16x16x32_bf16 v[32:35], v[236:239], v[156:159], v[32:35]
	v_mfma_f32_16x16x32_bf16 v[20:23], v[228:231], v[188:191], v[20:23]
	v_mfma_f32_16x16x32_bf16 v[12:15], v[236:239], v[188:191], v[12:15]
	v_mfma_f32_16x16x32_bf16 v[4:7], v[228:231], v[220:223], v[4:7]
	v_mfma_f32_16x16x32_bf16 v[0:3], v[236:239], v[220:223], v[0:3]
	s_setprio 0
	s_add_i32 s55, 0, 0x18000
	v_add_u32_e32 v140, s55, v196
	s_barrier
	ds_read_b128 v[128:131], v140
	ds_read_b128 v[132:135], v140 offset:1024
	ds_read_b128 v[136:139], v140 offset:2048
	ds_read_b128 v[140:143], v140 offset:3072
	s_add_u32 s28, s34, 0x160000
	s_addc_u32 s29, s35, 0
	s_mov_b32 m0, s43
	v_lshl_add_u64 v[224:225], s[28:29], 0, v[174:175]
	ds_read_b128 v[144:147], v219 offset:32768
	ds_read_b128 v[148:151], v219 offset:33792
	ds_read_b128 v[152:155], v219 offset:34816
	ds_read_b128 v[156:159], v219 offset:35840
	ds_read_b128 v[184:187], v219 offset:36864
	ds_read_b128 v[188:191], v219 offset:37888
	ds_read_b128 v[192:195], v219 offset:38912
	ds_read_b128 v[220:223], v219 offset:39936
	global_load_lds_dwordx4 v[224:225], off
	v_lshl_add_u64 v[224:225], s[28:29], 0, v[176:177]
	s_mov_b32 m0, s44
	s_nop 0
	global_load_lds_dwordx4 v[224:225], off
	s_waitcnt lgkmcnt(8)
	s_barrier
	s_waitcnt lgkmcnt(0)
	s_setprio 1
	v_mfma_f32_16x16x32_bf16 v[124:127], v[128:131], v[144:147], v[124:127]
	v_mfma_f32_16x16x32_bf16 v[120:123], v[136:139], v[144:147], v[120:123]
	v_mfma_f32_16x16x32_bf16 v[112:115], v[128:131], v[152:155], v[112:115]
	v_mfma_f32_16x16x32_bf16 v[104:107], v[136:139], v[152:155], v[104:107]
	v_mfma_f32_16x16x32_bf16 v[92:95], v[128:131], v[184:187], v[92:95]
	v_mfma_f32_16x16x32_bf16 v[88:91], v[136:139], v[184:187], v[88:91]
	v_mfma_f32_16x16x32_bf16 v[80:83], v[128:131], v[192:195], v[80:83]
	v_mfma_f32_16x16x32_bf16 v[72:75], v[136:139], v[192:195], v[72:75]
	v_mfma_f32_16x16x32_bf16 v[124:127], v[132:135], v[148:151], v[124:127]
	v_mfma_f32_16x16x32_bf16 v[120:123], v[140:143], v[148:151], v[120:123]
	v_mfma_f32_16x16x32_bf16 v[112:115], v[132:135], v[156:159], v[112:115]
	v_mfma_f32_16x16x32_bf16 v[104:107], v[140:143], v[156:159], v[104:107]
	v_mfma_f32_16x16x32_bf16 v[92:95], v[132:135], v[188:191], v[92:95]
	v_mfma_f32_16x16x32_bf16 v[88:91], v[140:143], v[188:191], v[88:91]
	v_mfma_f32_16x16x32_bf16 v[80:83], v[132:135], v[220:223], v[80:83]
	v_mfma_f32_16x16x32_bf16 v[72:75], v[140:143], v[220:223], v[72:75]
	s_setprio 0
	s_barrier
	s_add_i32 s34, 0, 0x1c000
	s_add_i32 s28, s55, s40
	v_add_u32_e32 v236, s34, v196
	v_lshl_add_u64 v[214:215], v[214:215], 0, s[2:3]
	s_mov_b32 m0, s28
	ds_read_b128 v[224:227], v236
	ds_read_b128 v[228:231], v236 offset:1024
	ds_read_b128 v[232:235], v236 offset:2048
	ds_read_b128 v[236:239], v236 offset:3072
	global_load_lds_dwordx4 v[214:215], off
	v_lshl_add_u64 v[214:215], v[216:217], 0, s[2:3]
	s_add_i32 m0, s28, 0x2000
	s_nop 0
	global_load_lds_dwordx4 v[214:215], off
	s_barrier
	s_waitcnt lgkmcnt(0)
	s_setprio 1
	v_mfma_f32_16x16x32_bf16 v[116:119], v[224:227], v[144:147], v[116:119]
	v_mfma_f32_16x16x32_bf16 v[108:111], v[232:235], v[144:147], v[108:111]
	v_mfma_f32_16x16x32_bf16 v[100:103], v[224:227], v[152:155], v[100:103]
	v_mfma_f32_16x16x32_bf16 v[96:99], v[232:235], v[152:155], v[96:99]
	v_mfma_f32_16x16x32_bf16 v[84:87], v[224:227], v[184:187], v[84:87]
	v_mfma_f32_16x16x32_bf16 v[76:79], v[232:235], v[184:187], v[76:79]
	v_mfma_f32_16x16x32_bf16 v[68:71], v[224:227], v[192:195], v[68:71]
	v_mfma_f32_16x16x32_bf16 v[64:67], v[232:235], v[192:195], v[64:67]
	v_mfma_f32_16x16x32_bf16 v[116:119], v[228:231], v[148:151], v[116:119]
	v_mfma_f32_16x16x32_bf16 v[108:111], v[236:239], v[148:151], v[108:111]
	v_mfma_f32_16x16x32_bf16 v[100:103], v[228:231], v[156:159], v[100:103]
	v_mfma_f32_16x16x32_bf16 v[96:99], v[236:239], v[156:159], v[96:99]
	v_mfma_f32_16x16x32_bf16 v[84:87], v[228:231], v[188:191], v[84:87]
	v_mfma_f32_16x16x32_bf16 v[76:79], v[236:239], v[188:191], v[76:79]
	v_mfma_f32_16x16x32_bf16 v[68:71], v[228:231], v[220:223], v[68:71]
	v_mfma_f32_16x16x32_bf16 v[64:67], v[236:239], v[220:223], v[64:67]
	s_setprio 0
	s_mov_b32 m0, s45
	v_lshl_add_u64 v[214:215], v[240:241], 0, s[2:3]
	s_barrier
	ds_read_b128 v[144:147], v219 offset:49152
	ds_read_b128 v[148:151], v219 offset:50176
	ds_read_b128 v[152:155], v219 offset:51200
	ds_read_b128 v[156:159], v219 offset:52224
	ds_read_b128 v[184:187], v219 offset:53248
	ds_read_b128 v[188:191], v219 offset:54272
	ds_read_b128 v[192:195], v219 offset:55296
	ds_read_b128 v[220:223], v219 offset:56320
	global_load_lds_dwordx4 v[214:215], off
	v_lshl_add_u64 v[214:215], v[242:243], 0, s[2:3]
	s_mov_b32 m0, s46
	s_nop 0
	global_load_lds_dwordx4 v[214:215], off
	s_barrier
; #define PG8_STAGE(bufoff, gbase, voff) do { _Pragma("unroll") for (int _i = 0; _i < 2; ++_i) \
;         __builtin_amdgcn_global_load_lds((const unsigned*)((const char*)(gbase) + (voff)[_i]), (LAS unsigned*)(lds + (bufoff) + ldsw + _i * 8192), 16, 0, 0); } while (0)
; #define PG8_LDA(dst, b, h) do { _Pragma("unroll") for (int m = 0; m < 4; ++m) _Pragma("unroll") for (int k = 0; k < 2; ++k) dst[m][k] = *(const LAS bf16x8*)(lds + PG8_SA(b, h) + aoff + m * 2048 + k * 1024); } while (0)
; #define PG8_MMA(ai, bj, At, Bt) do { __builtin_amdgcn_s_setprio(1); _Pragma("unroll") for (int m = 0; m < 4; ++m) _Pragma("unroll") for (int n = 0; n < 2; ++n) _Pragma("unroll") for (int k = 0; k < 2; ++k) \
;         acc[ai][bj][m][n] = __builtin_amdgcn_mfma_f32_16x16x32_bf16(Bt[n][k], At[m][k], acc[ai][bj][m][n], 0, 0, 0); __builtin_amdgcn_s_setprio(0); } while (0)
; #define PG8_WAIT_V(n) asm volatile("s_waitcnt vmcnt(" #n ")" ::: "memory")
; #define PG8_WAIT_L(n) asm volatile("s_waitcnt lgkmcnt(" #n ")" ::: "memory")
; #define PG8_BAR __builtin_amdgcn_s_barrier()
; #define PG8_SCHED __builtin_amdgcn_sched_barrier(0)
; template <class Epi>
; DEV void gemm_phase(LAS unsigned char* lds, const Gemm g, const StaticOrder& S, const Epi& E) {
;     ...
;             PG8_LDA(At, 1, 1); PG8_STAGE(PG8_SA(1, 0), a3, voffA);
;             PG8_BAR; PG8_WAIT_L(0); PG8_MMA(1, 0, At, B0); PG8_BAR; PG8_SCHED;
;             PG8_STAGE(PG8_SB(1, 1), b3 + hstep, voffB);
;             PG8_WAIT_V(6); PG8_BAR; PG8_MMA(1, 1, At, B1); PG8_BAR;
	s_waitcnt lgkmcnt(0)
	s_setprio 1
	v_mfma_f32_16x16x32_bf16 v[60:63], v[128:131], v[144:147], v[60:63]
	v_mfma_f32_16x16x32_bf16 v[56:59], v[136:139], v[144:147], v[56:59]
	v_mfma_f32_16x16x32_bf16 v[48:51], v[128:131], v[152:155], v[48:51]
	v_mfma_f32_16x16x32_bf16 v[40:43], v[136:139], v[152:155], v[40:43]
	v_mfma_f32_16x16x32_bf16 v[28:31], v[128:131], v[184:187], v[28:31]
	v_mfma_f32_16x16x32_bf16 v[24:27], v[136:139], v[184:187], v[24:27]
	v_mfma_f32_16x16x32_bf16 v[16:19], v[128:131], v[192:195], v[16:19]
	v_mfma_f32_16x16x32_bf16 v[8:11], v[136:139], v[192:195], v[8:11]
	v_mfma_f32_16x16x32_bf16 v[60:63], v[132:135], v[148:151], v[60:63]
	v_mfma_f32_16x16x32_bf16 v[56:59], v[140:143], v[148:151], v[56:59]
	v_mfma_f32_16x16x32_bf16 v[48:51], v[132:135], v[156:159], v[48:51]
	v_mfma_f32_16x16x32_bf16 v[40:43], v[140:143], v[156:159], v[40:43]
	v_mfma_f32_16x16x32_bf16 v[28:31], v[132:135], v[188:191], v[28:31]
	v_mfma_f32_16x16x32_bf16 v[24:27], v[140:143], v[188:191], v[24:27]
	v_mfma_f32_16x16x32_bf16 v[16:19], v[132:135], v[220:223], v[16:19]
	v_mfma_f32_16x16x32_bf16 v[8:11], v[140:143], v[220:223], v[8:11]
	s_setprio 0
	s_barrier
	s_add_u32 s28, s30, 0x160080
	s_addc_u32 s29, s31, 0
	s_add_i32 s30, s34, s40
	v_lshl_add_u64 v[128:129], s[28:29], 0, v[160:161]
	s_mov_b32 m0, s30
	s_nop 0
	global_load_lds_dwordx4 v[128:129], off
	v_lshl_add_u64 v[128:129], s[28:29], 0, v[178:179]
	s_add_i32 m0, s30, 0x2000
	s_nop 0
	global_load_lds_dwordx4 v[128:129], off
	s_waitcnt vmcnt(6)
	s_barrier
	s_setprio 1
	v_mfma_f32_16x16x32_bf16 v[52:55], v[224:227], v[144:147], v[52:55]
	v_mfma_f32_16x16x32_bf16 v[44:47], v[232:235], v[144:147], v[44:47]
	v_mfma_f32_16x16x32_bf16 v[36:39], v[224:227], v[152:155], v[36:39]
	v_mfma_f32_16x16x32_bf16 v[32:35], v[232:235], v[152:155], v[32:35]
	v_mfma_f32_16x16x32_bf16 v[20:23], v[224:227], v[184:187], v[20:23]
	v_mfma_f32_16x16x32_bf16 v[12:15], v[232:235], v[184:187], v[12:15]
	v_mfma_f32_16x16x32_bf16 v[4:7], v[224:227], v[192:195], v[4:7]
	v_mfma_f32_16x16x32_bf16 v[0:3], v[232:235], v[192:195], v[0:3]
	v_mfma_f32_16x16x32_bf16 v[52:55], v[228:231], v[148:151], v[52:55]
	v_mfma_f32_16x16x32_bf16 v[44:47], v[236:239], v[148:151], v[44:47]
	v_mfma_f32_16x16x32_bf16 v[36:39], v[228:231], v[156:159], v[36:39]
	v_mfma_f32_16x16x32_bf16 v[32:35], v[236:239], v[156:159], v[32:35]
	v_mfma_f32_16x16x32_bf16 v[20:23], v[228:231], v[188:191], v[20:23]
	v_mfma_f32_16x16x32_bf16 v[12:15], v[236:239], v[188:191], v[12:15]
	v_mfma_f32_16x16x32_bf16 v[4:7], v[228:231], v[220:223], v[4:7]
	v_mfma_f32_16x16x32_bf16 v[0:3], v[236:239], v[220:223], v[0:3]
	s_setprio 0
	s_add_i32 s54, s54, 2
	s_add_u32 s52, s52, 0x100
	s_addc_u32 s53, s53, 0
	s_cmpk_gt_u32 s54, 0x55
	s_mov_b64 s[28:29], s[6:7]
	s_barrier
	s_cbranch_scc0 .LBB0_657
; DEV bf16x8 pack8(f32x4 a, f32x4 b) { u32x4 w; w.x = cvt_pk_bf16(a[0], a[1]); w.y = cvt_pk_bf16(a[2], a[3]); w.z = cvt_pk_bf16(b[0], b[1]); w.w = cvt_pk_bf16(b[2], b[3]); return __builtin_bit_cast(bf16x8, w); }
;     DEV void operator()(AccRef acc, const pg8::Unit& u, int wr, int wc, int fr, int fq) const {
;         const int row0 = u.pm * 256 + wr * 64 + fr, col0 = u.pn * 256 + wc * 32 + 8 * fq;
; #pragma unroll
;         for (int am = 0; am < 4; ++am) { const int ai = am >> 1, m0 = (am & 1) * 2;
;             f32x4 bv[4][2][2];
; #pragma unroll
;             for (int m = m0; m < m0 + 2; ++m)
; #pragma unroll
;                 for (int bj = 0; bj < 2; ++bj)
; #pragma unroll
;                     for (int n = 0; n < 2; ++n) bv[m][bj][n] = *(const f32x4*)(base + (size_t)(row0 + ai * 128 + m * 16) * 2048 + col0 + bj * 128 + n * 4);
; #pragma unroll
;             for (int m = m0; m < m0 + 2; ++m) { const size_t off = (size_t)(row0 + ai * 128 + m * 16) * 2048 + col0; float sq = 0.f;
; #pragma unroll
;                 for (int bj = 0; bj < 2; ++bj) { const f32x4 o0 = bv[m][bj][0] + scale * acc[ai][bj][m][0], o1 = bv[m][bj][1] + scale * acc[ai][bj][m][1];
;                     *(f32x4*)(out + off + bj * 128) = o0; *(f32x4*)(out + off + bj * 128 + 4) = o1;
;                     if (xb) { *(u32x4*)(xb + off + bj * 128) = __builtin_bit_cast(u32x4, pack8(o0, o1));
;                         sq += (o0[0] * o0[0] + o0[1] * o0[1] + o0[2] * o0[2] + o0[3] * o0[3]) + (o1[0] * o1[0] + o1[1] * o1[1] + o1[2] * o1[2] + o1[3] * o1[3]); } }
;                 if (ssout) { sq += __shfl_xor(sq, 16); sq += __shfl_xor(sq, 32);
;                     if (fq == 0) { if (red) red[(ai * 128 + wr * 64 + m * 16 + fr) * 4 + wc] = sq; else atomicAdd(ssout + (size_t)(row0 + ai * 128 + m * 16) * 8 + u.pn, sq); } } }
	v_lshl_add_u32 v186, s23, 8, v167
	v_lshl_or_b32 v184, s22, 8, v197
	v_ashrrev_i32_e32 v185, 31, v184
	v_ashrrev_i32_e32 v187, 31, v186
	v_lshl_add_u64 v[188:189], v[184:185], 2, s[24:25]
	v_lshlrev_b64 v[128:129], 13, v[186:187]
	v_or_b32_e32 v190, 16, v186
	v_lshl_add_u64 v[128:129], v[188:189], 0, v[128:129]
	v_ashrrev_i32_e32 v191, 31, v190
	global_load_dwordx4 v[152:155], v[128:129], off offset:16
	global_load_dwordx4 v[156:159], v[128:129], off
	global_load_dwordx4 v[144:147], v[128:129], off offset:528
	global_load_dwordx4 v[148:151], v[128:129], off offset:512
	v_lshlrev_b64 v[128:129], 13, v[190:191]
	v_lshl_add_u64 v[132:133], v[188:189], 0, v[128:129]
	global_load_dwordx4 v[136:139], v[132:133], off offset:16
	global_load_dwordx4 v[140:143], v[132:133], off
	global_load_dwordx4 v[128:131], v[132:133], off offset:528
	s_nop 0
	global_load_dwordx4 v[132:135], v[132:133], off offset:512
	v_add_u32_e32 v255, 32, v186
	v_lshlrev_b32_e32 v255, 13, v255
	v_lshl_add_u32 v255, v184, 2, v255
	global_load_dwordx4 v[214:217], v255, s[24:25] offset:16
	global_load_dwordx4 v[224:227], v255, s[24:25]
	global_load_dwordx4 v[228:231], v255, s[24:25] offset:528
	global_load_dwordx4 v[232:235], v255, s[24:25] offset:512
	v_add_u32_e32 v255, 48, v186
	v_lshlrev_b32_e32 v255, 13, v255
	v_lshl_add_u32 v255, v184, 2, v255
	global_load_dwordx4 v[236:239], v255, s[24:25] offset:16
	global_load_dwordx4 v[240:243], v255, s[24:25]
	global_load_dwordx4 v[244:247], v255, s[24:25] offset:528
	global_load_dwordx2 v[248:249], v255, s[24:25] offset:512
	global_load_dwordx2 v[172:173], v255, s[24:25] offset:520
	v_lshlrev_b64 v[192:193], 11, v[186:187]
	v_lshl_add_u64 v[194:195], v[192:193], 0, v[184:185]
	s_ashr_i32 s23, s22, 31
	v_lshl_add_u64 v[192:193], v[194:195], 2, s[68:69]
	s_mov_b64 s[28:29], -1
	s_andn2_b64 vcc, exec, s[18:19]
	s_waitcnt vmcnt(0)
	v_pk_fma_f32 v[152:153], v[120:121], 0.5, v[152:153] op_sel_hi:[1,0,1]
	v_cndmask_b32_e64 v120, 0, 1, s[18:19]
	v_pk_fma_f32 v[158:159], v[126:127], 0.5, v[158:159] op_sel_hi:[1,0,1]
	v_pk_fma_f32 v[156:157], v[124:125], 0.5, v[156:157] op_sel_hi:[1,0,1]
	v_pk_fma_f32 v[154:155], v[122:123], 0.5, v[154:155] op_sel_hi:[1,0,1]
	v_cmp_ne_u32_e64 s[6:7], 1, v120
	v_pk_fma_f32 v[120:121], v[116:117], 0.5, v[148:149] op_sel_hi:[1,0,1]
	v_pk_fma_f32 v[124:125], v[108:109], 0.5, v[144:145] op_sel_hi:[1,0,1]
	global_store_dwordx4 v[192:193], v[156:159], off
	global_store_dwordx4 v[192:193], v[152:155], off offset:16
	s_cbranch_vccnz .LBB0_665
	v_mul_f32_e32 v108, v157, v157
	v_mul_f32_e32 v109, v153, v153
	v_fmac_f32_e32 v108, v156, v156
	v_fmac_f32_e32 v109, v152, v152
	v_fmac_f32_e32 v108, v158, v158
	v_fmac_f32_e32 v109, v154, v154
	v_fmac_f32_e32 v108, v159, v159
	v_fmac_f32_e32 v109, v155, v155
	v_add_f32_e32 v108, v108, v109
	v_mul_f32_e32 v109, v121, v121
	v_mul_f32_e32 v144, v125, v125
	v_pk_fma_f32 v[122:123], v[118:119], 0.5, v[150:151] op_sel_hi:[1,0,1]
	v_pk_fma_f32 v[126:127], v[110:111], 0.5, v[146:147] op_sel_hi:[1,0,1]
	v_fmac_f32_e32 v109, v120, v120
	v_fmac_f32_e32 v144, v124, v124
	v_fmac_f32_e32 v109, v122, v122
	v_fmac_f32_e32 v144, v126, v126
	v_fmac_f32_e32 v109, v123, v123
	v_fmac_f32_e32 v144, v127, v127
	v_add_f32_e32 v109, v109, v144
	v_cmp_lt_i32_e32 vcc, v208, v206
	v_add_f32_e32 v108, v108, v109
	v_readlane_b32 s28, v250, 9
	v_cndmask_b32_e32 v109, v204, v208, vcc
	v_lshlrev_b32_e32 v109, 2, v109
	ds_bpermute_b32 v109, v109, v108
	v_cmp_lt_i32_e32 vcc, v207, v206
	v_readlane_b32 s29, v250, 10
	v_cvt_pk_bf16_f32 v220, v156, v157
	v_cvt_pk_bf16_f32 v221, v158, v159
	s_waitcnt lgkmcnt(0)
	v_add_f32_e32 v108, v108, v109
	v_cndmask_b32_e32 v109, v204, v207, vcc
	v_lshlrev_b32_e32 v109, 2, v109
	ds_bpermute_b32 v109, v109, v108
	v_cvt_pk_bf16_f32 v222, v152, v153
	v_cvt_pk_bf16_f32 v223, v154, v155
	v_lshl_add_u64 v[116:117], v[194:195], 1, s[28:29]
	v_cvt_pk_bf16_f32 v152, v120, v121
	v_cvt_pk_bf16_f32 v153, v122, v123
	v_cvt_pk_bf16_f32 v154, v124, v125
	v_cvt_pk_bf16_f32 v155, v126, v127
	global_store_dwordx4 v[116:117], v[220:223], off
	global_store_dwordx4 v[192:193], v[120:123], off offset:512
	global_store_dwordx4 v[192:193], v[124:127], off offset:528
	global_store_dwordx4 v[116:117], v[152:155], off offset:256
	s_and_saveexec_b64 s[28:29], s[10:11]
	s_cbranch_execz .LBB0_664
	s_waitcnt lgkmcnt(0)
	v_add_f32_e32 v108, v108, v109
	s_andn2_b64 vcc, exec, s[20:21]
	s_mov_b64 s[30:31], -1
	s_cbranch_vccnz .LBB0_662
	s_mov_b64 s[30:31], 0
	ds_write_b32 v218, v108

; DEV bf16x8 pack8(f32x4 a, f32x4 b) { u32x4 w; w.x = cvt_pk_bf16(a[0], a[1]); w.y = cvt_pk_bf16(a[2], a[3]); w.z = cvt_pk_bf16(b[0], b[1]); w.w = cvt_pk_bf16(b[2], b[3]); return __builtin_bit_cast(bf16x8, w); }
;     DEV void operator()(AccRef acc, const pg8::Unit& u, int wr, int wc, int fr, int fq) const {
;     ...
;         for (int am = 0; am < 4; ++am) { const int ai = am >> 1, m0 = (am & 1) * 2;
;             f32x4 bv[4][2][2];
; #pragma unroll
;             for (int m = m0; m < m0 + 2; ++m)
; #pragma unroll
;                 for (int bj = 0; bj < 2; ++bj)
; #pragma unroll
;                     for (int n = 0; n < 2; ++n) bv[m][bj][n] = *(const f32x4*)(base + (size_t)(row0 + ai * 128 + m * 16) * 2048 + col0 + bj * 128 + n * 4);
; #pragma unroll
;             for (int m = m0; m < m0 + 2; ++m) { const size_t off = (size_t)(row0 + ai * 128 + m * 16) * 2048 + col0; float sq = 0.f;
; #pragma unroll
;                 for (int bj = 0; bj < 2; ++bj) { const f32x4 o0 = bv[m][bj][0] + scale * acc[ai][bj][m][0], o1 = bv[m][bj][1] + scale * acc[ai][bj][m][1];
;                     *(f32x4*)(out + off + bj * 128) = o0; *(f32x4*)(out + off + bj * 128 + 4) = o1;
;                     if (xb) { *(u32x4*)(xb + off + bj * 128) = __builtin_bit_cast(u32x4, pack8(o0, o1));
;                         sq += (o0[0] * o0[0] + o0[1] * o0[1] + o0[2] * o0[2] + o0[3] * o0[3]) + (o1[0] * o1[0] + o1[1] * o1[1] + o1[2] * o1[2] + o1[3] * o1[3]); } }
;                 if (ssout) { sq += __shfl_xor(sq, 16); sq += __shfl_xor(sq, 32);
;                     if (fq == 0) { if (red) red[(ai * 128 + wr * 64 + m * 16 + fr) * 4 + wc] = sq; else atomicAdd(ssout + (size_t)(row0 + ai * 128 + m * 16) * 8 + u.pn, sq); } } }
.LBB0_676:
	v_or_b32_e32 v132, 32, v186
	v_ashrrev_i32_e32 v133, 31, v132
	s_waitcnt lgkmcnt(0)
	v_lshlrev_b64 v[96:97], 13, v[132:133]
	v_or_b32_e32 v128, 48, v186
	v_lshl_add_u64 v[96:97], v[188:189], 0, v[96:97]
	v_ashrrev_i32_e32 v129, 31, v128
	v_mov_b32_e32 v120, v214
	v_mov_b32_e32 v121, v215
	v_mov_b32_e32 v122, v216
	v_mov_b32_e32 v123, v217
	v_mov_b32_e32 v124, v224
	v_mov_b32_e32 v125, v225
	v_mov_b32_e32 v126, v226
	v_mov_b32_e32 v127, v227
	v_mov_b32_e32 v112, v228
	v_mov_b32_e32 v113, v229
	v_mov_b32_e32 v114, v230
	v_mov_b32_e32 v115, v231
	v_mov_b32_e32 v116, v232
	v_mov_b32_e32 v117, v233
	v_mov_b32_e32 v118, v234
	v_mov_b32_e32 v119, v235
	v_lshlrev_b64 v[96:97], 13, v[128:129]
	v_lshl_add_u64 v[100:101], v[188:189], 0, v[96:97]
	v_mov_b32_e32 v104, v236
	v_mov_b32_e32 v105, v237
	v_mov_b32_e32 v106, v238
	v_mov_b32_e32 v107, v239
	v_mov_b32_e32 v108, v240
	v_mov_b32_e32 v109, v241
	v_mov_b32_e32 v110, v242
	v_mov_b32_e32 v111, v243
	v_mov_b32_e32 v96, v244
	v_mov_b32_e32 v97, v245
	v_mov_b32_e32 v98, v246
	v_mov_b32_e32 v99, v247
	s_nop 0
	v_mov_b32_e32 v100, v248
	v_mov_b32_e32 v101, v249
	v_mov_b32_e32 v102, v172
	v_mov_b32_e32 v103, v173
	v_add_u32_e32 v255, 128, v186
	v_lshlrev_b32_e32 v255, 13, v255
	v_lshl_add_u32 v255, v184, 2, v255
	global_load_dwordx4 v[214:217], v255, s[24:25] offset:16
	global_load_dwordx4 v[224:227], v255, s[24:25]
	global_load_dwordx4 v[228:231], v255, s[24:25] offset:528
	global_load_dwordx4 v[232:235], v255, s[24:25] offset:512
	v_add_u32_e32 v255, 144, v186
	v_lshlrev_b32_e32 v255, 13, v255
	v_lshl_add_u32 v255, v184, 2, v255
	global_load_dwordx4 v[236:239], v255, s[24:25] offset:16
	global_load_dwordx4 v[240:243], v255, s[24:25]
	global_load_dwordx4 v[244:247], v255, s[24:25] offset:528
	global_load_dwordx2 v[248:249], v255, s[24:25] offset:512
	global_load_dwordx2 v[172:173], v255, s[24:25] offset:520
	v_lshlrev_b64 v[130:131], 11, v[132:133]
	v_lshl_add_u64 v[134:135], v[130:131], 0, v[184:185]
	v_lshl_add_u64 v[130:131], v[134:135], 2, s[68:69]
	s_mov_b64 s[28:29], -1
	s_and_b64 vcc, exec, s[6:7]
	v_pk_fma_f32 v[122:123], v[90:91], 0.5, v[122:123] op_sel_hi:[1,0,1]
	v_pk_fma_f32 v[126:127], v[94:95], 0.5, v[126:127] op_sel_hi:[1,0,1]
	v_pk_fma_f32 v[124:125], v[92:93], 0.5, v[124:125] op_sel_hi:[1,0,1]
	v_pk_fma_f32 v[120:121], v[88:89], 0.5, v[120:121] op_sel_hi:[1,0,1]
	v_pk_fma_f32 v[88:89], v[84:85], 0.5, v[116:117] op_sel_hi:[1,0,1]
	v_pk_fma_f32 v[92:93], v[76:77], 0.5, v[112:113] op_sel_hi:[1,0,1]
	global_store_dwordx4 v[130:131], v[124:127], off
	global_store_dwordx4 v[130:131], v[120:123], off offset:16
	s_cbranch_vccnz .LBB0_683
	v_mul_f32_e32 v76, v125, v125
	v_mul_f32_e32 v77, v121, v121
	v_fmac_f32_e32 v76, v124, v124
	v_fmac_f32_e32 v77, v120, v120
	v_fmac_f32_e32 v76, v126, v126
	v_fmac_f32_e32 v77, v122, v122
	v_fmac_f32_e32 v76, v127, v127
	v_fmac_f32_e32 v77, v123, v123
	v_add_f32_e32 v76, v76, v77
	v_mul_f32_e32 v77, v89, v89
	v_mul_f32_e32 v112, v93, v93
	v_pk_fma_f32 v[90:91], v[86:87], 0.5, v[118:119] op_sel_hi:[1,0,1]
	v_pk_fma_f32 v[94:95], v[78:79], 0.5, v[114:115] op_sel_hi:[1,0,1]
	v_fmac_f32_e32 v77, v88, v88
	v_fmac_f32_e32 v112, v92, v92
	v_fmac_f32_e32 v77, v90, v90
	v_fmac_f32_e32 v112, v94, v94
	v_fmac_f32_e32 v77, v91, v91
	v_fmac_f32_e32 v112, v95, v95
	v_add_f32_e32 v77, v77, v112
	v_cmp_lt_i32_e32 vcc, v208, v206
	v_add_f32_e32 v76, v76, v77
	v_readlane_b32 s28, v250, 9
	v_cndmask_b32_e32 v77, v204, v208, vcc
	v_lshlrev_b32_e32 v77, 2, v77
	ds_bpermute_b32 v77, v77, v76
	v_cmp_lt_i32_e32 vcc, v207, v206
	v_readlane_b32 s29, v250, 10
	v_cvt_pk_bf16_f32 v136, v124, v125
	v_cvt_pk_bf16_f32 v137, v126, v127
	s_waitcnt lgkmcnt(0)
	v_add_f32_e32 v76, v76, v77
	v_cndmask_b32_e32 v77, v204, v207, vcc
	v_lshlrev_b32_e32 v77, 2, v77
	ds_bpermute_b32 v77, v77, v76
	v_cvt_pk_bf16_f32 v138, v120, v121
	v_cvt_pk_bf16_f32 v139, v122, v123
	v_lshl_add_u64 v[84:85], v[134:135], 1, s[28:29]
	v_cvt_pk_bf16_f32 v120, v88, v89
	v_cvt_pk_bf16_f32 v121, v90, v91
	v_cvt_pk_bf16_f32 v122, v92, v93
	v_cvt_pk_bf16_f32 v123, v94, v95
	global_store_dwordx4 v[84:85], v[136:139], off
	global_store_dwordx4 v[130:131], v[88:91], off offset:512
	global_store_dwordx4 v[130:131], v[92:95], off offset:528
	global_store_dwordx4 v[84:85], v[120:123], off offset:256
	s_and_saveexec_b64 s[28:29], s[10:11]
	s_cbranch_execz .LBB0_682
	s_waitcnt lgkmcnt(0)
	v_add_f32_e32 v76, v76, v77
	s_andn2_b64 vcc, exec, s[20:21]
	s_mov_b64 s[30:31], -1
	s_cbranch_vccnz .LBB0_680
	s_mov_b64 s[30:31], 0
	ds_write_b32 v218, v76 offset:512

; DEV bf16x8 pack8(f32x4 a, f32x4 b) { u32x4 w; w.x = cvt_pk_bf16(a[0], a[1]); w.y = cvt_pk_bf16(a[2], a[3]); w.z = cvt_pk_bf16(b[0], b[1]); w.w = cvt_pk_bf16(b[2], b[3]); return __builtin_bit_cast(bf16x8, w); }
;     DEV void operator()(AccRef acc, const pg8::Unit& u, int wr, int wc, int fr, int fq) const {
;     ...
;             for (int m = m0; m < m0 + 2; ++m) { const size_t off = (size_t)(row0 + ai * 128 + m * 16) * 2048 + col0; float sq = 0.f;
; #pragma unroll
;                 for (int bj = 0; bj < 2; ++bj) { const f32x4 o0 = bv[m][bj][0] + scale * acc[ai][bj][m][0], o1 = bv[m][bj][1] + scale * acc[ai][bj][m][1];
;                     *(f32x4*)(out + off + bj * 128) = o0; *(f32x4*)(out + off + bj * 128 + 4) = o1;
;                     if (xb) { *(u32x4*)(xb + off + bj * 128) = __builtin_bit_cast(u32x4, pack8(o0, o1));
;                         sq += (o0[0] * o0[0] + o0[1] * o0[1] + o0[2] * o0[2] + o0[3] * o0[3]) + (o1[0] * o1[0] + o1[1] * o1[1] + o1[2] * o1[2] + o1[3] * o1[3]); } }
;                 if (ssout) { sq += __shfl_xor(sq, 16); sq += __shfl_xor(sq, 32);
;                     if (fq == 0) { if (red) red[(ai * 128 + wr * 64 + m * 16 + fr) * 4 + wc] = sq; else atomicAdd(ssout + (size_t)(row0 + ai * 128 + m * 16) * 8 + u.pn, sq); } } }
.LBB0_685:
	s_waitcnt lgkmcnt(0)
	v_lshlrev_b64 v[76:77], 11, v[128:129]
	v_lshl_add_u64 v[78:79], v[76:77], 0, v[184:185]
	v_pk_fma_f32 v[82:83], v[82:83], 0.5, v[110:111] op_sel_hi:[1,0,1]
	v_pk_fma_f32 v[80:81], v[80:81], 0.5, v[108:109] op_sel_hi:[1,0,1]
	v_pk_fma_f32 v[86:87], v[74:75], 0.5, v[106:107] op_sel_hi:[1,0,1]
	v_pk_fma_f32 v[84:85], v[72:73], 0.5, v[104:105] op_sel_hi:[1,0,1]
	v_lshl_add_u64 v[88:89], v[78:79], 2, s[68:69]
	s_mov_b64 s[28:29], -1
	s_and_b64 vcc, exec, s[6:7]
	v_pk_fma_f32 v[76:77], v[68:69], 0.5, v[100:101] op_sel_hi:[1,0,1]
	v_pk_fma_f32 v[72:73], v[64:65], 0.5, v[96:97] op_sel_hi:[1,0,1]
	global_store_dwordx4 v[88:89], v[80:83], off
	global_store_dwordx4 v[88:89], v[84:87], off offset:16
	s_cbranch_vccnz .LBB0_692
	v_mul_f32_e32 v64, v81, v81
	v_mul_f32_e32 v65, v85, v85
	v_fmac_f32_e32 v64, v80, v80
	v_fmac_f32_e32 v65, v84, v84
	v_fmac_f32_e32 v64, v82, v82
	v_fmac_f32_e32 v65, v86, v86
	v_readlane_b32 s28, v250, 9
	v_fmac_f32_e32 v64, v83, v83
	v_fmac_f32_e32 v65, v87, v87
	v_cvt_pk_bf16_f32 v90, v80, v81
	v_readlane_b32 s29, v250, 10
	v_add_f32_e32 v64, v64, v65
	v_mul_f32_e32 v65, v77, v77
	v_mul_f32_e32 v80, v73, v73
	v_lshl_add_u64 v[68:69], v[78:79], 1, s[28:29]
	v_pk_fma_f32 v[78:79], v[70:71], 0.5, v[102:103] op_sel_hi:[1,0,1]
	v_pk_fma_f32 v[74:75], v[66:67], 0.5, v[98:99] op_sel_hi:[1,0,1]
	v_fmac_f32_e32 v65, v76, v76
	v_fmac_f32_e32 v80, v72, v72
	v_fmac_f32_e32 v65, v78, v78
	v_fmac_f32_e32 v80, v74, v74
	v_fmac_f32_e32 v65, v79, v79
	v_fmac_f32_e32 v80, v75, v75
	v_add_f32_e32 v65, v65, v80
	v_cmp_lt_i32_e32 vcc, v208, v206
	v_add_f32_e32 v64, v64, v65
	v_cvt_pk_bf16_f32 v91, v82, v83
	v_cndmask_b32_e32 v65, v204, v208, vcc
	v_lshlrev_b32_e32 v65, 2, v65
	ds_bpermute_b32 v65, v65, v64
	v_cmp_lt_i32_e32 vcc, v207, v206
	v_cvt_pk_bf16_f32 v92, v84, v85
	v_cvt_pk_bf16_f32 v93, v86, v87
	v_cvt_pk_bf16_f32 v80, v76, v77
	s_waitcnt lgkmcnt(0)
	v_add_f32_e32 v64, v64, v65
	v_cndmask_b32_e32 v65, v204, v207, vcc
	v_lshlrev_b32_e32 v65, 2, v65
	ds_bpermute_b32 v65, v65, v64
	v_cvt_pk_bf16_f32 v81, v78, v79
	v_cvt_pk_bf16_f32 v82, v72, v73
	v_cvt_pk_bf16_f32 v83, v74, v75
	global_store_dwordx4 v[68:69], v[90:93], off
	global_store_dwordx4 v[88:89], v[76:79], off offset:512
	global_store_dwordx4 v[88:89], v[72:75], off offset:528
	global_store_dwordx4 v[68:69], v[80:83], off offset:256
	s_and_saveexec_b64 s[28:29], s[10:11]
	s_cbranch_execz .LBB0_691
	s_waitcnt lgkmcnt(0)
	v_add_f32_e32 v64, v64, v65
	s_andn2_b64 vcc, exec, s[20:21]
	s_mov_b64 s[30:31], -1
	s_cbranch_vccnz .LBB0_689
	s_mov_b64 s[30:31], 0
	ds_write_b32 v218, v64 offset:768

; DEV bf16x8 pack8(f32x4 a, f32x4 b) { u32x4 w; w.x = cvt_pk_bf16(a[0], a[1]); w.y = cvt_pk_bf16(a[2], a[3]); w.z = cvt_pk_bf16(b[0], b[1]); w.w = cvt_pk_bf16(b[2], b[3]); return __builtin_bit_cast(bf16x8, w); }
;     DEV void operator()(AccRef acc, const pg8::Unit& u, int wr, int wc, int fr, int fq) const {
;     ...
;         for (int am = 0; am < 4; ++am) { const int ai = am >> 1, m0 = (am & 1) * 2;
;             f32x4 bv[4][2][2];
; #pragma unroll
;             for (int m = m0; m < m0 + 2; ++m)
; #pragma unroll
;                 for (int bj = 0; bj < 2; ++bj)
; #pragma unroll
;                     for (int n = 0; n < 2; ++n) bv[m][bj][n] = *(const f32x4*)(base + (size_t)(row0 + ai * 128 + m * 16) * 2048 + col0 + bj * 128 + n * 4);
; #pragma unroll
;             for (int m = m0; m < m0 + 2; ++m) { const size_t off = (size_t)(row0 + ai * 128 + m * 16) * 2048 + col0; float sq = 0.f;
; #pragma unroll
;                 for (int bj = 0; bj < 2; ++bj) { const f32x4 o0 = bv[m][bj][0] + scale * acc[ai][bj][m][0], o1 = bv[m][bj][1] + scale * acc[ai][bj][m][1];
;                     *(f32x4*)(out + off + bj * 128) = o0; *(f32x4*)(out + off + bj * 128 + 4) = o1;
;                     if (xb) { *(u32x4*)(xb + off + bj * 128) = __builtin_bit_cast(u32x4, pack8(o0, o1));
;                         sq += (o0[0] * o0[0] + o0[1] * o0[1] + o0[2] * o0[2] + o0[3] * o0[3]) + (o1[0] * o1[0] + o1[1] * o1[1] + o1[2] * o1[2] + o1[3] * o1[3]); } }
;                 if (ssout) { sq += __shfl_xor(sq, 16); sq += __shfl_xor(sq, 32);
;                     if (fq == 0) { if (red) red[(ai * 128 + wr * 64 + m * 16 + fr) * 4 + wc] = sq; else atomicAdd(ssout + (size_t)(row0 + ai * 128 + m * 16) * 8 + u.pn, sq); } } }
.LBB0_694:
	v_add_u32_e32 v100, 0x80, v186
	v_ashrrev_i32_e32 v101, 31, v100
	s_waitcnt lgkmcnt(0)
	v_lshlrev_b64 v[64:65], 13, v[100:101]
	v_add_u32_e32 v96, 0x90, v186
	v_lshl_add_u64 v[64:65], v[188:189], 0, v[64:65]
	v_ashrrev_i32_e32 v97, 31, v96
	s_waitcnt vmcnt(4)
	v_mov_b32_e32 v88, v214
	v_mov_b32_e32 v89, v215
	v_mov_b32_e32 v90, v216
	v_mov_b32_e32 v91, v217
	v_mov_b32_e32 v92, v224
	v_mov_b32_e32 v93, v225
	v_mov_b32_e32 v94, v226
	v_mov_b32_e32 v95, v227
	v_mov_b32_e32 v80, v228
	v_mov_b32_e32 v81, v229
	v_mov_b32_e32 v82, v230
	v_mov_b32_e32 v83, v231
	v_mov_b32_e32 v84, v232
	v_mov_b32_e32 v85, v233
	v_mov_b32_e32 v86, v234
	v_mov_b32_e32 v87, v235
	v_lshlrev_b64 v[64:65], 13, v[96:97]
	v_lshl_add_u64 v[68:69], v[188:189], 0, v[64:65]
	v_mov_b32_e32 v72, v236
	v_mov_b32_e32 v73, v237
	v_mov_b32_e32 v74, v238
	v_mov_b32_e32 v75, v239
	v_mov_b32_e32 v76, v240
	v_mov_b32_e32 v77, v241
	v_mov_b32_e32 v78, v242
	v_mov_b32_e32 v79, v243
	v_mov_b32_e32 v64, v244
	v_mov_b32_e32 v65, v245
	v_mov_b32_e32 v66, v246
	v_mov_b32_e32 v67, v247
	s_nop 0
	v_mov_b32_e32 v68, v248
	v_mov_b32_e32 v69, v249
	v_mov_b32_e32 v70, v172
	v_mov_b32_e32 v71, v173
	v_add_u32_e32 v255, 160, v186
	v_lshlrev_b32_e32 v255, 13, v255
	v_lshl_add_u32 v255, v184, 2, v255
	global_load_dwordx4 v[214:217], v255, s[24:25] offset:16
	global_load_dwordx4 v[224:227], v255, s[24:25]
	global_load_dwordx4 v[228:231], v255, s[24:25] offset:528
	global_load_dwordx4 v[232:235], v255, s[24:25] offset:512
	v_add_u32_e32 v255, 176, v186
	v_lshlrev_b32_e32 v255, 13, v255
	v_lshl_add_u32 v255, v184, 2, v255
	global_load_dwordx4 v[236:239], v255, s[24:25] offset:16
	global_load_dwordx4 v[240:243], v255, s[24:25]
	global_load_dwordx4 v[244:247], v255, s[24:25] offset:528
	global_load_dwordx2 v[248:249], v255, s[24:25] offset:512
	global_load_dwordx2 v[172:173], v255, s[24:25] offset:520
	v_lshlrev_b64 v[98:99], 11, v[100:101]
	v_lshl_add_u64 v[102:103], v[98:99], 0, v[184:185]
	v_lshl_add_u64 v[98:99], v[102:103], 2, s[68:69]
	s_mov_b64 s[28:29], -1
	s_and_b64 vcc, exec, s[6:7]
	v_pk_fma_f32 v[90:91], v[58:59], 0.5, v[90:91] op_sel_hi:[1,0,1]
	v_pk_fma_f32 v[94:95], v[62:63], 0.5, v[94:95] op_sel_hi:[1,0,1]
	v_pk_fma_f32 v[92:93], v[60:61], 0.5, v[92:93] op_sel_hi:[1,0,1]
	v_pk_fma_f32 v[88:89], v[56:57], 0.5, v[88:89] op_sel_hi:[1,0,1]
	v_pk_fma_f32 v[56:57], v[52:53], 0.5, v[84:85] op_sel_hi:[1,0,1]
	v_pk_fma_f32 v[60:61], v[44:45], 0.5, v[80:81] op_sel_hi:[1,0,1]
	global_store_dwordx4 v[98:99], v[92:95], off
	global_store_dwordx4 v[98:99], v[88:91], off offset:16
	s_cbranch_vccnz .LBB0_701
	v_mul_f32_e32 v44, v93, v93
	v_mul_f32_e32 v45, v89, v89
	v_fmac_f32_e32 v44, v92, v92
	v_fmac_f32_e32 v45, v88, v88
	v_fmac_f32_e32 v44, v94, v94
	v_fmac_f32_e32 v45, v90, v90
	v_fmac_f32_e32 v44, v95, v95
	v_fmac_f32_e32 v45, v91, v91
	v_add_f32_e32 v44, v44, v45
	v_mul_f32_e32 v45, v57, v57
	v_mul_f32_e32 v80, v61, v61
	v_pk_fma_f32 v[58:59], v[54:55], 0.5, v[86:87] op_sel_hi:[1,0,1]
	v_pk_fma_f32 v[62:63], v[46:47], 0.5, v[82:83] op_sel_hi:[1,0,1]
	v_fmac_f32_e32 v45, v56, v56
	v_fmac_f32_e32 v80, v60, v60
	v_fmac_f32_e32 v45, v58, v58
	v_fmac_f32_e32 v80, v62, v62
	v_fmac_f32_e32 v45, v59, v59
	v_fmac_f32_e32 v80, v63, v63
	v_add_f32_e32 v45, v45, v80
	v_cmp_lt_i32_e32 vcc, v208, v206
	v_add_f32_e32 v44, v44, v45
	v_readlane_b32 s28, v250, 9
	v_cndmask_b32_e32 v45, v204, v208, vcc
	v_lshlrev_b32_e32 v45, 2, v45
	ds_bpermute_b32 v45, v45, v44
	v_cmp_lt_i32_e32 vcc, v207, v206
	v_readlane_b32 s29, v250, 10
	v_cvt_pk_bf16_f32 v104, v92, v93
	v_cvt_pk_bf16_f32 v105, v94, v95
	s_waitcnt lgkmcnt(0)
	v_add_f32_e32 v44, v44, v45
	v_cndmask_b32_e32 v45, v204, v207, vcc
	v_lshlrev_b32_e32 v45, 2, v45
	ds_bpermute_b32 v45, v45, v44
	v_cvt_pk_bf16_f32 v106, v88, v89
	v_cvt_pk_bf16_f32 v107, v90, v91
	v_lshl_add_u64 v[52:53], v[102:103], 1, s[28:29]
	v_cvt_pk_bf16_f32 v88, v56, v57
	v_cvt_pk_bf16_f32 v89, v58, v59
	v_cvt_pk_bf16_f32 v90, v60, v61
	v_cvt_pk_bf16_f32 v91, v62, v63
	global_store_dwordx4 v[52:53], v[104:107], off
	global_store_dwordx4 v[98:99], v[56:59], off offset:512
	global_store_dwordx4 v[98:99], v[60:63], off offset:528
	global_store_dwordx4 v[52:53], v[88:91], off offset:256
	s_and_saveexec_b64 s[28:29], s[10:11]
	s_cbranch_execz .LBB0_700
	s_waitcnt lgkmcnt(0)
	v_add_f32_e32 v44, v44, v45
	s_andn2_b64 vcc, exec, s[20:21]
	s_mov_b64 s[30:31], -1
	s_cbranch_vccnz .LBB0_698
	s_mov_b64 s[30:31], 0
	ds_write_b32 v218, v44 offset:2048

; DEV bf16x8 pack8(f32x4 a, f32x4 b) { u32x4 w; w.x = cvt_pk_bf16(a[0], a[1]); w.y = cvt_pk_bf16(a[2], a[3]); w.z = cvt_pk_bf16(b[0], b[1]); w.w = cvt_pk_bf16(b[2], b[3]); return __builtin_bit_cast(bf16x8, w); }
;     DEV void operator()(AccRef acc, const pg8::Unit& u, int wr, int wc, int fr, int fq) const {
;     ...
;             for (int m = m0; m < m0 + 2; ++m) { const size_t off = (size_t)(row0 + ai * 128 + m * 16) * 2048 + col0; float sq = 0.f;
; #pragma unroll
;                 for (int bj = 0; bj < 2; ++bj) { const f32x4 o0 = bv[m][bj][0] + scale * acc[ai][bj][m][0], o1 = bv[m][bj][1] + scale * acc[ai][bj][m][1];
;                     *(f32x4*)(out + off + bj * 128) = o0; *(f32x4*)(out + off + bj * 128 + 4) = o1;
;                     if (xb) { *(u32x4*)(xb + off + bj * 128) = __builtin_bit_cast(u32x4, pack8(o0, o1));
;                         sq += (o0[0] * o0[0] + o0[1] * o0[1] + o0[2] * o0[2] + o0[3] * o0[3]) + (o1[0] * o1[0] + o1[1] * o1[1] + o1[2] * o1[2] + o1[3] * o1[3]); } }
;                 if (ssout) { sq += __shfl_xor(sq, 16); sq += __shfl_xor(sq, 32);
;                     if (fq == 0) { if (red) red[(ai * 128 + wr * 64 + m * 16 + fr) * 4 + wc] = sq; else atomicAdd(ssout + (size_t)(row0 + ai * 128 + m * 16) * 8 + u.pn, sq); } } }
.LBB0_703:
	s_waitcnt lgkmcnt(0)
	v_lshlrev_b64 v[44:45], 11, v[96:97]
	v_lshl_add_u64 v[46:47], v[44:45], 0, v[184:185]
	v_pk_fma_f32 v[50:51], v[50:51], 0.5, v[78:79] op_sel_hi:[1,0,1]
	v_pk_fma_f32 v[48:49], v[48:49], 0.5, v[76:77] op_sel_hi:[1,0,1]
	v_pk_fma_f32 v[54:55], v[42:43], 0.5, v[74:75] op_sel_hi:[1,0,1]
	v_pk_fma_f32 v[52:53], v[40:41], 0.5, v[72:73] op_sel_hi:[1,0,1]
	v_lshl_add_u64 v[56:57], v[46:47], 2, s[68:69]
	s_mov_b64 s[28:29], -1
	s_and_b64 vcc, exec, s[6:7]
	v_pk_fma_f32 v[44:45], v[36:37], 0.5, v[68:69] op_sel_hi:[1,0,1]
	v_pk_fma_f32 v[40:41], v[32:33], 0.5, v[64:65] op_sel_hi:[1,0,1]
	global_store_dwordx4 v[56:57], v[48:51], off
	global_store_dwordx4 v[56:57], v[52:55], off offset:16
	s_cbranch_vccnz .LBB0_710
	v_mul_f32_e32 v32, v49, v49
	v_mul_f32_e32 v33, v53, v53
	v_fmac_f32_e32 v32, v48, v48
	v_fmac_f32_e32 v33, v52, v52
	v_fmac_f32_e32 v32, v50, v50
	v_fmac_f32_e32 v33, v54, v54
	v_readlane_b32 s28, v250, 9
	v_fmac_f32_e32 v32, v51, v51
	v_fmac_f32_e32 v33, v55, v55
	v_cvt_pk_bf16_f32 v58, v48, v49
	v_readlane_b32 s29, v250, 10
	v_add_f32_e32 v32, v32, v33
	v_mul_f32_e32 v33, v45, v45
	v_mul_f32_e32 v48, v41, v41
	v_lshl_add_u64 v[36:37], v[46:47], 1, s[28:29]
	v_pk_fma_f32 v[46:47], v[38:39], 0.5, v[70:71] op_sel_hi:[1,0,1]
	v_pk_fma_f32 v[42:43], v[34:35], 0.5, v[66:67] op_sel_hi:[1,0,1]
	v_fmac_f32_e32 v33, v44, v44
	v_fmac_f32_e32 v48, v40, v40
	v_fmac_f32_e32 v33, v46, v46
	v_fmac_f32_e32 v48, v42, v42
	v_fmac_f32_e32 v33, v47, v47
	v_fmac_f32_e32 v48, v43, v43
	v_add_f32_e32 v33, v33, v48
	v_cmp_lt_i32_e32 vcc, v208, v206
	v_add_f32_e32 v32, v32, v33
	v_cvt_pk_bf16_f32 v59, v50, v51
	v_cndmask_b32_e32 v33, v204, v208, vcc
	v_lshlrev_b32_e32 v33, 2, v33
	ds_bpermute_b32 v33, v33, v32
	v_cmp_lt_i32_e32 vcc, v207, v206
	v_cvt_pk_bf16_f32 v60, v52, v53
	v_cvt_pk_bf16_f32 v61, v54, v55
	v_cvt_pk_bf16_f32 v48, v44, v45
	s_waitcnt lgkmcnt(0)
	v_add_f32_e32 v32, v32, v33
	v_cndmask_b32_e32 v33, v204, v207, vcc
	v_lshlrev_b32_e32 v33, 2, v33
	ds_bpermute_b32 v33, v33, v32
	v_cvt_pk_bf16_f32 v49, v46, v47
	v_cvt_pk_bf16_f32 v50, v40, v41
	v_cvt_pk_bf16_f32 v51, v42, v43
	global_store_dwordx4 v[36:37], v[58:61], off
	global_store_dwordx4 v[56:57], v[44:47], off offset:512
	global_store_dwordx4 v[56:57], v[40:43], off offset:528
	global_store_dwordx4 v[36:37], v[48:51], off offset:256
	s_and_saveexec_b64 s[28:29], s[10:11]
	s_cbranch_execz .LBB0_709
	s_waitcnt lgkmcnt(0)
	v_add_f32_e32 v32, v32, v33
	s_andn2_b64 vcc, exec, s[20:21]
	s_mov_b64 s[30:31], -1
	s_cbranch_vccnz .LBB0_707
	s_mov_b64 s[30:31], 0
	ds_write_b32 v218, v32 offset:2304

; DEV bf16x8 pack8(f32x4 a, f32x4 b) { u32x4 w; w.x = cvt_pk_bf16(a[0], a[1]); w.y = cvt_pk_bf16(a[2], a[3]); w.z = cvt_pk_bf16(b[0], b[1]); w.w = cvt_pk_bf16(b[2], b[3]); return __builtin_bit_cast(bf16x8, w); }
;     DEV void operator()(AccRef acc, const pg8::Unit& u, int wr, int wc, int fr, int fq) const {
;     ...
;         for (int am = 0; am < 4; ++am) { const int ai = am >> 1, m0 = (am & 1) * 2;
;             f32x4 bv[4][2][2];
; #pragma unroll
;             for (int m = m0; m < m0 + 2; ++m)
; #pragma unroll
;                 for (int bj = 0; bj < 2; ++bj)
; #pragma unroll
;                     for (int n = 0; n < 2; ++n) bv[m][bj][n] = *(const f32x4*)(base + (size_t)(row0 + ai * 128 + m * 16) * 2048 + col0 + bj * 128 + n * 4);
; #pragma unroll
;             for (int m = m0; m < m0 + 2; ++m) { const size_t off = (size_t)(row0 + ai * 128 + m * 16) * 2048 + col0; float sq = 0.f;
; #pragma unroll
;                 for (int bj = 0; bj < 2; ++bj) { const f32x4 o0 = bv[m][bj][0] + scale * acc[ai][bj][m][0], o1 = bv[m][bj][1] + scale * acc[ai][bj][m][1];
;                     *(f32x4*)(out + off + bj * 128) = o0; *(f32x4*)(out + off + bj * 128 + 4) = o1;
;                     if (xb) { *(u32x4*)(xb + off + bj * 128) = __builtin_bit_cast(u32x4, pack8(o0, o1));
;                         sq += (o0[0] * o0[0] + o0[1] * o0[1] + o0[2] * o0[2] + o0[3] * o0[3]) + (o1[0] * o1[0] + o1[1] * o1[1] + o1[2] * o1[2] + o1[3] * o1[3]); } }
;                 if (ssout) { sq += __shfl_xor(sq, 16); sq += __shfl_xor(sq, 32);
;                     if (fq == 0) { if (red) red[(ai * 128 + wr * 64 + m * 16 + fr) * 4 + wc] = sq; else atomicAdd(ssout + (size_t)(row0 + ai * 128 + m * 16) * 8 + u.pn, sq); } } }
.LBB0_712:
	v_add_u32_e32 v68, 0xa0, v186
	v_ashrrev_i32_e32 v69, 31, v68
	s_waitcnt lgkmcnt(0)
	v_lshlrev_b64 v[32:33], 13, v[68:69]
	v_add_u32_e32 v64, 0xb0, v186
	v_lshl_add_u64 v[32:33], v[188:189], 0, v[32:33]
	v_ashrrev_i32_e32 v65, 31, v64
	s_waitcnt vmcnt(4)
	v_mov_b32_e32 v56, v214
	v_mov_b32_e32 v57, v215
	v_mov_b32_e32 v58, v216
	v_mov_b32_e32 v59, v217
	v_mov_b32_e32 v60, v224
	v_mov_b32_e32 v61, v225
	v_mov_b32_e32 v62, v226
	v_mov_b32_e32 v63, v227
	v_mov_b32_e32 v48, v228
	v_mov_b32_e32 v49, v229
	v_mov_b32_e32 v50, v230
	v_mov_b32_e32 v51, v231
	v_mov_b32_e32 v52, v232
	v_mov_b32_e32 v53, v233
	v_mov_b32_e32 v54, v234
	v_mov_b32_e32 v55, v235
	v_lshlrev_b64 v[32:33], 13, v[64:65]
	v_lshl_add_u64 v[36:37], v[188:189], 0, v[32:33]
	v_mov_b32_e32 v40, v236
	v_mov_b32_e32 v41, v237
	v_mov_b32_e32 v42, v238
	v_mov_b32_e32 v43, v239
	v_mov_b32_e32 v44, v240
	v_mov_b32_e32 v45, v241
	v_mov_b32_e32 v46, v242
	v_mov_b32_e32 v47, v243
	v_mov_b32_e32 v32, v244
	v_mov_b32_e32 v33, v245
	v_mov_b32_e32 v34, v246
	v_mov_b32_e32 v35, v247
	s_nop 0
	v_mov_b32_e32 v36, v248
	v_mov_b32_e32 v37, v249
	v_mov_b32_e32 v38, v172
	v_mov_b32_e32 v39, v173
	v_lshlrev_b64 v[66:67], 11, v[68:69]
	v_lshl_add_u64 v[70:71], v[66:67], 0, v[184:185]
	v_lshl_add_u64 v[66:67], v[70:71], 2, s[68:69]
	s_mov_b64 s[28:29], -1
	s_and_b64 vcc, exec, s[6:7]
	v_pk_fma_f32 v[58:59], v[26:27], 0.5, v[58:59] op_sel_hi:[1,0,1]
	v_pk_fma_f32 v[62:63], v[30:31], 0.5, v[62:63] op_sel_hi:[1,0,1]
	v_pk_fma_f32 v[60:61], v[28:29], 0.5, v[60:61] op_sel_hi:[1,0,1]
	v_pk_fma_f32 v[56:57], v[24:25], 0.5, v[56:57] op_sel_hi:[1,0,1]
	v_pk_fma_f32 v[24:25], v[20:21], 0.5, v[52:53] op_sel_hi:[1,0,1]
	v_pk_fma_f32 v[28:29], v[12:13], 0.5, v[48:49] op_sel_hi:[1,0,1]
	global_store_dwordx4 v[66:67], v[60:63], off
	global_store_dwordx4 v[66:67], v[56:59], off offset:16
	s_cbranch_vccnz .LBB0_719
	v_mul_f32_e32 v12, v61, v61
	v_mul_f32_e32 v13, v57, v57
	v_fmac_f32_e32 v12, v60, v60
	v_fmac_f32_e32 v13, v56, v56
	v_fmac_f32_e32 v12, v62, v62
	v_fmac_f32_e32 v13, v58, v58
	v_fmac_f32_e32 v12, v63, v63
	v_fmac_f32_e32 v13, v59, v59
	v_add_f32_e32 v12, v12, v13
	v_mul_f32_e32 v13, v25, v25
	v_mul_f32_e32 v48, v29, v29
	v_pk_fma_f32 v[26:27], v[22:23], 0.5, v[54:55] op_sel_hi:[1,0,1]
	v_pk_fma_f32 v[30:31], v[14:15], 0.5, v[50:51] op_sel_hi:[1,0,1]
	v_fmac_f32_e32 v13, v24, v24
	v_fmac_f32_e32 v48, v28, v28
	v_fmac_f32_e32 v13, v26, v26
	v_fmac_f32_e32 v48, v30, v30
	v_fmac_f32_e32 v13, v27, v27
	v_fmac_f32_e32 v48, v31, v31
	v_add_f32_e32 v13, v13, v48
	v_cmp_lt_i32_e32 vcc, v208, v206
	v_add_f32_e32 v12, v12, v13
	v_readlane_b32 s28, v250, 9
	v_cndmask_b32_e32 v13, v204, v208, vcc
	v_lshlrev_b32_e32 v13, 2, v13
	ds_bpermute_b32 v13, v13, v12
	v_cmp_lt_i32_e32 vcc, v207, v206
	v_readlane_b32 s29, v250, 10
	v_cvt_pk_bf16_f32 v72, v60, v61
	v_cvt_pk_bf16_f32 v73, v62, v63
	s_waitcnt lgkmcnt(0)
	v_add_f32_e32 v12, v12, v13
	v_cndmask_b32_e32 v13, v204, v207, vcc
	v_lshlrev_b32_e32 v13, 2, v13
	ds_bpermute_b32 v13, v13, v12
	v_cvt_pk_bf16_f32 v74, v56, v57
	v_cvt_pk_bf16_f32 v75, v58, v59
	v_lshl_add_u64 v[20:21], v[70:71], 1, s[28:29]
	v_cvt_pk_bf16_f32 v56, v24, v25
	v_cvt_pk_bf16_f32 v57, v26, v27
	v_cvt_pk_bf16_f32 v58, v28, v29
	v_cvt_pk_bf16_f32 v59, v30, v31
	global_store_dwordx4 v[20:21], v[72:75], off
	global_store_dwordx4 v[66:67], v[24:27], off offset:512
	global_store_dwordx4 v[66:67], v[28:31], off offset:528
	global_store_dwordx4 v[20:21], v[56:59], off offset:256
	s_and_saveexec_b64 s[28:29], s[10:11]
	s_cbranch_execz .LBB0_718
	s_waitcnt lgkmcnt(0)
	v_add_f32_e32 v12, v12, v13
	s_andn2_b64 vcc, exec, s[20:21]
	s_mov_b64 s[30:31], -1
	s_cbranch_vccnz .LBB0_716
	s_mov_b64 s[30:31], 0
	ds_write_b32 v218, v12 offset:2560

; DEV bf16x8 pack8(f32x4 a, f32x4 b) { u32x4 w; w.x = cvt_pk_bf16(a[0], a[1]); w.y = cvt_pk_bf16(a[2], a[3]); w.z = cvt_pk_bf16(b[0], b[1]); w.w = cvt_pk_bf16(b[2], b[3]); return __builtin_bit_cast(bf16x8, w); }
;     DEV void operator()(AccRef acc, const pg8::Unit& u, int wr, int wc, int fr, int fq) const {
;     ...
;             for (int m = m0; m < m0 + 2; ++m) { const size_t off = (size_t)(row0 + ai * 128 + m * 16) * 2048 + col0; float sq = 0.f;
; #pragma unroll
;                 for (int bj = 0; bj < 2; ++bj) { const f32x4 o0 = bv[m][bj][0] + scale * acc[ai][bj][m][0], o1 = bv[m][bj][1] + scale * acc[ai][bj][m][1];
;                     *(f32x4*)(out + off + bj * 128) = o0; *(f32x4*)(out + off + bj * 128 + 4) = o1;
;                     if (xb) { *(u32x4*)(xb + off + bj * 128) = __builtin_bit_cast(u32x4, pack8(o0, o1));
;                         sq += (o0[0] * o0[0] + o0[1] * o0[1] + o0[2] * o0[2] + o0[3] * o0[3]) + (o1[0] * o1[0] + o1[1] * o1[1] + o1[2] * o1[2] + o1[3] * o1[3]); } }
;                 if (ssout) { sq += __shfl_xor(sq, 16); sq += __shfl_xor(sq, 32);
;                     if (fq == 0) { if (red) red[(ai * 128 + wr * 64 + m * 16 + fr) * 4 + wc] = sq; else atomicAdd(ssout + (size_t)(row0 + ai * 128 + m * 16) * 8 + u.pn, sq); } } }
.LBB0_721:
	s_waitcnt lgkmcnt(0)
	v_lshlrev_b64 v[12:13], 11, v[64:65]
	v_lshl_add_u64 v[14:15], v[12:13], 0, v[184:185]
	v_pk_fma_f32 v[18:19], v[18:19], 0.5, v[46:47] op_sel_hi:[1,0,1]
	v_pk_fma_f32 v[16:17], v[16:17], 0.5, v[44:45] op_sel_hi:[1,0,1]
	v_pk_fma_f32 v[22:23], v[10:11], 0.5, v[42:43] op_sel_hi:[1,0,1]
	v_pk_fma_f32 v[20:21], v[8:9], 0.5, v[40:41] op_sel_hi:[1,0,1]
	v_lshl_add_u64 v[24:25], v[14:15], 2, s[68:69]
	s_mov_b64 s[28:29], -1
	s_and_b64 vcc, exec, s[6:7]
	v_pk_fma_f32 v[12:13], v[4:5], 0.5, v[36:37] op_sel_hi:[1,0,1]
	v_pk_fma_f32 v[8:9], v[0:1], 0.5, v[32:33] op_sel_hi:[1,0,1]
	global_store_dwordx4 v[24:25], v[16:19], off
	global_store_dwordx4 v[24:25], v[20:23], off offset:16
	s_cbranch_vccnz .LBB0_729
	v_mul_f32_e32 v0, v17, v17
	v_mul_f32_e32 v1, v21, v21
	v_fmac_f32_e32 v0, v16, v16
	v_fmac_f32_e32 v1, v20, v20
	v_fmac_f32_e32 v0, v18, v18
	v_fmac_f32_e32 v1, v22, v22
	v_readlane_b32 s6, v250, 9
	v_fmac_f32_e32 v0, v19, v19
	v_fmac_f32_e32 v1, v23, v23
	v_cvt_pk_bf16_f32 v26, v16, v17
	v_readlane_b32 s7, v250, 10
	v_add_f32_e32 v0, v0, v1
	v_mul_f32_e32 v1, v13, v13
	v_mul_f32_e32 v16, v9, v9
	v_lshl_add_u64 v[4:5], v[14:15], 1, s[6:7]
	v_pk_fma_f32 v[14:15], v[6:7], 0.5, v[38:39] op_sel_hi:[1,0,1]
	v_pk_fma_f32 v[10:11], v[2:3], 0.5, v[34:35] op_sel_hi:[1,0,1]
	v_fmac_f32_e32 v1, v12, v12
	v_fmac_f32_e32 v16, v8, v8
	v_fmac_f32_e32 v1, v14, v14
	v_fmac_f32_e32 v16, v10, v10
	v_fmac_f32_e32 v1, v15, v15
	v_fmac_f32_e32 v16, v11, v11
	v_add_f32_e32 v1, v1, v16
	v_cmp_lt_i32_e32 vcc, v208, v206
	v_add_f32_e32 v0, v0, v1
	v_cvt_pk_bf16_f32 v27, v18, v19
	v_cndmask_b32_e32 v1, v204, v208, vcc
	v_lshlrev_b32_e32 v1, 2, v1
	ds_bpermute_b32 v1, v1, v0
	v_cmp_lt_i32_e32 vcc, v207, v206
	v_cvt_pk_bf16_f32 v28, v20, v21
	v_cvt_pk_bf16_f32 v29, v22, v23
	v_cvt_pk_bf16_f32 v16, v12, v13
	s_waitcnt lgkmcnt(0)
	v_add_f32_e32 v0, v0, v1
	v_cndmask_b32_e32 v1, v204, v207, vcc
	v_lshlrev_b32_e32 v1, 2, v1
	ds_bpermute_b32 v1, v1, v0
	v_cvt_pk_bf16_f32 v17, v14, v15
	v_cvt_pk_bf16_f32 v18, v8, v9
	v_cvt_pk_bf16_f32 v19, v10, v11
	global_store_dwordx4 v[4:5], v[26:29], off
	global_store_dwordx4 v[24:25], v[12:15], off offset:512
	global_store_dwordx4 v[24:25], v[8:11], off offset:528
	global_store_dwordx4 v[4:5], v[16:19], off offset:256
	s_and_saveexec_b64 s[6:7], s[10:11]
	s_cbranch_execz .LBB0_727
	s_waitcnt lgkmcnt(0)
	v_add_f32_e32 v0, v0, v1
	s_andn2_b64 vcc, exec, s[20:21]
	s_cbranch_vccnz .LBB0_725
	s_mov_b64 s[28:29], 0
	ds_write_b32 v218, v0 offset:2816
